# GEMM loop heads 64B-aligned, mid-segment setprio 0/1 pairs removed, on top of attention max-fold + PV repipeline
# speedup vs baseline: 1.0011x; 1.0011x over previous
; #define PG8_STAGE(bufoff, gbase, RR, ld) do { _Pragma("unroll") for (int _i = 0; _i < 2; ++_i) \
;         __builtin_amdgcn_global_load_lds((const unsigned*)((const char*)(gbase) + (RR)[_i] * (ld) + C2[_i]), (LAS unsigned*)(lds + (bufoff) + ldsw + _i * 8192), 16, 0, 0); } while (0)
; #define PG8_LDA(dst, b, h) do { _Pragma("unroll") for (int m = 0; m < 4; ++m) _Pragma("unroll") for (int k = 0; k < 2; ++k) dst[m][k] = *(const LAS bf16x8*)(lds + PG8_SA(b, h) + aoff + m * 2048 + k * 1024); } while (0)
; #define PG8_LDB(dst, b, h) do { _Pragma("unroll") for (int n = 0; n < 2; ++n) _Pragma("unroll") for (int k = 0; k < 2; ++k) dst[n][k] = *(const LAS bf16x8*)(lds + PG8_SB(b, h) + boff + n * 2048 + k * 1024); } while (0)
; #define PG8_WAIT_V(n) asm volatile("s_waitcnt vmcnt(" #n ")" ::: "memory")
; #define PG8_WAIT_L(n) asm volatile("s_waitcnt lgkmcnt(" #n ")" ::: "memory")
; #define PG8_BAR __builtin_amdgcn_s_barrier()
; template <class Sched, class Epi>
; __device__ __forceinline__ void gemm_run(LAS unsigned char* lds, const Sched& S, const Epi& E) {
;     ...
;         const bool has_next = S.next(ui + 1, nxt);
;         const char* nA = has_next ? nxt.A : cA; const char* nB = has_next ? nxt.B : cB; const unsigned nlda = has_next ? nxt.lda : lda, nldb = has_next ? nxt.ldb : ldb;
;         const int nt = cur.nt;
;         for (int t = 0; t < nt; t += 2) {
;             const bool last = (t == nt - 2);
;             const char* a1 = cA + (size_t)(t + 1) * kstep;
;             const char* a2 = last ? nA : cA + (size_t)(t + 2) * kstep; const char* b2 = last ? nB : cB + (size_t)(t + 2) * kstep;
;             const unsigned la2 = last ? nlda : lda, lb2 = last ? nldb : ldb;
;             const char* a3 = a2 + kstep; const char* b3 = b2 + kstep;
;             PG8_LDB(B0, 0, 0); PG8_LDB(B1, 0, 1); PG8_SCHED; PG8_LDA(At, 0, 0); PG8_STAGE(PG8_SA(1, 1), a1 + (size_t)HALF * lda, RA, lda);
;             PG8_WAIT_V(8); PG8_WAIT_L(0); PG8_BAR; PG8_MMA(0, 0, At, B0); PG8_MMA(0, 1, At, B1); PG8_BAR; PG8_SCHED;
;     ...
;         for (int a = 0; a < 2; ++a)
; #pragma unroll
;             for (int b = 0; b < 2; ++b)
; #pragma unroll
;                 for (int m = 0; m < 4; ++m)
; #pragma unroll
;                     for (int n = 0; n < 2; ++n) acc[a][b][m][n] = (f32x4){0.f, 0.f, 0.f, 0.f};
;         cur = nxt; cA = nA; cB = nB; lda = nlda; ldb = nldb; ++ui;
.LBB0_245:
	s_add_u32 s12, s54, 0x100
	v_mov_b32_e32 v2, 0
	s_addc_u32 s33, s55, 0
	s_mov_b32 s38, -2
	s_mov_b64 s[54:55], 0
	s_waitcnt lgkmcnt(0)
	v_mov_b32_e32 v3, v2
	v_mov_b32_e32 v4, v2
	v_mov_b32_e32 v5, v2
	v_mov_b32_e32 v6, v2
	v_mov_b32_e32 v7, v2
	v_mov_b32_e32 v8, v2
	v_mov_b32_e32 v9, v2
	v_mov_b32_e32 v18, v2
	v_mov_b32_e32 v19, v2
	v_mov_b32_e32 v20, v2
	v_mov_b32_e32 v21, v2
	v_mov_b32_e32 v22, v2
	v_mov_b32_e32 v23, v2
	v_mov_b32_e32 v24, v2
	v_mov_b32_e32 v25, v2
	v_mov_b32_e32 v34, v2
	v_mov_b32_e32 v35, v2
	v_mov_b32_e32 v36, v2
	v_mov_b32_e32 v37, v2
	v_mov_b32_e32 v38, v2
	v_mov_b32_e32 v39, v2
	v_mov_b32_e32 v40, v2
	v_mov_b32_e32 v41, v2
	v_mov_b32_e32 v50, v2
	v_mov_b32_e32 v51, v2
	v_mov_b32_e32 v52, v2
	v_mov_b32_e32 v53, v2
	v_mov_b32_e32 v54, v2
	v_mov_b32_e32 v55, v2
	v_mov_b32_e32 v56, v2
	v_mov_b32_e32 v57, v2
	v_mov_b32_e32 v10, v2
	v_mov_b32_e32 v11, v2
	v_mov_b32_e32 v12, v2
	v_mov_b32_e32 v13, v2
	v_mov_b32_e32 v14, v2
	v_mov_b32_e32 v15, v2
	v_mov_b32_e32 v16, v2
	v_mov_b32_e32 v17, v2
	v_mov_b32_e32 v26, v2
	v_mov_b32_e32 v27, v2
	v_mov_b32_e32 v28, v2
	v_mov_b32_e32 v29, v2
	v_mov_b32_e32 v30, v2
	v_mov_b32_e32 v31, v2
	v_mov_b32_e32 v32, v2
	v_mov_b32_e32 v33, v2
	v_mov_b32_e32 v42, v2
	v_mov_b32_e32 v43, v2
	v_mov_b32_e32 v44, v2
	v_mov_b32_e32 v45, v2
	v_mov_b32_e32 v46, v2
	v_mov_b32_e32 v47, v2
	v_mov_b32_e32 v48, v2
	v_mov_b32_e32 v49, v2
	v_mov_b32_e32 v58, v2
	v_mov_b32_e32 v59, v2
	v_mov_b32_e32 v60, v2
	v_mov_b32_e32 v61, v2
	v_mov_b32_e32 v62, v2
	v_mov_b32_e32 v63, v2
	v_mov_b32_e32 v64, v2
	v_mov_b32_e32 v65, v2
	v_mov_b32_e32 v66, v2
	v_mov_b32_e32 v67, v2
	v_mov_b32_e32 v68, v2
	v_mov_b32_e32 v69, v2
	v_mov_b32_e32 v70, v2
	v_mov_b32_e32 v71, v2
	v_mov_b32_e32 v72, v2
	v_mov_b32_e32 v73, v2
	v_mov_b32_e32 v82, v2
	v_mov_b32_e32 v83, v2
	v_mov_b32_e32 v84, v2
	v_mov_b32_e32 v85, v2
	v_mov_b32_e32 v86, v2
	v_mov_b32_e32 v87, v2
	v_mov_b32_e32 v88, v2
	v_mov_b32_e32 v89, v2
	v_mov_b32_e32 v98, v2
	v_mov_b32_e32 v99, v2
	v_mov_b32_e32 v100, v2
	v_mov_b32_e32 v101, v2
	v_mov_b32_e32 v102, v2
	v_mov_b32_e32 v103, v2
	v_mov_b32_e32 v104, v2
	v_mov_b32_e32 v105, v2
	v_mov_b32_e32 v114, v2
	v_mov_b32_e32 v115, v2
	v_mov_b32_e32 v116, v2
	v_mov_b32_e32 v117, v2
	v_mov_b32_e32 v118, v2
	v_mov_b32_e32 v119, v2
	v_mov_b32_e32 v120, v2
	v_mov_b32_e32 v121, v2
	v_mov_b32_e32 v74, v2
	v_mov_b32_e32 v75, v2
	v_mov_b32_e32 v76, v2
	v_mov_b32_e32 v77, v2
	v_mov_b32_e32 v78, v2
	v_mov_b32_e32 v79, v2
	v_mov_b32_e32 v80, v2
	v_mov_b32_e32 v81, v2
	v_mov_b32_e32 v90, v2
	v_mov_b32_e32 v91, v2
	v_mov_b32_e32 v92, v2
	v_mov_b32_e32 v93, v2
	v_mov_b32_e32 v94, v2
	v_mov_b32_e32 v95, v2
	v_mov_b32_e32 v96, v2
	v_mov_b32_e32 v97, v2
	v_mov_b32_e32 v106, v2
	v_mov_b32_e32 v107, v2
	v_mov_b32_e32 v108, v2
	v_mov_b32_e32 v109, v2
	v_mov_b32_e32 v110, v2
	v_mov_b32_e32 v111, v2
	v_mov_b32_e32 v112, v2
	v_mov_b32_e32 v113, v2
	v_mov_b32_e32 v122, v2
	v_mov_b32_e32 v123, v2
	v_mov_b32_e32 v124, v2
	v_mov_b32_e32 v125, v2
	v_mov_b32_e32 v126, v2
	v_mov_b32_e32 v127, v2
	v_mov_b32_e32 v128, v2
	v_mov_b32_e32 v129, v2
	v_lshl_add_u64 v[150:151], s[6:7], 0, v[146:147]
	s_waitcnt vmcnt(0)
	v_lshl_add_u64 v[152:153], s[6:7], 0, v[148:149]
	.p2align 6
.LBB0_246:
	ds_read_b128 v[154:157], v182
	ds_read_b128 v[158:161], v182 offset:1024
	ds_read_b128 v[162:165], v182 offset:2048
	ds_read_b128 v[166:169], v182 offset:3072
	ds_read_b128 v[170:173], v183
	ds_read_b128 v[186:189], v183 offset:1024
	ds_read_b128 v[190:193], v183 offset:2048
	ds_read_b128 v[194:197], v183 offset:3072
	s_add_u32 s39, s6, s54
	s_addc_u32 s40, s7, s55
	s_add_u32 s39, s39, 0x100
	s_addc_u32 s40, s40, 0
	s_add_u32 s41, s12, s54
	s_addc_u32 s42, s33, s55
	s_cmpk_eq_i32 s54, 0xf00
	s_cselect_b32 s59, s29, s40
	s_cselect_b32 s58, s28, s39
	s_cselect_b32 s57, s37, s42
	s_cselect_b32 s56, s36, s41
	v_lshl_add_u64 v[174:175], v[150:151], 0, s[54:55]
	s_add_i32 m0, s21, 0xc000
	ds_read_b128 v[198:201], v184
	ds_read_b128 v[202:205], v184 offset:1024
	ds_read_b128 v[206:209], v184 offset:2048
	ds_read_b128 v[210:213], v184 offset:3072
	ds_read_b128 v[214:217], v184 offset:4096
	ds_read_b128 v[218:221], v184 offset:5120
	ds_read_b128 v[222:225], v184 offset:6144
	ds_read_b128 v[226:229], v184 offset:7168
	global_load_lds_dwordx4 v[174:175], off
	v_lshl_add_u64 v[174:175], v[152:153], 0, s[54:55]
	s_add_i32 m0, s21, 0xe000
	s_nop 0
	global_load_lds_dwordx4 v[174:175], off
	s_waitcnt vmcnt(8)
	s_waitcnt lgkmcnt(0)
	s_barrier
; #define PG8_STAGE(bufoff, gbase, RR, ld) do { _Pragma("unroll") for (int _i = 0; _i < 2; ++_i) \
;         __builtin_amdgcn_global_load_lds((const unsigned*)((const char*)(gbase) + (RR)[_i] * (ld) + C2[_i]), (LAS unsigned*)(lds + (bufoff) + ldsw + _i * 8192), 16, 0, 0); } while (0)
; #define PG8_LDA(dst, b, h) do { _Pragma("unroll") for (int m = 0; m < 4; ++m) _Pragma("unroll") for (int k = 0; k < 2; ++k) dst[m][k] = *(const LAS bf16x8*)(lds + PG8_SA(b, h) + aoff + m * 2048 + k * 1024); } while (0)
; #define PG8_MMA(ai, bj, At, Bt) do { __builtin_amdgcn_s_setprio(1); _Pragma("unroll") for (int m = 0; m < 4; ++m) _Pragma("unroll") for (int n = 0; n < 2; ++n) _Pragma("unroll") for (int k = 0; k < 2; ++k) \
;         acc[ai][bj][m][n] = __builtin_amdgcn_mfma_f32_16x16x32_bf16(Bt[n][k], At[m][k], acc[ai][bj][m][n], 0, 0, 0); __builtin_amdgcn_s_setprio(0); } while (0)
; #define PG8_WAIT_V(n) asm volatile("s_waitcnt vmcnt(" #n ")" ::: "memory")
; #define PG8_WAIT_L(n) asm volatile("s_waitcnt lgkmcnt(" #n ")" ::: "memory")
; #define PG8_BAR __builtin_amdgcn_s_barrier()
; #define PG8_SCHED __builtin_amdgcn_sched_barrier(0)
; template <class Sched, class Epi>
; __device__ __forceinline__ void gemm_run(LAS unsigned char* lds, const Sched& S, const Epi& E) {
;     ...
;             PG8_WAIT_V(8); PG8_WAIT_L(0); PG8_BAR; PG8_MMA(0, 0, At, B0); PG8_MMA(0, 1, At, B1); PG8_BAR; PG8_SCHED;
;             PG8_LDA(At, 0, 1); PG8_STAGE(PG8_SB(0, 0), b2, RB, lb2); PG8_STAGE(PG8_SB(0, 1), b2 + (size_t)HALF * lb2, RB, lb2); PG8_STAGE(PG8_SA(0, 0), a2, RA, la2);
;             PG8_WAIT_V(8); PG8_WAIT_L(0); PG8_BAR; PG8_MMA(1, 0, At, B0); PG8_MMA(1, 1, At, B1); PG8_BAR; PG8_SCHED;
	s_setprio 1
	s_waitcnt lgkmcnt(0)
	v_mfma_f32_16x16x32_bf16 v[126:129], v[154:157], v[198:201], v[126:129]
	v_mfma_f32_16x16x32_bf16 v[122:125], v[162:165], v[198:201], v[122:125]
	v_mfma_f32_16x16x32_bf16 v[110:113], v[154:157], v[206:209], v[110:113]
	v_mfma_f32_16x16x32_bf16 v[106:109], v[162:165], v[206:209], v[106:109]
	v_mfma_f32_16x16x32_bf16 v[94:97], v[154:157], v[214:217], v[94:97]
	v_mfma_f32_16x16x32_bf16 v[90:93], v[162:165], v[214:217], v[90:93]
	v_mfma_f32_16x16x32_bf16 v[78:81], v[154:157], v[222:225], v[78:81]
	v_mfma_f32_16x16x32_bf16 v[74:77], v[162:165], v[222:225], v[74:77]
	v_mfma_f32_16x16x32_bf16 v[126:129], v[158:161], v[202:205], v[126:129]
	v_mfma_f32_16x16x32_bf16 v[122:125], v[166:169], v[202:205], v[122:125]
	v_mfma_f32_16x16x32_bf16 v[110:113], v[158:161], v[210:213], v[110:113]
	v_mfma_f32_16x16x32_bf16 v[106:109], v[166:169], v[210:213], v[106:109]
	v_mfma_f32_16x16x32_bf16 v[94:97], v[158:161], v[218:221], v[94:97]
	v_mfma_f32_16x16x32_bf16 v[90:93], v[166:169], v[218:221], v[90:93]
	v_mfma_f32_16x16x32_bf16 v[78:81], v[158:161], v[226:229], v[78:81]
	v_mfma_f32_16x16x32_bf16 v[74:77], v[166:169], v[226:229], v[74:77]
	v_mfma_f32_16x16x32_bf16 v[118:121], v[170:173], v[198:201], v[118:121]
	v_mfma_f32_16x16x32_bf16 v[114:117], v[190:193], v[198:201], v[114:117]
	v_mfma_f32_16x16x32_bf16 v[102:105], v[170:173], v[206:209], v[102:105]
	v_mfma_f32_16x16x32_bf16 v[98:101], v[190:193], v[206:209], v[98:101]
	v_mfma_f32_16x16x32_bf16 v[86:89], v[170:173], v[214:217], v[86:89]
	v_mfma_f32_16x16x32_bf16 v[82:85], v[190:193], v[214:217], v[82:85]
	v_mfma_f32_16x16x32_bf16 v[70:73], v[170:173], v[222:225], v[70:73]
	v_mfma_f32_16x16x32_bf16 v[66:69], v[190:193], v[222:225], v[66:69]
	v_mfma_f32_16x16x32_bf16 v[118:121], v[186:189], v[202:205], v[118:121]
	v_mfma_f32_16x16x32_bf16 v[114:117], v[194:197], v[202:205], v[114:117]
	v_mfma_f32_16x16x32_bf16 v[102:105], v[186:189], v[210:213], v[102:105]
	v_mfma_f32_16x16x32_bf16 v[98:101], v[194:197], v[210:213], v[98:101]
	v_mfma_f32_16x16x32_bf16 v[86:89], v[186:189], v[218:221], v[86:89]
	v_mfma_f32_16x16x32_bf16 v[82:85], v[194:197], v[218:221], v[82:85]
	v_mfma_f32_16x16x32_bf16 v[70:73], v[186:189], v[226:229], v[70:73]
	v_mfma_f32_16x16x32_bf16 v[66:69], v[194:197], v[226:229], v[66:69]
	s_setprio 0
	s_barrier
	v_lshl_add_u64 v[174:175], s[56:57], 0, v[132:133]
	s_add_i32 s39, s71, s3
	v_lshl_add_u64 v[174:175], v[174:175], 0, v[130:131]
	s_mov_b32 m0, s39
	ds_read_b128 v[198:201], v184 offset:16384
	ds_read_b128 v[202:205], v184 offset:17408
	ds_read_b128 v[206:209], v184 offset:18432
	ds_read_b128 v[210:213], v184 offset:19456
	ds_read_b128 v[214:217], v184 offset:20480
	ds_read_b128 v[218:221], v184 offset:21504
	ds_read_b128 v[222:225], v184 offset:22528
	ds_read_b128 v[226:229], v184 offset:23552
	global_load_lds_dwordx4 v[174:175], off
	s_add_i32 m0, s39, 0x2000
	s_add_u32 s40, s56, 0x80000
	v_lshl_add_u64 v[230:231], s[56:57], 0, v[136:137]
	s_addc_u32 s41, s57, 0
	v_lshl_add_u64 v[230:231], v[230:231], 0, v[130:131]
	v_lshl_add_u64 v[232:233], s[40:41], 0, v[132:133]
	s_add_i32 s39, s72, s3
	global_load_lds_dwordx4 v[230:231], off
	v_lshl_add_u64 v[232:233], v[232:233], 0, v[130:131]
	s_mov_b32 m0, s39
	v_lshl_add_u64 v[234:235], s[58:59], 0, v[140:141]
	global_load_lds_dwordx4 v[232:233], off
	v_lshl_add_u64 v[232:233], s[40:41], 0, v[136:137]
	v_lshl_add_u64 v[232:233], v[232:233], 0, v[130:131]
	s_add_i32 m0, s39, 0x2000
	v_lshl_add_u64 v[234:235], v[234:235], 0, v[130:131]
	global_load_lds_dwordx4 v[232:233], off
	v_lshl_add_u64 v[232:233], s[58:59], 0, v[138:139]
	v_lshl_add_u64 v[232:233], v[232:233], 0, v[130:131]
	s_mov_b32 m0, s21
	s_nop 0
	global_load_lds_dwordx4 v[232:233], off
	s_mov_b32 m0, s35
	s_nop 0
	global_load_lds_dwordx4 v[234:235], off
	s_waitcnt vmcnt(8)
	s_waitcnt lgkmcnt(0)
	s_barrier
	s_setprio 1
	s_waitcnt lgkmcnt(0)
	v_mfma_f32_16x16x32_bf16 v[62:65], v[154:157], v[198:201], v[62:65]
	v_mfma_f32_16x16x32_bf16 v[58:61], v[162:165], v[198:201], v[58:61]
	v_mfma_f32_16x16x32_bf16 v[46:49], v[154:157], v[206:209], v[46:49]
	v_mfma_f32_16x16x32_bf16 v[42:45], v[162:165], v[206:209], v[42:45]
	v_mfma_f32_16x16x32_bf16 v[30:33], v[154:157], v[214:217], v[30:33]
	v_mfma_f32_16x16x32_bf16 v[26:29], v[162:165], v[214:217], v[26:29]
	v_mfma_f32_16x16x32_bf16 v[14:17], v[154:157], v[222:225], v[14:17]
	v_mfma_f32_16x16x32_bf16 v[10:13], v[162:165], v[222:225], v[10:13]
	v_mfma_f32_16x16x32_bf16 v[62:65], v[158:161], v[202:205], v[62:65]
	v_mfma_f32_16x16x32_bf16 v[58:61], v[166:169], v[202:205], v[58:61]
	v_mfma_f32_16x16x32_bf16 v[46:49], v[158:161], v[210:213], v[46:49]
	v_mfma_f32_16x16x32_bf16 v[42:45], v[166:169], v[210:213], v[42:45]
	v_mfma_f32_16x16x32_bf16 v[30:33], v[158:161], v[218:221], v[30:33]
	v_mfma_f32_16x16x32_bf16 v[26:29], v[166:169], v[218:221], v[26:29]
	v_mfma_f32_16x16x32_bf16 v[14:17], v[158:161], v[226:229], v[14:17]
	v_mfma_f32_16x16x32_bf16 v[10:13], v[166:169], v[226:229], v[10:13]
	v_mfma_f32_16x16x32_bf16 v[54:57], v[170:173], v[198:201], v[54:57]
	v_mfma_f32_16x16x32_bf16 v[50:53], v[190:193], v[198:201], v[50:53]
	v_mfma_f32_16x16x32_bf16 v[38:41], v[170:173], v[206:209], v[38:41]
	v_mfma_f32_16x16x32_bf16 v[34:37], v[190:193], v[206:209], v[34:37]
	v_mfma_f32_16x16x32_bf16 v[22:25], v[170:173], v[214:217], v[22:25]
	v_mfma_f32_16x16x32_bf16 v[18:21], v[190:193], v[214:217], v[18:21]
	v_mfma_f32_16x16x32_bf16 v[6:9], v[170:173], v[222:225], v[6:9]
	v_mfma_f32_16x16x32_bf16 v[2:5], v[190:193], v[222:225], v[2:5]
	v_mfma_f32_16x16x32_bf16 v[54:57], v[186:189], v[202:205], v[54:57]
	v_mfma_f32_16x16x32_bf16 v[50:53], v[194:197], v[202:205], v[50:53]
	v_mfma_f32_16x16x32_bf16 v[38:41], v[186:189], v[210:213], v[38:41]
	v_mfma_f32_16x16x32_bf16 v[34:37], v[194:197], v[210:213], v[34:37]
	v_mfma_f32_16x16x32_bf16 v[22:25], v[186:189], v[218:221], v[22:25]
	v_mfma_f32_16x16x32_bf16 v[18:21], v[194:197], v[218:221], v[18:21]
	v_mfma_f32_16x16x32_bf16 v[6:9], v[186:189], v[226:229], v[6:9]
	v_mfma_f32_16x16x32_bf16 v[2:5], v[194:197], v[226:229], v[2:5]
	s_setprio 0
	s_barrier
; #define PG8_STAGE(bufoff, gbase, RR, ld) do { _Pragma("unroll") for (int _i = 0; _i < 2; ++_i) \
;         __builtin_amdgcn_global_load_lds((const unsigned*)((const char*)(gbase) + (RR)[_i] * (ld) + C2[_i]), (LAS unsigned*)(lds + (bufoff) + ldsw + _i * 8192), 16, 0, 0); } while (0)
; #define PG8_LDA(dst, b, h) do { _Pragma("unroll") for (int m = 0; m < 4; ++m) _Pragma("unroll") for (int k = 0; k < 2; ++k) dst[m][k] = *(const LAS bf16x8*)(lds + PG8_SA(b, h) + aoff + m * 2048 + k * 1024); } while (0)
; #define PG8_LDB(dst, b, h) do { _Pragma("unroll") for (int n = 0; n < 2; ++n) _Pragma("unroll") for (int k = 0; k < 2; ++k) dst[n][k] = *(const LAS bf16x8*)(lds + PG8_SB(b, h) + boff + n * 2048 + k * 1024); } while (0)
; #define PG8_MMA(ai, bj, At, Bt) do { __builtin_amdgcn_s_setprio(1); _Pragma("unroll") for (int m = 0; m < 4; ++m) _Pragma("unroll") for (int n = 0; n < 2; ++n) _Pragma("unroll") for (int k = 0; k < 2; ++k) \
;         acc[ai][bj][m][n] = __builtin_amdgcn_mfma_f32_16x16x32_bf16(Bt[n][k], At[m][k], acc[ai][bj][m][n], 0, 0, 0); __builtin_amdgcn_s_setprio(0); } while (0)
; #define PG8_WAIT_V(n) asm volatile("s_waitcnt vmcnt(" #n ")" ::: "memory")
; #define PG8_WAIT_L(n) asm volatile("s_waitcnt lgkmcnt(" #n ")" ::: "memory")
; #define PG8_BAR __builtin_amdgcn_s_barrier()
; #define PG8_SCHED __builtin_amdgcn_sched_barrier(0)
; template <class Sched, class Epi>
; __device__ __forceinline__ void gemm_run(LAS unsigned char* lds, const Sched& S, const Epi& E) {
;     ...
;             PG8_LDB(B0, 1, 0); PG8_LDB(B1, 1, 1); PG8_SCHED; PG8_LDA(At, 1, 0); PG8_STAGE(PG8_SA(0, 1), a2 + (size_t)HALF * la2, RA, la2);
;             PG8_WAIT_V(8); PG8_WAIT_L(0); PG8_BAR; PG8_MMA(0, 0, At, B0); PG8_MMA(0, 1, At, B1); PG8_BAR; PG8_SCHED;
	s_add_i32 s39, 0, 0x18000
	v_add_u32_e32 v134, s39, v179
	s_add_i32 s42, 0, 0x1c000
	ds_read_b128 v[154:157], v134
	ds_read_b128 v[158:161], v134 offset:1024
	ds_read_b128 v[162:165], v134 offset:2048
	ds_read_b128 v[166:169], v134 offset:3072
	v_add_u32_e32 v134, s42, v179
	ds_read_b128 v[170:173], v134
	ds_read_b128 v[186:189], v134 offset:1024
	ds_read_b128 v[190:193], v134 offset:2048
	ds_read_b128 v[194:197], v134 offset:3072
	s_add_u32 s40, s58, 0x80000
	s_addc_u32 s41, s59, 0
	v_lshl_add_u64 v[236:237], s[40:41], 0, v[138:139]
	s_mov_b32 m0, s60
	v_lshl_add_u64 v[236:237], v[236:237], 0, v[130:131]
	ds_read_b128 v[198:201], v184 offset:32768
	ds_read_b128 v[202:205], v184 offset:33792
	ds_read_b128 v[206:209], v184 offset:34816
	ds_read_b128 v[210:213], v184 offset:35840
	ds_read_b128 v[214:217], v184 offset:36864
	ds_read_b128 v[218:221], v184 offset:37888
	ds_read_b128 v[222:225], v184 offset:38912
	ds_read_b128 v[226:229], v184 offset:39936
	global_load_lds_dwordx4 v[236:237], off
	v_lshl_add_u64 v[236:237], s[40:41], 0, v[140:141]
	v_lshl_add_u64 v[236:237], v[236:237], 0, v[130:131]
	s_mov_b32 m0, s61
	s_nop 0
	global_load_lds_dwordx4 v[236:237], off
	s_waitcnt vmcnt(8)
	s_waitcnt lgkmcnt(0)
	s_barrier
	s_setprio 1
	s_waitcnt lgkmcnt(0)
	v_mfma_f32_16x16x32_bf16 v[126:129], v[154:157], v[198:201], v[126:129]
	v_mfma_f32_16x16x32_bf16 v[122:125], v[162:165], v[198:201], v[122:125]
	v_mfma_f32_16x16x32_bf16 v[110:113], v[154:157], v[206:209], v[110:113]
	v_mfma_f32_16x16x32_bf16 v[106:109], v[162:165], v[206:209], v[106:109]
	v_mfma_f32_16x16x32_bf16 v[94:97], v[154:157], v[214:217], v[94:97]
	v_mfma_f32_16x16x32_bf16 v[90:93], v[162:165], v[214:217], v[90:93]
	v_mfma_f32_16x16x32_bf16 v[78:81], v[154:157], v[222:225], v[78:81]
	v_mfma_f32_16x16x32_bf16 v[74:77], v[162:165], v[222:225], v[74:77]
	v_mfma_f32_16x16x32_bf16 v[126:129], v[158:161], v[202:205], v[126:129]
	v_mfma_f32_16x16x32_bf16 v[122:125], v[166:169], v[202:205], v[122:125]
	v_mfma_f32_16x16x32_bf16 v[110:113], v[158:161], v[210:213], v[110:113]
	v_mfma_f32_16x16x32_bf16 v[106:109], v[166:169], v[210:213], v[106:109]
	v_mfma_f32_16x16x32_bf16 v[94:97], v[158:161], v[218:221], v[94:97]
	v_mfma_f32_16x16x32_bf16 v[90:93], v[166:169], v[218:221], v[90:93]
	v_mfma_f32_16x16x32_bf16 v[78:81], v[158:161], v[226:229], v[78:81]
	v_mfma_f32_16x16x32_bf16 v[74:77], v[166:169], v[226:229], v[74:77]
	v_mfma_f32_16x16x32_bf16 v[118:121], v[170:173], v[198:201], v[118:121]
	v_mfma_f32_16x16x32_bf16 v[114:117], v[190:193], v[198:201], v[114:117]
	v_mfma_f32_16x16x32_bf16 v[102:105], v[170:173], v[206:209], v[102:105]
	v_mfma_f32_16x16x32_bf16 v[98:101], v[190:193], v[206:209], v[98:101]
	v_mfma_f32_16x16x32_bf16 v[86:89], v[170:173], v[214:217], v[86:89]
	v_mfma_f32_16x16x32_bf16 v[82:85], v[190:193], v[214:217], v[82:85]
	v_mfma_f32_16x16x32_bf16 v[70:73], v[170:173], v[222:225], v[70:73]
	v_mfma_f32_16x16x32_bf16 v[66:69], v[190:193], v[222:225], v[66:69]
	v_mfma_f32_16x16x32_bf16 v[118:121], v[186:189], v[202:205], v[118:121]
	v_mfma_f32_16x16x32_bf16 v[114:117], v[194:197], v[202:205], v[114:117]
	v_mfma_f32_16x16x32_bf16 v[102:105], v[186:189], v[210:213], v[102:105]
	v_mfma_f32_16x16x32_bf16 v[98:101], v[194:197], v[210:213], v[98:101]
	v_mfma_f32_16x16x32_bf16 v[86:89], v[186:189], v[218:221], v[86:89]
	v_mfma_f32_16x16x32_bf16 v[82:85], v[194:197], v[218:221], v[82:85]
	v_mfma_f32_16x16x32_bf16 v[70:73], v[186:189], v[226:229], v[70:73]
	v_mfma_f32_16x16x32_bf16 v[66:69], v[194:197], v[226:229], v[66:69]
	s_setprio 0
	s_barrier
; #define PG8_STAGE(bufoff, gbase, RR, ld) do { _Pragma("unroll") for (int _i = 0; _i < 2; ++_i) \
;         __builtin_amdgcn_global_load_lds((const unsigned*)((const char*)(gbase) + (RR)[_i] * (ld) + C2[_i]), (LAS unsigned*)(lds + (bufoff) + ldsw + _i * 8192), 16, 0, 0); } while (0)
; #define PG8_LDA(dst, b, h) do { _Pragma("unroll") for (int m = 0; m < 4; ++m) _Pragma("unroll") for (int k = 0; k < 2; ++k) dst[m][k] = *(const LAS bf16x8*)(lds + PG8_SA(b, h) + aoff + m * 2048 + k * 1024); } while (0)
; #define PG8_MMA(ai, bj, At, Bt) do { __builtin_amdgcn_s_setprio(1); _Pragma("unroll") for (int m = 0; m < 4; ++m) _Pragma("unroll") for (int n = 0; n < 2; ++n) _Pragma("unroll") for (int k = 0; k < 2; ++k) \
;         acc[ai][bj][m][n] = __builtin_amdgcn_mfma_f32_16x16x32_bf16(Bt[n][k], At[m][k], acc[ai][bj][m][n], 0, 0, 0); __builtin_amdgcn_s_setprio(0); } while (0)
; #define PG8_WAIT_V(n) asm volatile("s_waitcnt vmcnt(" #n ")" ::: "memory")
; #define PG8_WAIT_L(n) asm volatile("s_waitcnt lgkmcnt(" #n ")" ::: "memory")
; #define PG8_BAR __builtin_amdgcn_s_barrier()
; #define PG8_SCHED __builtin_amdgcn_sched_barrier(0)
; template <class Sched, class Epi>
; __device__ __forceinline__ void gemm_run(LAS unsigned char* lds, const Sched& S, const Epi& E) {
;     ...
;             PG8_LDA(At, 1, 1); PG8_STAGE(PG8_SB(1, 0), b3, RB, lb2); PG8_STAGE(PG8_SB(1, 1), b3 + (size_t)HALF * lb2, RB, lb2); PG8_STAGE(PG8_SA(1, 0), a3, RA, la2);
;             PG8_WAIT_V(8); PG8_WAIT_L(0); PG8_BAR; PG8_MMA(1, 0, At, B0); PG8_MMA(1, 1, At, B1); PG8_BAR; PG8_SCHED;
;         }
;         if (wr == 0) PG8_BAR;
	s_add_i32 s39, s39, s3
	v_lshl_add_u64 v[174:175], v[174:175], 0, s[14:15]
	s_mov_b32 m0, s39
	ds_read_b128 v[198:201], v184 offset:49152
	ds_read_b128 v[202:205], v184 offset:50176
	ds_read_b128 v[206:209], v184 offset:51200
	ds_read_b128 v[210:213], v184 offset:52224
	ds_read_b128 v[214:217], v184 offset:53248
	ds_read_b128 v[218:221], v184 offset:54272
	ds_read_b128 v[222:225], v184 offset:55296
	ds_read_b128 v[226:229], v184 offset:56320
	global_load_lds_dwordx4 v[174:175], off
	s_add_i32 m0, s39, 0x2000
	s_add_u32 s40, s56, 0x80080
	v_lshl_add_u64 v[174:175], v[230:231], 0, s[14:15]
	s_addc_u32 s41, s57, 0
	global_load_lds_dwordx4 v[174:175], off
	v_lshl_add_u64 v[174:175], s[40:41], 0, v[132:133]
	s_add_i32 s39, s42, s3
	v_lshl_add_u64 v[174:175], v[174:175], 0, v[130:131]
	s_mov_b32 m0, s39
	s_nop 0
	global_load_lds_dwordx4 v[174:175], off
	v_lshl_add_u64 v[174:175], s[40:41], 0, v[136:137]
	v_lshl_add_u64 v[174:175], v[174:175], 0, v[130:131]
	s_add_i32 m0, s39, 0x2000
	s_nop 0
	global_load_lds_dwordx4 v[174:175], off
	v_lshl_add_u64 v[174:175], v[232:233], 0, s[14:15]
	s_mov_b32 m0, s64
	s_nop 0
	global_load_lds_dwordx4 v[174:175], off
	v_lshl_add_u64 v[174:175], v[234:235], 0, s[14:15]
	s_mov_b32 m0, s65
	s_nop 0
	global_load_lds_dwordx4 v[174:175], off
	s_waitcnt vmcnt(8)
	s_waitcnt lgkmcnt(0)
	s_barrier
	s_setprio 1
	s_waitcnt lgkmcnt(0)
	v_mfma_f32_16x16x32_bf16 v[62:65], v[154:157], v[198:201], v[62:65]
	v_mfma_f32_16x16x32_bf16 v[58:61], v[162:165], v[198:201], v[58:61]
	v_mfma_f32_16x16x32_bf16 v[46:49], v[154:157], v[206:209], v[46:49]
	v_mfma_f32_16x16x32_bf16 v[42:45], v[162:165], v[206:209], v[42:45]
	v_mfma_f32_16x16x32_bf16 v[30:33], v[154:157], v[214:217], v[30:33]
	v_mfma_f32_16x16x32_bf16 v[26:29], v[162:165], v[214:217], v[26:29]
	v_mfma_f32_16x16x32_bf16 v[14:17], v[154:157], v[222:225], v[14:17]
	v_mfma_f32_16x16x32_bf16 v[10:13], v[162:165], v[222:225], v[10:13]
	v_mfma_f32_16x16x32_bf16 v[62:65], v[158:161], v[202:205], v[62:65]
	v_mfma_f32_16x16x32_bf16 v[58:61], v[166:169], v[202:205], v[58:61]
	v_mfma_f32_16x16x32_bf16 v[46:49], v[158:161], v[210:213], v[46:49]
	v_mfma_f32_16x16x32_bf16 v[42:45], v[166:169], v[210:213], v[42:45]
	v_mfma_f32_16x16x32_bf16 v[30:33], v[158:161], v[218:221], v[30:33]
	v_mfma_f32_16x16x32_bf16 v[26:29], v[166:169], v[218:221], v[26:29]
	v_mfma_f32_16x16x32_bf16 v[14:17], v[158:161], v[226:229], v[14:17]
	v_mfma_f32_16x16x32_bf16 v[10:13], v[166:169], v[226:229], v[10:13]
	v_mfma_f32_16x16x32_bf16 v[54:57], v[170:173], v[198:201], v[54:57]
	v_mfma_f32_16x16x32_bf16 v[50:53], v[190:193], v[198:201], v[50:53]
	v_mfma_f32_16x16x32_bf16 v[38:41], v[170:173], v[206:209], v[38:41]
	v_mfma_f32_16x16x32_bf16 v[34:37], v[190:193], v[206:209], v[34:37]
	v_mfma_f32_16x16x32_bf16 v[22:25], v[170:173], v[214:217], v[22:25]
	v_mfma_f32_16x16x32_bf16 v[18:21], v[190:193], v[214:217], v[18:21]
	v_mfma_f32_16x16x32_bf16 v[6:9], v[170:173], v[222:225], v[6:9]
	v_mfma_f32_16x16x32_bf16 v[2:5], v[190:193], v[222:225], v[2:5]
	v_mfma_f32_16x16x32_bf16 v[54:57], v[186:189], v[202:205], v[54:57]
	v_mfma_f32_16x16x32_bf16 v[50:53], v[194:197], v[202:205], v[50:53]
	v_mfma_f32_16x16x32_bf16 v[38:41], v[186:189], v[210:213], v[38:41]
	v_mfma_f32_16x16x32_bf16 v[34:37], v[194:197], v[210:213], v[34:37]
	v_mfma_f32_16x16x32_bf16 v[22:25], v[186:189], v[218:221], v[22:25]
	v_mfma_f32_16x16x32_bf16 v[18:21], v[194:197], v[218:221], v[18:21]
	v_mfma_f32_16x16x32_bf16 v[6:9], v[186:189], v[226:229], v[6:9]
	v_mfma_f32_16x16x32_bf16 v[2:5], v[194:197], v[226:229], v[2:5]
	s_setprio 0
	s_barrier
	s_add_i32 s38, s38, 2
	s_add_u32 s54, s54, 0x100
	s_addc_u32 s55, s55, 0
	s_cmp_gt_u32 s38, 29
	s_cbranch_scc0 .LBB0_246
	s_and_b64 vcc, exec, s[16:17]
	s_cbranch_vccz .LBB0_249
	s_barrier

; #define PG8_STAGE(bufoff, gbase, RR, ld) do { _Pragma("unroll") for (int _i = 0; _i < 2; ++_i) \
;         __builtin_amdgcn_global_load_lds((const unsigned*)((const char*)(gbase) + (RR)[_i] * (ld) + C2[_i]), (LAS unsigned*)(lds + (bufoff) + ldsw + _i * 8192), 16, 0, 0); } while (0)
; #define PG8_LDA(dst, b, h) do { _Pragma("unroll") for (int m = 0; m < 4; ++m) _Pragma("unroll") for (int k = 0; k < 2; ++k) dst[m][k] = *(const LAS bf16x8*)(lds + PG8_SA(b, h) + aoff + m * 2048 + k * 1024); } while (0)
; #define PG8_LDB(dst, b, h) do { _Pragma("unroll") for (int n = 0; n < 2; ++n) _Pragma("unroll") for (int k = 0; k < 2; ++k) dst[n][k] = *(const LAS bf16x8*)(lds + PG8_SB(b, h) + boff + n * 2048 + k * 1024); } while (0)
; #define PG8_SCHED __builtin_amdgcn_sched_barrier(0)
; template <class Sched, class Epi>
; __device__ __forceinline__ void gemm_run(LAS unsigned char* lds, const Sched& S, const Epi& E) {
;     ...
;         const bool has_next = S.next(ui + 1, nxt);
;         const char* nA = has_next ? nxt.A : cA; const char* nB = has_next ? nxt.B : cB; const unsigned nlda = has_next ? nxt.lda : lda, nldb = has_next ? nxt.ldb : ldb;
;         const int nt = cur.nt;
;         for (int t = 0; t < nt; t += 2) {
;             const bool last = (t == nt - 2);
;             const char* a1 = cA + (size_t)(t + 1) * kstep;
;             const char* a2 = last ? nA : cA + (size_t)(t + 2) * kstep; const char* b2 = last ? nB : cB + (size_t)(t + 2) * kstep;
;             const unsigned la2 = last ? nlda : lda, lb2 = last ? nldb : ldb;
;             const char* a3 = a2 + kstep; const char* b3 = b2 + kstep;
;             PG8_LDB(B0, 0, 0); PG8_LDB(B1, 0, 1); PG8_SCHED; PG8_LDA(At, 0, 0); PG8_STAGE(PG8_SA(1, 1), a1 + (size_t)HALF * lda, RA, lda);
;     ...
;         for (int a = 0; a < 2; ++a)
; #pragma unroll
;             for (int b = 0; b < 2; ++b)
; #pragma unroll
;                 for (int m = 0; m < 4; ++m)
; #pragma unroll
;                     for (int n = 0; n < 2; ++n) acc[a][b][m][n] = (f32x4){0.f, 0.f, 0.f, 0.f};
;         cur = nxt; cA = nA; cB = nB; lda = nlda; ldb = nldb; ++ui;
.LBB0_439:
	s_and_b64 s[38:39], s[36:37], exec
	s_mov_b32 s63, s1
	s_cselect_b32 s55, s29, s59
	s_cselect_b32 s61, s28, s58
	s_cselect_b32 vcc_lo, s31, s65
	s_cselect_b32 vcc_hi, s30, s64
	s_lshl_b64 s[42:43], s[62:63], 7
	v_mul_lo_u32 v148, v177, s62
	v_lshl_add_u64 v[2:3], s[58:59], 0, v[160:161]
	v_lshl_add_u64 v[4:5], s[42:43], 0, v[148:149]
	v_mul_lo_u32 v148, v178, s62
	s_add_i32 s38, s5, -2
	v_lshl_add_u64 v[130:131], v[2:3], 0, v[4:5]
	v_lshl_add_u64 v[4:5], s[42:43], 0, v[148:149]
	s_add_u32 s39, s64, 0x100
	v_lshl_add_u64 v[132:133], v[2:3], 0, v[4:5]
	v_mov_b32_e32 v2, 0
	s_addc_u32 s40, s65, 0
	s_mov_b64 s[64:65], 0
	v_mov_b32_e32 v3, v2
	v_mov_b32_e32 v4, v2
	v_mov_b32_e32 v5, v2
	v_mov_b32_e32 v6, v2
	v_mov_b32_e32 v7, v2
	v_mov_b32_e32 v8, v2
	v_mov_b32_e32 v9, v2
	v_mov_b32_e32 v18, v2
	v_mov_b32_e32 v19, v2
	v_mov_b32_e32 v20, v2
	v_mov_b32_e32 v21, v2
	v_mov_b32_e32 v22, v2
	v_mov_b32_e32 v23, v2
	v_mov_b32_e32 v24, v2
	v_mov_b32_e32 v25, v2
	v_mov_b32_e32 v34, v2
	v_mov_b32_e32 v35, v2
	v_mov_b32_e32 v36, v2
	v_mov_b32_e32 v37, v2
	v_mov_b32_e32 v38, v2
	v_mov_b32_e32 v39, v2
	v_mov_b32_e32 v40, v2
	v_mov_b32_e32 v41, v2
	v_mov_b32_e32 v50, v2
	v_mov_b32_e32 v51, v2
	v_mov_b32_e32 v52, v2
	v_mov_b32_e32 v53, v2
	v_mov_b32_e32 v54, v2
	v_mov_b32_e32 v55, v2
	v_mov_b32_e32 v56, v2
	v_mov_b32_e32 v57, v2
	v_mov_b32_e32 v10, v2
	v_mov_b32_e32 v11, v2
	v_mov_b32_e32 v12, v2
	v_mov_b32_e32 v13, v2
	v_mov_b32_e32 v14, v2
	v_mov_b32_e32 v15, v2
	v_mov_b32_e32 v16, v2
	v_mov_b32_e32 v17, v2
	v_mov_b32_e32 v26, v2
	v_mov_b32_e32 v27, v2
	v_mov_b32_e32 v28, v2
	v_mov_b32_e32 v29, v2
	v_mov_b32_e32 v30, v2
	v_mov_b32_e32 v31, v2
	v_mov_b32_e32 v32, v2
	v_mov_b32_e32 v33, v2
	v_mov_b32_e32 v42, v2
	v_mov_b32_e32 v43, v2
	v_mov_b32_e32 v44, v2
	v_mov_b32_e32 v45, v2
	v_mov_b32_e32 v46, v2
	v_mov_b32_e32 v47, v2
	v_mov_b32_e32 v48, v2
	v_mov_b32_e32 v49, v2
	v_mov_b32_e32 v58, v2
	v_mov_b32_e32 v59, v2
	v_mov_b32_e32 v60, v2
	v_mov_b32_e32 v61, v2
	v_mov_b32_e32 v62, v2
	v_mov_b32_e32 v63, v2
	v_mov_b32_e32 v64, v2
	v_mov_b32_e32 v65, v2
	v_mov_b32_e32 v66, v2
	v_mov_b32_e32 v67, v2
	v_mov_b32_e32 v68, v2
	v_mov_b32_e32 v69, v2
	v_mov_b32_e32 v70, v2
	v_mov_b32_e32 v71, v2
	v_mov_b32_e32 v72, v2
	v_mov_b32_e32 v73, v2
	v_mov_b32_e32 v82, v2
	v_mov_b32_e32 v83, v2
	v_mov_b32_e32 v84, v2
	v_mov_b32_e32 v85, v2
	v_mov_b32_e32 v86, v2
	v_mov_b32_e32 v87, v2
	v_mov_b32_e32 v88, v2
	v_mov_b32_e32 v89, v2
	v_mov_b32_e32 v98, v2
	v_mov_b32_e32 v99, v2
	v_mov_b32_e32 v100, v2
	v_mov_b32_e32 v101, v2
	v_mov_b32_e32 v102, v2
	v_mov_b32_e32 v103, v2
	v_mov_b32_e32 v104, v2
	v_mov_b32_e32 v105, v2
	v_mov_b32_e32 v114, v2
	v_mov_b32_e32 v115, v2
	v_mov_b32_e32 v116, v2
	v_mov_b32_e32 v117, v2
	v_mov_b32_e32 v118, v2
	v_mov_b32_e32 v119, v2
	v_mov_b32_e32 v120, v2
	v_mov_b32_e32 v121, v2
	v_mov_b32_e32 v74, v2
	v_mov_b32_e32 v75, v2
	v_mov_b32_e32 v76, v2
	v_mov_b32_e32 v77, v2
	v_mov_b32_e32 v78, v2
	v_mov_b32_e32 v79, v2
	v_mov_b32_e32 v80, v2
	v_mov_b32_e32 v81, v2
	v_mov_b32_e32 v90, v2
	v_mov_b32_e32 v91, v2
	v_mov_b32_e32 v92, v2
	v_mov_b32_e32 v93, v2
	v_mov_b32_e32 v94, v2
	v_mov_b32_e32 v95, v2
	v_mov_b32_e32 v96, v2
	v_mov_b32_e32 v97, v2
	v_mov_b32_e32 v106, v2
	v_mov_b32_e32 v107, v2
	v_mov_b32_e32 v108, v2
	v_mov_b32_e32 v109, v2
	v_mov_b32_e32 v110, v2
	v_mov_b32_e32 v111, v2
	v_mov_b32_e32 v112, v2
	v_mov_b32_e32 v113, v2
	v_mov_b32_e32 v122, v2
	v_mov_b32_e32 v123, v2
	v_mov_b32_e32 v124, v2
	v_mov_b32_e32 v125, v2
	v_mov_b32_e32 v126, v2
	v_mov_b32_e32 v127, v2
	v_mov_b32_e32 v128, v2
	v_mov_b32_e32 v129, v2
	.p2align 6
.LBB0_440:
	s_add_i32 s41, s0, 2
	s_add_u32 s42, s58, s64
	s_addc_u32 s43, s59, s65
	ds_read_b128 v[134:137], v179
	ds_read_b128 v[138:141], v179 offset:1024
	ds_read_b128 v[142:145], v179 offset:2048
	ds_read_b128 v[162:165], v179 offset:3072
	ds_read_b128 v[166:169], v180
	ds_read_b128 v[186:189], v180 offset:1024
	ds_read_b128 v[190:193], v180 offset:2048
	ds_read_b128 v[194:197], v180 offset:3072
	s_add_u32 s46, s42, 0x100
	s_addc_u32 s47, s43, 0
	s_add_u32 s48, s39, s64
	s_addc_u32 s49, s40, s65
	s_cmp_eq_u32 s38, s0
	s_cselect_b64 s[42:43], -1, 0
	s_and_b64 s[44:45], s[42:43], exec
	s_cselect_b32 s67, s55, s47
	s_cselect_b32 s66, s61, s46
	s_cselect_b32 s71, vcc_lo, s49
	s_cselect_b32 s70, vcc_hi, s48
	s_and_b64 s[42:43], s[36:37], s[42:43]
	s_and_b64 s[42:43], s[42:43], exec
	s_cselect_b32 s0, s3, s60
	s_cselect_b32 s68, s4, s62
	v_lshl_add_u64 v[170:171], v[130:131], 0, s[64:65]
	s_add_i32 m0, s82, 0xc000
	ds_read_b128 v[198:201], v181
	ds_read_b128 v[202:205], v181 offset:1024
	ds_read_b128 v[206:209], v181 offset:2048
	ds_read_b128 v[210:213], v181 offset:3072
	ds_read_b128 v[214:217], v181 offset:4096
	ds_read_b128 v[218:221], v181 offset:5120
	ds_read_b128 v[222:225], v181 offset:6144
	ds_read_b128 v[226:229], v181 offset:7168
	global_load_lds_dwordx4 v[170:171], off
	v_lshl_add_u64 v[170:171], v[132:133], 0, s[64:65]
	s_add_i32 m0, s82, 0xe000
	s_nop 0
	global_load_lds_dwordx4 v[170:171], off
	s_waitcnt vmcnt(8)
	s_waitcnt lgkmcnt(0)
	s_barrier
; #define PG8_STAGE(bufoff, gbase, RR, ld) do { _Pragma("unroll") for (int _i = 0; _i < 2; ++_i) \
;         __builtin_amdgcn_global_load_lds((const unsigned*)((const char*)(gbase) + (RR)[_i] * (ld) + C2[_i]), (LAS unsigned*)(lds + (bufoff) + ldsw + _i * 8192), 16, 0, 0); } while (0)
; #define PG8_LDA(dst, b, h) do { _Pragma("unroll") for (int m = 0; m < 4; ++m) _Pragma("unroll") for (int k = 0; k < 2; ++k) dst[m][k] = *(const LAS bf16x8*)(lds + PG8_SA(b, h) + aoff + m * 2048 + k * 1024); } while (0)
; #define PG8_MMA(ai, bj, At, Bt) do { __builtin_amdgcn_s_setprio(1); _Pragma("unroll") for (int m = 0; m < 4; ++m) _Pragma("unroll") for (int n = 0; n < 2; ++n) _Pragma("unroll") for (int k = 0; k < 2; ++k) \
;         acc[ai][bj][m][n] = __builtin_amdgcn_mfma_f32_16x16x32_bf16(Bt[n][k], At[m][k], acc[ai][bj][m][n], 0, 0, 0); __builtin_amdgcn_s_setprio(0); } while (0)
; #define PG8_WAIT_V(n) asm volatile("s_waitcnt vmcnt(" #n ")" ::: "memory")
; #define PG8_WAIT_L(n) asm volatile("s_waitcnt lgkmcnt(" #n ")" ::: "memory")
; #define PG8_BAR __builtin_amdgcn_s_barrier()
; #define PG8_SCHED __builtin_amdgcn_sched_barrier(0)
; template <class Sched, class Epi>
; __device__ __forceinline__ void gemm_run(LAS unsigned char* lds, const Sched& S, const Epi& E) {
;     ...
;             PG8_WAIT_V(8); PG8_WAIT_L(0); PG8_BAR; PG8_MMA(0, 0, At, B0); PG8_MMA(0, 1, At, B1); PG8_BAR; PG8_SCHED;
;             PG8_LDA(At, 0, 1); PG8_STAGE(PG8_SB(0, 0), b2, RB, lb2); PG8_STAGE(PG8_SB(0, 1), b2 + (size_t)HALF * lb2, RB, lb2); PG8_STAGE(PG8_SA(0, 0), a2, RA, la2);
;             PG8_WAIT_V(8); PG8_WAIT_L(0); PG8_BAR; PG8_MMA(1, 0, At, B0); PG8_MMA(1, 1, At, B1); PG8_BAR; PG8_SCHED;
	s_setprio 1
	s_waitcnt lgkmcnt(0)
	v_mfma_f32_16x16x32_bf16 v[126:129], v[134:137], v[198:201], v[126:129]
	v_mfma_f32_16x16x32_bf16 v[122:125], v[142:145], v[198:201], v[122:125]
	v_mfma_f32_16x16x32_bf16 v[110:113], v[134:137], v[206:209], v[110:113]
	v_mfma_f32_16x16x32_bf16 v[106:109], v[142:145], v[206:209], v[106:109]
	v_mfma_f32_16x16x32_bf16 v[94:97], v[134:137], v[214:217], v[94:97]
	v_mfma_f32_16x16x32_bf16 v[90:93], v[142:145], v[214:217], v[90:93]
	v_mfma_f32_16x16x32_bf16 v[78:81], v[134:137], v[222:225], v[78:81]
	v_mfma_f32_16x16x32_bf16 v[74:77], v[142:145], v[222:225], v[74:77]
	v_mfma_f32_16x16x32_bf16 v[126:129], v[138:141], v[202:205], v[126:129]
	v_mfma_f32_16x16x32_bf16 v[122:125], v[162:165], v[202:205], v[122:125]
	v_mfma_f32_16x16x32_bf16 v[110:113], v[138:141], v[210:213], v[110:113]
	v_mfma_f32_16x16x32_bf16 v[106:109], v[162:165], v[210:213], v[106:109]
	v_mfma_f32_16x16x32_bf16 v[94:97], v[138:141], v[218:221], v[94:97]
	v_mfma_f32_16x16x32_bf16 v[90:93], v[162:165], v[218:221], v[90:93]
	v_mfma_f32_16x16x32_bf16 v[78:81], v[138:141], v[226:229], v[78:81]
	v_mfma_f32_16x16x32_bf16 v[74:77], v[162:165], v[226:229], v[74:77]
	v_mfma_f32_16x16x32_bf16 v[118:121], v[166:169], v[198:201], v[118:121]
	v_mfma_f32_16x16x32_bf16 v[114:117], v[190:193], v[198:201], v[114:117]
	v_mfma_f32_16x16x32_bf16 v[102:105], v[166:169], v[206:209], v[102:105]
	v_mfma_f32_16x16x32_bf16 v[98:101], v[190:193], v[206:209], v[98:101]
	v_mfma_f32_16x16x32_bf16 v[86:89], v[166:169], v[214:217], v[86:89]
	v_mfma_f32_16x16x32_bf16 v[82:85], v[190:193], v[214:217], v[82:85]
	v_mfma_f32_16x16x32_bf16 v[70:73], v[166:169], v[222:225], v[70:73]
	v_mfma_f32_16x16x32_bf16 v[66:69], v[190:193], v[222:225], v[66:69]
	v_mfma_f32_16x16x32_bf16 v[118:121], v[186:189], v[202:205], v[118:121]
	v_mfma_f32_16x16x32_bf16 v[114:117], v[194:197], v[202:205], v[114:117]
	v_mfma_f32_16x16x32_bf16 v[102:105], v[186:189], v[210:213], v[102:105]
	v_mfma_f32_16x16x32_bf16 v[98:101], v[194:197], v[210:213], v[98:101]
	v_mfma_f32_16x16x32_bf16 v[86:89], v[186:189], v[218:221], v[86:89]
	v_mfma_f32_16x16x32_bf16 v[82:85], v[194:197], v[218:221], v[82:85]
	v_mfma_f32_16x16x32_bf16 v[70:73], v[186:189], v[226:229], v[70:73]
	v_mfma_f32_16x16x32_bf16 v[66:69], v[194:197], v[226:229], v[66:69]
	s_setprio 0
	s_barrier
	v_mul_lo_u32 v148, s0, v173
	v_lshl_add_u64 v[170:171], s[70:71], 0, v[148:149]
	s_add_i32 s42, s97, s81
	v_lshl_add_u64 v[170:171], v[170:171], 0, v[146:147]
	s_mov_b32 m0, s42
	ds_read_b128 v[198:201], v181 offset:16384
	ds_read_b128 v[202:205], v181 offset:17408
	ds_read_b128 v[206:209], v181 offset:18432
	ds_read_b128 v[210:213], v181 offset:19456
	ds_read_b128 v[214:217], v181 offset:20480
	ds_read_b128 v[218:221], v181 offset:21504
	ds_read_b128 v[222:225], v181 offset:22528
	ds_read_b128 v[226:229], v181 offset:23552
	global_load_lds_dwordx4 v[170:171], off
	s_add_i32 m0, s42, 0x2000
	s_lshl_b64 s[42:43], s[0:1], 7
	v_mul_lo_u32 v230, s0, v175
	v_mov_b32_e32 v231, v149
	s_add_u32 s42, s70, s42
	v_lshl_add_u64 v[232:233], s[70:71], 0, v[230:231]
	s_addc_u32 s43, s71, s43
	v_lshl_add_u64 v[232:233], v[232:233], 0, v[146:147]
	v_lshl_add_u64 v[234:235], s[42:43], 0, v[148:149]
	s_add_i32 s0, s33, s81
	global_load_lds_dwordx4 v[232:233], off
	v_lshl_add_u64 v[234:235], v[234:235], 0, v[146:147]
	s_mov_b32 m0, s0
	v_lshl_add_u64 v[230:231], s[42:43], 0, v[230:231]
	v_mul_lo_u32 v148, s68, v172
	global_load_lds_dwordx4 v[234:235], off
	v_lshl_add_u64 v[230:231], v[230:231], 0, v[146:147]
	s_add_i32 m0, s0, 0x2000
	v_lshl_add_u64 v[236:237], s[66:67], 0, v[148:149]
	v_mul_lo_u32 v238, s68, v174
	v_mov_b32_e32 v239, v149
	global_load_lds_dwordx4 v[230:231], off
	v_lshl_add_u64 v[236:237], v[236:237], 0, v[146:147]
	s_mov_b32 m0, s82
	v_lshl_add_u64 v[240:241], s[66:67], 0, v[238:239]
	global_load_lds_dwordx4 v[236:237], off
	v_lshl_add_u64 v[240:241], v[240:241], 0, v[146:147]
	s_mov_b32 m0, s83
	s_nop 0
	global_load_lds_dwordx4 v[240:241], off
	s_waitcnt vmcnt(8)
	s_waitcnt lgkmcnt(0)
	s_barrier
	s_setprio 1
	s_waitcnt lgkmcnt(0)
	v_mfma_f32_16x16x32_bf16 v[62:65], v[134:137], v[198:201], v[62:65]
	v_mfma_f32_16x16x32_bf16 v[58:61], v[142:145], v[198:201], v[58:61]
	v_mfma_f32_16x16x32_bf16 v[46:49], v[134:137], v[206:209], v[46:49]
	v_mfma_f32_16x16x32_bf16 v[42:45], v[142:145], v[206:209], v[42:45]
	v_mfma_f32_16x16x32_bf16 v[30:33], v[134:137], v[214:217], v[30:33]
	v_mfma_f32_16x16x32_bf16 v[26:29], v[142:145], v[214:217], v[26:29]
	v_mfma_f32_16x16x32_bf16 v[14:17], v[134:137], v[222:225], v[14:17]
	v_mfma_f32_16x16x32_bf16 v[10:13], v[142:145], v[222:225], v[10:13]
	v_mfma_f32_16x16x32_bf16 v[62:65], v[138:141], v[202:205], v[62:65]
	v_mfma_f32_16x16x32_bf16 v[58:61], v[162:165], v[202:205], v[58:61]
	v_mfma_f32_16x16x32_bf16 v[46:49], v[138:141], v[210:213], v[46:49]
	v_mfma_f32_16x16x32_bf16 v[42:45], v[162:165], v[210:213], v[42:45]
	v_mfma_f32_16x16x32_bf16 v[30:33], v[138:141], v[218:221], v[30:33]
	v_mfma_f32_16x16x32_bf16 v[26:29], v[162:165], v[218:221], v[26:29]
	v_mfma_f32_16x16x32_bf16 v[14:17], v[138:141], v[226:229], v[14:17]
	v_mfma_f32_16x16x32_bf16 v[10:13], v[162:165], v[226:229], v[10:13]
	v_mfma_f32_16x16x32_bf16 v[54:57], v[166:169], v[198:201], v[54:57]
	v_mfma_f32_16x16x32_bf16 v[50:53], v[190:193], v[198:201], v[50:53]
	v_mfma_f32_16x16x32_bf16 v[38:41], v[166:169], v[206:209], v[38:41]
	v_mfma_f32_16x16x32_bf16 v[34:37], v[190:193], v[206:209], v[34:37]
	v_mfma_f32_16x16x32_bf16 v[22:25], v[166:169], v[214:217], v[22:25]
	v_mfma_f32_16x16x32_bf16 v[18:21], v[190:193], v[214:217], v[18:21]
	v_mfma_f32_16x16x32_bf16 v[6:9], v[166:169], v[222:225], v[6:9]
	v_mfma_f32_16x16x32_bf16 v[2:5], v[190:193], v[222:225], v[2:5]
	v_mfma_f32_16x16x32_bf16 v[54:57], v[186:189], v[202:205], v[54:57]
	v_mfma_f32_16x16x32_bf16 v[50:53], v[194:197], v[202:205], v[50:53]
	v_mfma_f32_16x16x32_bf16 v[38:41], v[186:189], v[210:213], v[38:41]
	v_mfma_f32_16x16x32_bf16 v[34:37], v[194:197], v[210:213], v[34:37]
	v_mfma_f32_16x16x32_bf16 v[22:25], v[186:189], v[218:221], v[22:25]
	v_mfma_f32_16x16x32_bf16 v[18:21], v[194:197], v[218:221], v[18:21]
	v_mfma_f32_16x16x32_bf16 v[6:9], v[186:189], v[226:229], v[6:9]
	v_mfma_f32_16x16x32_bf16 v[2:5], v[194:197], v[226:229], v[2:5]
	s_setprio 0
	s_barrier
; #define PG8_STAGE(bufoff, gbase, RR, ld) do { _Pragma("unroll") for (int _i = 0; _i < 2; ++_i) \
;         __builtin_amdgcn_global_load_lds((const unsigned*)((const char*)(gbase) + (RR)[_i] * (ld) + C2[_i]), (LAS unsigned*)(lds + (bufoff) + ldsw + _i * 8192), 16, 0, 0); } while (0)
; #define PG8_LDA(dst, b, h) do { _Pragma("unroll") for (int m = 0; m < 4; ++m) _Pragma("unroll") for (int k = 0; k < 2; ++k) dst[m][k] = *(const LAS bf16x8*)(lds + PG8_SA(b, h) + aoff + m * 2048 + k * 1024); } while (0)
; #define PG8_LDB(dst, b, h) do { _Pragma("unroll") for (int n = 0; n < 2; ++n) _Pragma("unroll") for (int k = 0; k < 2; ++k) dst[n][k] = *(const LAS bf16x8*)(lds + PG8_SB(b, h) + boff + n * 2048 + k * 1024); } while (0)
; #define PG8_MMA(ai, bj, At, Bt) do { __builtin_amdgcn_s_setprio(1); _Pragma("unroll") for (int m = 0; m < 4; ++m) _Pragma("unroll") for (int n = 0; n < 2; ++n) _Pragma("unroll") for (int k = 0; k < 2; ++k) \
;         acc[ai][bj][m][n] = __builtin_amdgcn_mfma_f32_16x16x32_bf16(Bt[n][k], At[m][k], acc[ai][bj][m][n], 0, 0, 0); __builtin_amdgcn_s_setprio(0); } while (0)
; #define PG8_WAIT_V(n) asm volatile("s_waitcnt vmcnt(" #n ")" ::: "memory")
; #define PG8_WAIT_L(n) asm volatile("s_waitcnt lgkmcnt(" #n ")" ::: "memory")
; #define PG8_BAR __builtin_amdgcn_s_barrier()
; #define PG8_SCHED __builtin_amdgcn_sched_barrier(0)
; template <class Sched, class Epi>
; __device__ __forceinline__ void gemm_run(LAS unsigned char* lds, const Sched& S, const Epi& E) {
;     ...
;             PG8_LDB(B0, 1, 0); PG8_LDB(B1, 1, 1); PG8_SCHED; PG8_LDA(At, 1, 0); PG8_STAGE(PG8_SA(0, 1), a2 + (size_t)HALF * la2, RA, la2);
;             PG8_WAIT_V(8); PG8_WAIT_L(0); PG8_BAR; PG8_MMA(0, 0, At, B0); PG8_MMA(0, 1, At, B1); PG8_BAR; PG8_SCHED;
	s_add_i32 s0, 0, 0x18000
	s_add_i32 s44, 0, 0x1c000
	v_add_u32_e32 v162, s0, v176
	v_add_u32_e32 v185, s44, v176
	ds_read_b128 v[134:137], v162
	ds_read_b128 v[138:141], v162 offset:1024
	ds_read_b128 v[142:145], v162 offset:2048
	ds_read_b128 v[162:165], v162 offset:3072
	ds_read_b128 v[166:169], v185
	ds_read_b128 v[186:189], v185 offset:1024
	ds_read_b128 v[190:193], v185 offset:2048
	ds_read_b128 v[194:197], v185 offset:3072
	s_mov_b32 s69, s1
	s_lshl_b64 s[42:43], s[68:69], 7
	s_add_u32 s42, s66, s42
	s_addc_u32 s43, s67, s43
	v_lshl_add_u64 v[242:243], s[42:43], 0, v[148:149]
	s_mov_b32 m0, s85
	v_lshl_add_u64 v[242:243], v[242:243], 0, v[146:147]
	v_lshl_add_u64 v[238:239], s[42:43], 0, v[238:239]
	ds_read_b128 v[198:201], v181 offset:32768
	ds_read_b128 v[202:205], v181 offset:33792
	ds_read_b128 v[206:209], v181 offset:34816
	ds_read_b128 v[210:213], v181 offset:35840
	ds_read_b128 v[214:217], v181 offset:36864
	ds_read_b128 v[218:221], v181 offset:37888
	ds_read_b128 v[222:225], v181 offset:38912
	ds_read_b128 v[226:229], v181 offset:39936
	global_load_lds_dwordx4 v[242:243], off
	v_lshl_add_u64 v[238:239], v[238:239], 0, v[146:147]
	s_mov_b32 m0, s90
	s_nop 0
	global_load_lds_dwordx4 v[238:239], off
	s_waitcnt vmcnt(8)
	s_waitcnt lgkmcnt(0)
	s_barrier
	s_setprio 1
	s_waitcnt lgkmcnt(0)
	v_mfma_f32_16x16x32_bf16 v[126:129], v[134:137], v[198:201], v[126:129]
	v_mfma_f32_16x16x32_bf16 v[122:125], v[142:145], v[198:201], v[122:125]
	v_mfma_f32_16x16x32_bf16 v[110:113], v[134:137], v[206:209], v[110:113]
	v_mfma_f32_16x16x32_bf16 v[106:109], v[142:145], v[206:209], v[106:109]
	v_mfma_f32_16x16x32_bf16 v[94:97], v[134:137], v[214:217], v[94:97]
	v_mfma_f32_16x16x32_bf16 v[90:93], v[142:145], v[214:217], v[90:93]
	v_mfma_f32_16x16x32_bf16 v[78:81], v[134:137], v[222:225], v[78:81]
	v_mfma_f32_16x16x32_bf16 v[74:77], v[142:145], v[222:225], v[74:77]
	v_mfma_f32_16x16x32_bf16 v[126:129], v[138:141], v[202:205], v[126:129]
	v_mfma_f32_16x16x32_bf16 v[122:125], v[162:165], v[202:205], v[122:125]
	v_mfma_f32_16x16x32_bf16 v[110:113], v[138:141], v[210:213], v[110:113]
	v_mfma_f32_16x16x32_bf16 v[106:109], v[162:165], v[210:213], v[106:109]
	v_mfma_f32_16x16x32_bf16 v[94:97], v[138:141], v[218:221], v[94:97]
	v_mfma_f32_16x16x32_bf16 v[90:93], v[162:165], v[218:221], v[90:93]
	v_mfma_f32_16x16x32_bf16 v[78:81], v[138:141], v[226:229], v[78:81]
	v_mfma_f32_16x16x32_bf16 v[74:77], v[162:165], v[226:229], v[74:77]
	v_mfma_f32_16x16x32_bf16 v[118:121], v[166:169], v[198:201], v[118:121]
	v_mfma_f32_16x16x32_bf16 v[114:117], v[190:193], v[198:201], v[114:117]
	v_mfma_f32_16x16x32_bf16 v[102:105], v[166:169], v[206:209], v[102:105]
	v_mfma_f32_16x16x32_bf16 v[98:101], v[190:193], v[206:209], v[98:101]
	v_mfma_f32_16x16x32_bf16 v[86:89], v[166:169], v[214:217], v[86:89]
	v_mfma_f32_16x16x32_bf16 v[82:85], v[190:193], v[214:217], v[82:85]
	v_mfma_f32_16x16x32_bf16 v[70:73], v[166:169], v[222:225], v[70:73]
	v_mfma_f32_16x16x32_bf16 v[66:69], v[190:193], v[222:225], v[66:69]
	v_mfma_f32_16x16x32_bf16 v[118:121], v[186:189], v[202:205], v[118:121]
	v_mfma_f32_16x16x32_bf16 v[114:117], v[194:197], v[202:205], v[114:117]
	v_mfma_f32_16x16x32_bf16 v[102:105], v[186:189], v[210:213], v[102:105]
	v_mfma_f32_16x16x32_bf16 v[98:101], v[194:197], v[210:213], v[98:101]
	v_mfma_f32_16x16x32_bf16 v[86:89], v[186:189], v[218:221], v[86:89]
	v_mfma_f32_16x16x32_bf16 v[82:85], v[194:197], v[218:221], v[82:85]
	v_mfma_f32_16x16x32_bf16 v[70:73], v[186:189], v[226:229], v[70:73]
	v_mfma_f32_16x16x32_bf16 v[66:69], v[194:197], v[226:229], v[66:69]
	s_setprio 0
	s_barrier
; #define PG8_STAGE(bufoff, gbase, RR, ld) do { _Pragma("unroll") for (int _i = 0; _i < 2; ++_i) \
;         __builtin_amdgcn_global_load_lds((const unsigned*)((const char*)(gbase) + (RR)[_i] * (ld) + C2[_i]), (LAS unsigned*)(lds + (bufoff) + ldsw + _i * 8192), 16, 0, 0); } while (0)
; #define PG8_LDA(dst, b, h) do { _Pragma("unroll") for (int m = 0; m < 4; ++m) _Pragma("unroll") for (int k = 0; k < 2; ++k) dst[m][k] = *(const LAS bf16x8*)(lds + PG8_SA(b, h) + aoff + m * 2048 + k * 1024); } while (0)
; #define PG8_MMA(ai, bj, At, Bt) do { __builtin_amdgcn_s_setprio(1); _Pragma("unroll") for (int m = 0; m < 4; ++m) _Pragma("unroll") for (int n = 0; n < 2; ++n) _Pragma("unroll") for (int k = 0; k < 2; ++k) \
;         acc[ai][bj][m][n] = __builtin_amdgcn_mfma_f32_16x16x32_bf16(Bt[n][k], At[m][k], acc[ai][bj][m][n], 0, 0, 0); __builtin_amdgcn_s_setprio(0); } while (0)
; #define PG8_WAIT_V(n) asm volatile("s_waitcnt vmcnt(" #n ")" ::: "memory")
; #define PG8_WAIT_L(n) asm volatile("s_waitcnt lgkmcnt(" #n ")" ::: "memory")
; #define PG8_BAR __builtin_amdgcn_s_barrier()
; #define PG8_SCHED __builtin_amdgcn_sched_barrier(0)
; template <class Sched, class Epi>
; __device__ __forceinline__ void gemm_run(LAS unsigned char* lds, const Sched& S, const Epi& E) {
;     ...
;             PG8_LDA(At, 1, 1); PG8_STAGE(PG8_SB(1, 0), b3, RB, lb2); PG8_STAGE(PG8_SB(1, 1), b3 + (size_t)HALF * lb2, RB, lb2); PG8_STAGE(PG8_SA(1, 0), a3, RA, la2);
;             PG8_WAIT_V(8); PG8_WAIT_L(0); PG8_BAR; PG8_MMA(1, 0, At, B0); PG8_MMA(1, 1, At, B1); PG8_BAR; PG8_SCHED;
;         }
;         if (wr == 0) PG8_BAR;
	s_add_i32 s0, s0, s81
	v_lshl_add_u64 v[170:171], v[170:171], 0, s[8:9]
	s_mov_b32 m0, s0
	ds_read_b128 v[198:201], v181 offset:49152
	ds_read_b128 v[202:205], v181 offset:50176
	ds_read_b128 v[206:209], v181 offset:51200
	ds_read_b128 v[210:213], v181 offset:52224
	ds_read_b128 v[214:217], v181 offset:53248
	ds_read_b128 v[218:221], v181 offset:54272
	ds_read_b128 v[222:225], v181 offset:55296
	ds_read_b128 v[226:229], v181 offset:56320
	global_load_lds_dwordx4 v[170:171], off
	v_lshl_add_u64 v[170:171], v[232:233], 0, s[8:9]
	s_add_i32 m0, s0, 0x2000
	s_add_i32 s0, s44, s81
	global_load_lds_dwordx4 v[170:171], off
	v_lshl_add_u64 v[170:171], v[234:235], 0, s[8:9]
	s_mov_b32 m0, s0
	s_nop 0
	global_load_lds_dwordx4 v[170:171], off
	v_lshl_add_u64 v[170:171], v[230:231], 0, s[8:9]
	s_add_i32 m0, s0, 0x2000
	s_nop 0
	global_load_lds_dwordx4 v[170:171], off
	v_lshl_add_u64 v[170:171], v[236:237], 0, s[8:9]
	s_mov_b32 m0, s93
	s_nop 0
	global_load_lds_dwordx4 v[170:171], off
	v_lshl_add_u64 v[170:171], v[240:241], 0, s[8:9]
	s_mov_b32 m0, s94
	s_nop 0
	global_load_lds_dwordx4 v[170:171], off
	s_waitcnt vmcnt(8)
	s_waitcnt lgkmcnt(0)
	s_barrier
	s_setprio 1
	s_waitcnt lgkmcnt(0)
	v_mfma_f32_16x16x32_bf16 v[62:65], v[134:137], v[198:201], v[62:65]
	v_mfma_f32_16x16x32_bf16 v[58:61], v[142:145], v[198:201], v[58:61]
	v_mfma_f32_16x16x32_bf16 v[46:49], v[134:137], v[206:209], v[46:49]
	v_mfma_f32_16x16x32_bf16 v[42:45], v[142:145], v[206:209], v[42:45]
	v_mfma_f32_16x16x32_bf16 v[30:33], v[134:137], v[214:217], v[30:33]
	v_mfma_f32_16x16x32_bf16 v[26:29], v[142:145], v[214:217], v[26:29]
	v_mfma_f32_16x16x32_bf16 v[14:17], v[134:137], v[222:225], v[14:17]
	v_mfma_f32_16x16x32_bf16 v[10:13], v[142:145], v[222:225], v[10:13]
	v_mfma_f32_16x16x32_bf16 v[62:65], v[138:141], v[202:205], v[62:65]
	v_mfma_f32_16x16x32_bf16 v[58:61], v[162:165], v[202:205], v[58:61]
	v_mfma_f32_16x16x32_bf16 v[46:49], v[138:141], v[210:213], v[46:49]
	v_mfma_f32_16x16x32_bf16 v[42:45], v[162:165], v[210:213], v[42:45]
	v_mfma_f32_16x16x32_bf16 v[30:33], v[138:141], v[218:221], v[30:33]
	v_mfma_f32_16x16x32_bf16 v[26:29], v[162:165], v[218:221], v[26:29]
	v_mfma_f32_16x16x32_bf16 v[14:17], v[138:141], v[226:229], v[14:17]
	v_mfma_f32_16x16x32_bf16 v[10:13], v[162:165], v[226:229], v[10:13]
	v_mfma_f32_16x16x32_bf16 v[54:57], v[166:169], v[198:201], v[54:57]
	v_mfma_f32_16x16x32_bf16 v[50:53], v[190:193], v[198:201], v[50:53]
	v_mfma_f32_16x16x32_bf16 v[38:41], v[166:169], v[206:209], v[38:41]
	v_mfma_f32_16x16x32_bf16 v[34:37], v[190:193], v[206:209], v[34:37]
	v_mfma_f32_16x16x32_bf16 v[22:25], v[166:169], v[214:217], v[22:25]
	v_mfma_f32_16x16x32_bf16 v[18:21], v[190:193], v[214:217], v[18:21]
	v_mfma_f32_16x16x32_bf16 v[6:9], v[166:169], v[222:225], v[6:9]
	v_mfma_f32_16x16x32_bf16 v[2:5], v[190:193], v[222:225], v[2:5]
	v_mfma_f32_16x16x32_bf16 v[54:57], v[186:189], v[202:205], v[54:57]
	v_mfma_f32_16x16x32_bf16 v[50:53], v[194:197], v[202:205], v[50:53]
	v_mfma_f32_16x16x32_bf16 v[38:41], v[186:189], v[210:213], v[38:41]
	v_mfma_f32_16x16x32_bf16 v[34:37], v[194:197], v[210:213], v[34:37]
	v_mfma_f32_16x16x32_bf16 v[22:25], v[186:189], v[218:221], v[22:25]
	v_mfma_f32_16x16x32_bf16 v[18:21], v[194:197], v[218:221], v[18:21]
	v_mfma_f32_16x16x32_bf16 v[6:9], v[186:189], v[226:229], v[6:9]
	v_mfma_f32_16x16x32_bf16 v[2:5], v[194:197], v[226:229], v[2:5]
	s_setprio 0
	s_barrier
	s_add_u32 s64, s64, 0x100
	s_addc_u32 s65, s65, 0
	s_cmp_ge_i32 s41, s5
	s_mov_b32 s0, s41
	s_cbranch_scc0 .LBB0_440
	s_and_b64 vcc, exec, s[10:11]
	s_cbranch_vccz .LBB0_443
	s_barrier

; #define PG8_STAGE(bufoff, gbase, RR, ld) do { _Pragma("unroll") for (int _i = 0; _i < 2; ++_i) \
;         __builtin_amdgcn_global_load_lds((const unsigned*)((const char*)(gbase) + (RR)[_i] * (ld) + C2[_i]), (LAS unsigned*)(lds + (bufoff) + ldsw + _i * 8192), 16, 0, 0); } while (0)
; #define PG8_LDA(dst, b, h) do { _Pragma("unroll") for (int m = 0; m < 4; ++m) _Pragma("unroll") for (int k = 0; k < 2; ++k) dst[m][k] = *(const LAS bf16x8*)(lds + PG8_SA(b, h) + aoff + m * 2048 + k * 1024); } while (0)
; #define PG8_WAIT_V(n) asm volatile("s_waitcnt vmcnt(" #n ")" ::: "memory")
; #define PG8_WAIT_L(n) asm volatile("s_waitcnt lgkmcnt(" #n ")" ::: "memory")
; template <class Sched, class Epi>
; __device__ __forceinline__ void gemm_run(LAS unsigned char* lds, const Sched& S, const Epi& E) {
;     ...
;         const bool has_next = S.next(ui + 1, nxt);
;         const char* nA = has_next ? nxt.A : cA; const char* nB = has_next ? nxt.B : cB; const unsigned nlda = has_next ? nxt.lda : lda, nldb = has_next ? nxt.ldb : ldb;
;         const int nt = cur.nt;
;         for (int t = 0; t < nt; t += 2) {
;             const bool last = (t == nt - 2);
;             const char* a1 = cA + (size_t)(t + 1) * kstep;
;             const char* a2 = last ? nA : cA + (size_t)(t + 2) * kstep; const char* b2 = last ? nB : cB + (size_t)(t + 2) * kstep;
;             const unsigned la2 = last ? nlda : lda, lb2 = last ? nldb : ldb;
;             const char* a3 = a2 + kstep; const char* b3 = b2 + kstep;
;             PG8_LDB(B0, 0, 0); PG8_LDB(B1, 0, 1); PG8_SCHED; PG8_LDA(At, 0, 0); PG8_STAGE(PG8_SA(1, 1), a1 + (size_t)HALF * lda, RA, lda);
;             PG8_WAIT_V(8); PG8_WAIT_L(0); PG8_BAR; PG8_MMA(0, 0, At, B0); PG8_MMA(0, 1, At, B1); PG8_BAR; PG8_SCHED;
;             PG8_LDA(At, 0, 1); PG8_STAGE(PG8_SB(0, 0), b2, RB, lb2); PG8_STAGE(PG8_SB(0, 1), b2 + (size_t)HALF * lb2, RB, lb2); PG8_STAGE(PG8_SA(0, 0), a2, RA, la2);
;             PG8_WAIT_V(8); PG8_WAIT_L(0); PG8_BAR; PG8_MMA(1, 0, At, B0); PG8_MMA(1, 1, At, B1); PG8_BAR; PG8_SCHED;
;     ...
;         for (int a = 0; a < 2; ++a)
; #pragma unroll
;             for (int b = 0; b < 2; ++b)
; #pragma unroll
;                 for (int m = 0; m < 4; ++m)
; #pragma unroll
;                     for (int n = 0; n < 2; ++n) acc[a][b][m][n] = (f32x4){0.f, 0.f, 0.f, 0.f};
;         cur = nxt; cA = nA; cB = nB; lda = nlda; ldb = nldb; ++ui;
.LBB0_699:
	s_add_u32 s38, s20, 0x100
	v_mov_b32_e32 v2, 0
	s_addc_u32 s39, s21, 0
	v_lshl_add_u64 v[146:147], s[18:19], 0, v[142:143]
	v_lshl_add_u64 v[148:149], s[18:19], 0, v[144:145]
	s_mov_b32 s40, -2
	s_mov_b64 s[20:21], 0
	v_mov_b32_e32 v3, v2
	v_mov_b32_e32 v4, v2
	v_mov_b32_e32 v5, v2
	v_mov_b32_e32 v6, v2
	v_mov_b32_e32 v7, v2
	v_mov_b32_e32 v8, v2
	v_mov_b32_e32 v9, v2
	v_mov_b32_e32 v18, v2
	v_mov_b32_e32 v19, v2
	v_mov_b32_e32 v20, v2
	v_mov_b32_e32 v21, v2
	v_mov_b32_e32 v22, v2
	v_mov_b32_e32 v23, v2
	v_mov_b32_e32 v24, v2
	v_mov_b32_e32 v25, v2
	v_mov_b32_e32 v34, v2
	v_mov_b32_e32 v35, v2
	v_mov_b32_e32 v36, v2
	v_mov_b32_e32 v37, v2
	v_mov_b32_e32 v38, v2
	v_mov_b32_e32 v39, v2
	v_mov_b32_e32 v40, v2
	v_mov_b32_e32 v41, v2
	v_mov_b32_e32 v50, v2
	v_mov_b32_e32 v51, v2
	v_mov_b32_e32 v52, v2
	v_mov_b32_e32 v53, v2
	v_mov_b32_e32 v54, v2
	v_mov_b32_e32 v55, v2
	v_mov_b32_e32 v56, v2
	v_mov_b32_e32 v57, v2
	v_mov_b32_e32 v10, v2
	v_mov_b32_e32 v11, v2
	v_mov_b32_e32 v12, v2
	v_mov_b32_e32 v13, v2
	v_mov_b32_e32 v14, v2
	v_mov_b32_e32 v15, v2
	v_mov_b32_e32 v16, v2
	v_mov_b32_e32 v17, v2
	v_mov_b32_e32 v26, v2
	v_mov_b32_e32 v27, v2
	v_mov_b32_e32 v28, v2
	v_mov_b32_e32 v29, v2
	v_mov_b32_e32 v30, v2
	v_mov_b32_e32 v31, v2
	v_mov_b32_e32 v32, v2
	v_mov_b32_e32 v33, v2
	v_mov_b32_e32 v42, v2
	v_mov_b32_e32 v43, v2
	v_mov_b32_e32 v44, v2
	v_mov_b32_e32 v45, v2
	v_mov_b32_e32 v46, v2
	v_mov_b32_e32 v47, v2
	v_mov_b32_e32 v48, v2
	v_mov_b32_e32 v49, v2
	v_mov_b32_e32 v58, v2
	v_mov_b32_e32 v59, v2
	v_mov_b32_e32 v60, v2
	v_mov_b32_e32 v61, v2
	v_mov_b32_e32 v62, v2
	v_mov_b32_e32 v63, v2
	v_mov_b32_e32 v64, v2
	v_mov_b32_e32 v65, v2
	v_mov_b32_e32 v66, v2
	v_mov_b32_e32 v67, v2
	v_mov_b32_e32 v68, v2
	v_mov_b32_e32 v69, v2
	v_mov_b32_e32 v70, v2
	v_mov_b32_e32 v71, v2
	v_mov_b32_e32 v72, v2
	v_mov_b32_e32 v73, v2
	v_mov_b32_e32 v82, v2
	v_mov_b32_e32 v83, v2
	v_mov_b32_e32 v84, v2
	v_mov_b32_e32 v85, v2
	v_mov_b32_e32 v86, v2
	v_mov_b32_e32 v87, v2
	v_mov_b32_e32 v88, v2
	v_mov_b32_e32 v89, v2
	v_mov_b32_e32 v98, v2
	v_mov_b32_e32 v99, v2
	v_mov_b32_e32 v100, v2
	v_mov_b32_e32 v101, v2
	v_mov_b32_e32 v102, v2
	v_mov_b32_e32 v103, v2
	v_mov_b32_e32 v104, v2
	v_mov_b32_e32 v105, v2
	v_mov_b32_e32 v114, v2
	v_mov_b32_e32 v115, v2
	v_mov_b32_e32 v116, v2
	v_mov_b32_e32 v117, v2
	v_mov_b32_e32 v118, v2
	v_mov_b32_e32 v119, v2
	v_mov_b32_e32 v120, v2
	v_mov_b32_e32 v121, v2
	v_mov_b32_e32 v74, v2
	v_mov_b32_e32 v75, v2
	v_mov_b32_e32 v76, v2
	v_mov_b32_e32 v77, v2
	v_mov_b32_e32 v78, v2
	v_mov_b32_e32 v79, v2
	v_mov_b32_e32 v80, v2
	v_mov_b32_e32 v81, v2
	v_mov_b32_e32 v90, v2
	v_mov_b32_e32 v91, v2
	v_mov_b32_e32 v92, v2
	v_mov_b32_e32 v93, v2
	v_mov_b32_e32 v94, v2
	v_mov_b32_e32 v95, v2
	v_mov_b32_e32 v96, v2
	v_mov_b32_e32 v97, v2
	v_mov_b32_e32 v106, v2
	v_mov_b32_e32 v107, v2
	v_mov_b32_e32 v108, v2
	v_mov_b32_e32 v109, v2
	v_mov_b32_e32 v110, v2
	v_mov_b32_e32 v111, v2
	v_mov_b32_e32 v112, v2
	v_mov_b32_e32 v113, v2
	v_mov_b32_e32 v122, v2
	v_mov_b32_e32 v123, v2
	v_mov_b32_e32 v124, v2
	v_mov_b32_e32 v125, v2
	v_mov_b32_e32 v126, v2
	v_mov_b32_e32 v127, v2
	v_mov_b32_e32 v128, v2
	v_mov_b32_e32 v129, v2
	.p2align 6
.LBB0_700:
	ds_read_b128 v[166:169], v160
	ds_read_b128 v[170:173], v160 offset:1024
	ds_read_b128 v[174:177], v160 offset:2048
	ds_read_b128 v[178:181], v160 offset:3072
	ds_read_b128 v[182:185], v161
	ds_read_b128 v[186:189], v161 offset:1024
	ds_read_b128 v[190:193], v161 offset:2048
	ds_read_b128 v[194:197], v161 offset:3072
	s_add_u32 s22, s18, s20
	s_addc_u32 s23, s19, s21
	s_add_u32 s22, s22, 0x100
	s_addc_u32 s23, s23, 0
	s_add_u32 s41, s38, s20
	s_addc_u32 s42, s39, s21
	s_cmpk_eq_i32 s20, 0x200
	s_cselect_b32 s29, s13, s23
	s_cselect_b32 s28, s12, s22
	s_cselect_b32 s23, s15, s42
	s_cselect_b32 s22, s14, s41
	s_mov_b32 m0, s58
	v_lshl_add_u64 v[230:231], v[146:147], 0, s[20:21]
	ds_read_b128 v[198:201], v162
	ds_read_b128 v[202:205], v162 offset:1024
	ds_read_b128 v[206:209], v162 offset:2048
	ds_read_b128 v[210:213], v162 offset:3072
	ds_read_b128 v[214:217], v162 offset:4096
	ds_read_b128 v[218:221], v162 offset:5120
	ds_read_b128 v[222:225], v162 offset:6144
	ds_read_b128 v[226:229], v162 offset:7168
	global_load_lds_dwordx4 v[230:231], off
	v_lshl_add_u64 v[230:231], v[148:149], 0, s[20:21]
	s_mov_b32 m0, s59
	s_nop 0
	global_load_lds_dwordx4 v[230:231], off
	s_waitcnt vmcnt(8)
	s_waitcnt lgkmcnt(0)
	s_barrier
	s_setprio 1
	s_waitcnt lgkmcnt(0)
	v_mfma_f32_16x16x32_bf16 v[126:129], v[166:169], v[198:201], v[126:129]
	v_mfma_f32_16x16x32_bf16 v[122:125], v[174:177], v[198:201], v[122:125]
	v_mfma_f32_16x16x32_bf16 v[110:113], v[166:169], v[206:209], v[110:113]
	v_mfma_f32_16x16x32_bf16 v[106:109], v[174:177], v[206:209], v[106:109]
	v_mfma_f32_16x16x32_bf16 v[94:97], v[166:169], v[214:217], v[94:97]
	v_mfma_f32_16x16x32_bf16 v[90:93], v[174:177], v[214:217], v[90:93]
	v_mfma_f32_16x16x32_bf16 v[78:81], v[166:169], v[222:225], v[78:81]
	v_mfma_f32_16x16x32_bf16 v[74:77], v[174:177], v[222:225], v[74:77]
	v_mfma_f32_16x16x32_bf16 v[126:129], v[170:173], v[202:205], v[126:129]
	v_mfma_f32_16x16x32_bf16 v[122:125], v[178:181], v[202:205], v[122:125]
	v_mfma_f32_16x16x32_bf16 v[110:113], v[170:173], v[210:213], v[110:113]
	v_mfma_f32_16x16x32_bf16 v[106:109], v[178:181], v[210:213], v[106:109]
	v_mfma_f32_16x16x32_bf16 v[94:97], v[170:173], v[218:221], v[94:97]
	v_mfma_f32_16x16x32_bf16 v[90:93], v[178:181], v[218:221], v[90:93]
	v_mfma_f32_16x16x32_bf16 v[78:81], v[170:173], v[226:229], v[78:81]
	v_mfma_f32_16x16x32_bf16 v[74:77], v[178:181], v[226:229], v[74:77]
	v_mfma_f32_16x16x32_bf16 v[118:121], v[182:185], v[198:201], v[118:121]
	v_mfma_f32_16x16x32_bf16 v[114:117], v[190:193], v[198:201], v[114:117]
	v_mfma_f32_16x16x32_bf16 v[102:105], v[182:185], v[206:209], v[102:105]
	v_mfma_f32_16x16x32_bf16 v[98:101], v[190:193], v[206:209], v[98:101]
	v_mfma_f32_16x16x32_bf16 v[86:89], v[182:185], v[214:217], v[86:89]
	v_mfma_f32_16x16x32_bf16 v[82:85], v[190:193], v[214:217], v[82:85]
	v_mfma_f32_16x16x32_bf16 v[70:73], v[182:185], v[222:225], v[70:73]
	v_mfma_f32_16x16x32_bf16 v[66:69], v[190:193], v[222:225], v[66:69]
	v_mfma_f32_16x16x32_bf16 v[118:121], v[186:189], v[202:205], v[118:121]
	v_mfma_f32_16x16x32_bf16 v[114:117], v[194:197], v[202:205], v[114:117]
	v_mfma_f32_16x16x32_bf16 v[102:105], v[186:189], v[210:213], v[102:105]
	v_mfma_f32_16x16x32_bf16 v[98:101], v[194:197], v[210:213], v[98:101]
	v_mfma_f32_16x16x32_bf16 v[86:89], v[186:189], v[218:221], v[86:89]
	v_mfma_f32_16x16x32_bf16 v[82:85], v[194:197], v[218:221], v[82:85]
	v_mfma_f32_16x16x32_bf16 v[70:73], v[186:189], v[226:229], v[70:73]
	v_mfma_f32_16x16x32_bf16 v[66:69], v[194:197], v[226:229], v[66:69]
	s_setprio 0
	s_barrier
; #define PG8_STAGE(bufoff, gbase, RR, ld) do { _Pragma("unroll") for (int _i = 0; _i < 2; ++_i) \
;         __builtin_amdgcn_global_load_lds((const unsigned*)((const char*)(gbase) + (RR)[_i] * (ld) + C2[_i]), (LAS unsigned*)(lds + (bufoff) + ldsw + _i * 8192), 16, 0, 0); } while (0)
; #define PG8_LDA(dst, b, h) do { _Pragma("unroll") for (int m = 0; m < 4; ++m) _Pragma("unroll") for (int k = 0; k < 2; ++k) dst[m][k] = *(const LAS bf16x8*)(lds + PG8_SA(b, h) + aoff + m * 2048 + k * 1024); } while (0)
; #define PG8_LDB(dst, b, h) do { _Pragma("unroll") for (int n = 0; n < 2; ++n) _Pragma("unroll") for (int k = 0; k < 2; ++k) dst[n][k] = *(const LAS bf16x8*)(lds + PG8_SB(b, h) + boff + n * 2048 + k * 1024); } while (0)
; #define PG8_MMA(ai, bj, At, Bt) do { __builtin_amdgcn_s_setprio(1); _Pragma("unroll") for (int m = 0; m < 4; ++m) _Pragma("unroll") for (int n = 0; n < 2; ++n) _Pragma("unroll") for (int k = 0; k < 2; ++k) \
;         acc[ai][bj][m][n] = __builtin_amdgcn_mfma_f32_16x16x32_bf16(Bt[n][k], At[m][k], acc[ai][bj][m][n], 0, 0, 0); __builtin_amdgcn_s_setprio(0); } while (0)
; #define PG8_WAIT_V(n) asm volatile("s_waitcnt vmcnt(" #n ")" ::: "memory")
; #define PG8_WAIT_L(n) asm volatile("s_waitcnt lgkmcnt(" #n ")" ::: "memory")
; #define PG8_BAR __builtin_amdgcn_s_barrier()
; #define PG8_SCHED __builtin_amdgcn_sched_barrier(0)
; template <class Sched, class Epi>
; __device__ __forceinline__ void gemm_run(LAS unsigned char* lds, const Sched& S, const Epi& E) {
;     ...
;             PG8_LDA(At, 0, 1); PG8_STAGE(PG8_SB(0, 0), b2, RB, lb2); PG8_STAGE(PG8_SB(0, 1), b2 + (size_t)HALF * lb2, RB, lb2); PG8_STAGE(PG8_SA(0, 0), a2, RA, la2);
;             PG8_WAIT_V(8); PG8_WAIT_L(0); PG8_BAR; PG8_MMA(1, 0, At, B0); PG8_MMA(1, 1, At, B1); PG8_BAR; PG8_SCHED;
;             PG8_LDB(B0, 1, 0); PG8_LDB(B1, 1, 1); PG8_SCHED; PG8_LDA(At, 1, 0); PG8_STAGE(PG8_SA(0, 1), a2 + (size_t)HALF * la2, RA, la2);
;             PG8_WAIT_V(8); PG8_WAIT_L(0); PG8_BAR; PG8_MMA(0, 0, At, B0); PG8_MMA(0, 1, At, B1); PG8_BAR; PG8_SCHED;
	v_lshl_add_u64 v[230:231], s[22:23], 0, v[132:133]
	s_add_u32 s42, s22, 0x18000
	s_mov_b32 m0, s60
	v_lshl_add_u64 v[230:231], v[230:231], 0, v[130:131]
	v_lshl_add_u64 v[232:233], s[22:23], 0, v[136:137]
	s_addc_u32 s43, s23, 0
	ds_read_b128 v[198:201], v162 offset:16384
	ds_read_b128 v[202:205], v162 offset:17408
	ds_read_b128 v[206:209], v162 offset:18432
	ds_read_b128 v[210:213], v162 offset:19456
	ds_read_b128 v[214:217], v162 offset:20480
	ds_read_b128 v[218:221], v162 offset:21504
	ds_read_b128 v[222:225], v162 offset:22528
	ds_read_b128 v[226:229], v162 offset:23552
	global_load_lds_dwordx4 v[230:231], off
	v_lshl_add_u64 v[232:233], v[232:233], 0, v[130:131]
	s_mov_b32 m0, s61
	v_lshl_add_u64 v[234:235], s[42:43], 0, v[132:133]
	global_load_lds_dwordx4 v[232:233], off
	v_lshl_add_u64 v[234:235], v[234:235], 0, v[130:131]
	s_mov_b32 m0, s62
	v_lshl_add_u64 v[236:237], s[28:29], 0, v[140:141]
	global_load_lds_dwordx4 v[234:235], off
	v_lshl_add_u64 v[234:235], s[42:43], 0, v[136:137]
	v_lshl_add_u64 v[234:235], v[234:235], 0, v[130:131]
	s_mov_b32 m0, s63
	v_lshl_add_u64 v[236:237], v[236:237], 0, v[130:131]
	global_load_lds_dwordx4 v[234:235], off
	v_lshl_add_u64 v[234:235], s[28:29], 0, v[138:139]
	v_lshl_add_u64 v[234:235], v[234:235], 0, v[130:131]
	s_mov_b32 m0, s35
	s_nop 0
	global_load_lds_dwordx4 v[234:235], off
	s_mov_b32 m0, s36
	s_nop 0
	global_load_lds_dwordx4 v[236:237], off
	s_waitcnt vmcnt(8)
	s_waitcnt lgkmcnt(0)
	s_barrier
	s_setprio 1
	s_waitcnt lgkmcnt(0)
	v_mfma_f32_16x16x32_bf16 v[62:65], v[166:169], v[198:201], v[62:65]
	v_mfma_f32_16x16x32_bf16 v[58:61], v[174:177], v[198:201], v[58:61]
	v_mfma_f32_16x16x32_bf16 v[46:49], v[166:169], v[206:209], v[46:49]
	v_mfma_f32_16x16x32_bf16 v[42:45], v[174:177], v[206:209], v[42:45]
	v_mfma_f32_16x16x32_bf16 v[30:33], v[166:169], v[214:217], v[30:33]
	v_mfma_f32_16x16x32_bf16 v[26:29], v[174:177], v[214:217], v[26:29]
	v_mfma_f32_16x16x32_bf16 v[14:17], v[166:169], v[222:225], v[14:17]
	v_mfma_f32_16x16x32_bf16 v[10:13], v[174:177], v[222:225], v[10:13]
	v_mfma_f32_16x16x32_bf16 v[62:65], v[170:173], v[202:205], v[62:65]
	v_mfma_f32_16x16x32_bf16 v[58:61], v[178:181], v[202:205], v[58:61]
	v_mfma_f32_16x16x32_bf16 v[46:49], v[170:173], v[210:213], v[46:49]
	v_mfma_f32_16x16x32_bf16 v[42:45], v[178:181], v[210:213], v[42:45]
	v_mfma_f32_16x16x32_bf16 v[30:33], v[170:173], v[218:221], v[30:33]
	v_mfma_f32_16x16x32_bf16 v[26:29], v[178:181], v[218:221], v[26:29]
	v_mfma_f32_16x16x32_bf16 v[14:17], v[170:173], v[226:229], v[14:17]
	v_mfma_f32_16x16x32_bf16 v[10:13], v[178:181], v[226:229], v[10:13]
	v_mfma_f32_16x16x32_bf16 v[54:57], v[182:185], v[198:201], v[54:57]
	v_mfma_f32_16x16x32_bf16 v[50:53], v[190:193], v[198:201], v[50:53]
	v_mfma_f32_16x16x32_bf16 v[38:41], v[182:185], v[206:209], v[38:41]
	v_mfma_f32_16x16x32_bf16 v[34:37], v[190:193], v[206:209], v[34:37]
	v_mfma_f32_16x16x32_bf16 v[22:25], v[182:185], v[214:217], v[22:25]
	v_mfma_f32_16x16x32_bf16 v[18:21], v[190:193], v[214:217], v[18:21]
	v_mfma_f32_16x16x32_bf16 v[6:9], v[182:185], v[222:225], v[6:9]
	v_mfma_f32_16x16x32_bf16 v[2:5], v[190:193], v[222:225], v[2:5]
	v_mfma_f32_16x16x32_bf16 v[54:57], v[186:189], v[202:205], v[54:57]
	v_mfma_f32_16x16x32_bf16 v[50:53], v[194:197], v[202:205], v[50:53]
	v_mfma_f32_16x16x32_bf16 v[38:41], v[186:189], v[210:213], v[38:41]
	v_mfma_f32_16x16x32_bf16 v[34:37], v[194:197], v[210:213], v[34:37]
	v_mfma_f32_16x16x32_bf16 v[22:25], v[186:189], v[218:221], v[22:25]
	v_mfma_f32_16x16x32_bf16 v[18:21], v[194:197], v[218:221], v[18:21]
	v_mfma_f32_16x16x32_bf16 v[6:9], v[186:189], v[226:229], v[6:9]
	v_mfma_f32_16x16x32_bf16 v[2:5], v[194:197], v[226:229], v[2:5]
	s_setprio 0
	s_barrier
	ds_read_b128 v[166:169], v163
	ds_read_b128 v[170:173], v163 offset:1024
	ds_read_b128 v[174:177], v163 offset:2048
	ds_read_b128 v[178:181], v163 offset:3072
	ds_read_b128 v[182:185], v164
	ds_read_b128 v[186:189], v164 offset:1024
	ds_read_b128 v[190:193], v164 offset:2048
	ds_read_b128 v[194:197], v164 offset:3072
	s_add_u32 s28, s28, 0x18000
	s_addc_u32 s29, s29, 0
	v_lshl_add_u64 v[238:239], s[28:29], 0, v[138:139]
	s_mov_b32 m0, s37
	v_lshl_add_u64 v[238:239], v[238:239], 0, v[130:131]
	ds_read_b128 v[198:201], v162 offset:32768
	ds_read_b128 v[202:205], v162 offset:33792
	ds_read_b128 v[206:209], v162 offset:34816
	ds_read_b128 v[210:213], v162 offset:35840
	ds_read_b128 v[214:217], v162 offset:36864
	ds_read_b128 v[218:221], v162 offset:37888
	ds_read_b128 v[222:225], v162 offset:38912
	ds_read_b128 v[226:229], v162 offset:39936
	global_load_lds_dwordx4 v[238:239], off
	v_lshl_add_u64 v[238:239], s[28:29], 0, v[140:141]
	v_lshl_add_u64 v[238:239], v[238:239], 0, v[130:131]
	s_mov_b32 m0, s54
	s_nop 0
	global_load_lds_dwordx4 v[238:239], off
	s_waitcnt vmcnt(8)
	s_waitcnt lgkmcnt(0)
	s_barrier
; #define PG8_STAGE(bufoff, gbase, RR, ld) do { _Pragma("unroll") for (int _i = 0; _i < 2; ++_i) \
;         __builtin_amdgcn_global_load_lds((const unsigned*)((const char*)(gbase) + (RR)[_i] * (ld) + C2[_i]), (LAS unsigned*)(lds + (bufoff) + ldsw + _i * 8192), 16, 0, 0); } while (0)
; #define PG8_LDA(dst, b, h) do { _Pragma("unroll") for (int m = 0; m < 4; ++m) _Pragma("unroll") for (int k = 0; k < 2; ++k) dst[m][k] = *(const LAS bf16x8*)(lds + PG8_SA(b, h) + aoff + m * 2048 + k * 1024); } while (0)
; #define PG8_MMA(ai, bj, At, Bt) do { __builtin_amdgcn_s_setprio(1); _Pragma("unroll") for (int m = 0; m < 4; ++m) _Pragma("unroll") for (int n = 0; n < 2; ++n) _Pragma("unroll") for (int k = 0; k < 2; ++k) \
;         acc[ai][bj][m][n] = __builtin_amdgcn_mfma_f32_16x16x32_bf16(Bt[n][k], At[m][k], acc[ai][bj][m][n], 0, 0, 0); __builtin_amdgcn_s_setprio(0); } while (0)
; #define PG8_WAIT_V(n) asm volatile("s_waitcnt vmcnt(" #n ")" ::: "memory")
; #define PG8_WAIT_L(n) asm volatile("s_waitcnt lgkmcnt(" #n ")" ::: "memory")
; #define PG8_BAR __builtin_amdgcn_s_barrier()
; #define PG8_SCHED __builtin_amdgcn_sched_barrier(0)
; template <class Sched, class Epi>
; __device__ __forceinline__ void gemm_run(LAS unsigned char* lds, const Sched& S, const Epi& E) {
;     ...
;             PG8_WAIT_V(8); PG8_WAIT_L(0); PG8_BAR; PG8_MMA(0, 0, At, B0); PG8_MMA(0, 1, At, B1); PG8_BAR; PG8_SCHED;
;             PG8_LDA(At, 1, 1); PG8_STAGE(PG8_SB(1, 0), b3, RB, lb2); PG8_STAGE(PG8_SB(1, 1), b3 + (size_t)HALF * lb2, RB, lb2); PG8_STAGE(PG8_SA(1, 0), a3, RA, la2);
;             PG8_WAIT_V(8); PG8_WAIT_L(0); PG8_BAR; PG8_MMA(1, 0, At, B0); PG8_MMA(1, 1, At, B1); PG8_BAR; PG8_SCHED;
;         }
;         if (wr == 0) PG8_BAR;
	s_setprio 1
	s_waitcnt lgkmcnt(0)
	v_mfma_f32_16x16x32_bf16 v[126:129], v[166:169], v[198:201], v[126:129]
	v_mfma_f32_16x16x32_bf16 v[122:125], v[174:177], v[198:201], v[122:125]
	v_mfma_f32_16x16x32_bf16 v[110:113], v[166:169], v[206:209], v[110:113]
	v_mfma_f32_16x16x32_bf16 v[106:109], v[174:177], v[206:209], v[106:109]
	v_mfma_f32_16x16x32_bf16 v[94:97], v[166:169], v[214:217], v[94:97]
	v_mfma_f32_16x16x32_bf16 v[90:93], v[174:177], v[214:217], v[90:93]
	v_mfma_f32_16x16x32_bf16 v[78:81], v[166:169], v[222:225], v[78:81]
	v_mfma_f32_16x16x32_bf16 v[74:77], v[174:177], v[222:225], v[74:77]
	v_mfma_f32_16x16x32_bf16 v[126:129], v[170:173], v[202:205], v[126:129]
	v_mfma_f32_16x16x32_bf16 v[122:125], v[178:181], v[202:205], v[122:125]
	v_mfma_f32_16x16x32_bf16 v[110:113], v[170:173], v[210:213], v[110:113]
	v_mfma_f32_16x16x32_bf16 v[106:109], v[178:181], v[210:213], v[106:109]
	v_mfma_f32_16x16x32_bf16 v[94:97], v[170:173], v[218:221], v[94:97]
	v_mfma_f32_16x16x32_bf16 v[90:93], v[178:181], v[218:221], v[90:93]
	v_mfma_f32_16x16x32_bf16 v[78:81], v[170:173], v[226:229], v[78:81]
	v_mfma_f32_16x16x32_bf16 v[74:77], v[178:181], v[226:229], v[74:77]
	v_mfma_f32_16x16x32_bf16 v[118:121], v[182:185], v[198:201], v[118:121]
	v_mfma_f32_16x16x32_bf16 v[114:117], v[190:193], v[198:201], v[114:117]
	v_mfma_f32_16x16x32_bf16 v[102:105], v[182:185], v[206:209], v[102:105]
	v_mfma_f32_16x16x32_bf16 v[98:101], v[190:193], v[206:209], v[98:101]
	v_mfma_f32_16x16x32_bf16 v[86:89], v[182:185], v[214:217], v[86:89]
	v_mfma_f32_16x16x32_bf16 v[82:85], v[190:193], v[214:217], v[82:85]
	v_mfma_f32_16x16x32_bf16 v[70:73], v[182:185], v[222:225], v[70:73]
	v_mfma_f32_16x16x32_bf16 v[66:69], v[190:193], v[222:225], v[66:69]
	v_mfma_f32_16x16x32_bf16 v[118:121], v[186:189], v[202:205], v[118:121]
	v_mfma_f32_16x16x32_bf16 v[114:117], v[194:197], v[202:205], v[114:117]
	v_mfma_f32_16x16x32_bf16 v[102:105], v[186:189], v[210:213], v[102:105]
	v_mfma_f32_16x16x32_bf16 v[98:101], v[194:197], v[210:213], v[98:101]
	v_mfma_f32_16x16x32_bf16 v[86:89], v[186:189], v[218:221], v[86:89]
	v_mfma_f32_16x16x32_bf16 v[82:85], v[194:197], v[218:221], v[82:85]
	v_mfma_f32_16x16x32_bf16 v[70:73], v[186:189], v[226:229], v[70:73]
	v_mfma_f32_16x16x32_bf16 v[66:69], v[194:197], v[226:229], v[66:69]
	s_setprio 0
	s_barrier
	s_mov_b32 m0, s64
	v_lshl_add_u64 v[230:231], v[230:231], 0, s[6:7]
	s_add_u32 s22, s22, 0x18080
	ds_read_b128 v[198:201], v162 offset:49152
	ds_read_b128 v[202:205], v162 offset:50176
	ds_read_b128 v[206:209], v162 offset:51200
	ds_read_b128 v[210:213], v162 offset:52224
	ds_read_b128 v[214:217], v162 offset:53248
	ds_read_b128 v[218:221], v162 offset:54272
	ds_read_b128 v[222:225], v162 offset:55296
	ds_read_b128 v[226:229], v162 offset:56320
	global_load_lds_dwordx4 v[230:231], off
	v_lshl_add_u64 v[230:231], v[232:233], 0, s[6:7]
	s_mov_b32 m0, s65
	s_addc_u32 s23, s23, 0
	global_load_lds_dwordx4 v[230:231], off
	v_lshl_add_u64 v[230:231], s[22:23], 0, v[132:133]
	v_lshl_add_u64 v[230:231], v[230:231], 0, v[130:131]
	s_mov_b32 m0, s66
	s_nop 0
	global_load_lds_dwordx4 v[230:231], off
	v_lshl_add_u64 v[230:231], s[22:23], 0, v[136:137]
	v_lshl_add_u64 v[230:231], v[230:231], 0, v[130:131]
	s_mov_b32 m0, s67
	s_nop 0
	global_load_lds_dwordx4 v[230:231], off
	v_lshl_add_u64 v[230:231], v[234:235], 0, s[6:7]
	s_mov_b32 m0, s56
	s_nop 0
	global_load_lds_dwordx4 v[230:231], off
	v_lshl_add_u64 v[230:231], v[236:237], 0, s[6:7]
	s_mov_b32 m0, s57
	s_nop 0
	global_load_lds_dwordx4 v[230:231], off
	s_waitcnt vmcnt(8)
	s_waitcnt lgkmcnt(0)
	s_barrier
	s_setprio 1
	s_waitcnt lgkmcnt(0)
	v_mfma_f32_16x16x32_bf16 v[62:65], v[166:169], v[198:201], v[62:65]
	v_mfma_f32_16x16x32_bf16 v[58:61], v[174:177], v[198:201], v[58:61]
	v_mfma_f32_16x16x32_bf16 v[46:49], v[166:169], v[206:209], v[46:49]
	v_mfma_f32_16x16x32_bf16 v[42:45], v[174:177], v[206:209], v[42:45]
	v_mfma_f32_16x16x32_bf16 v[30:33], v[166:169], v[214:217], v[30:33]
	v_mfma_f32_16x16x32_bf16 v[26:29], v[174:177], v[214:217], v[26:29]
	v_mfma_f32_16x16x32_bf16 v[14:17], v[166:169], v[222:225], v[14:17]
	v_mfma_f32_16x16x32_bf16 v[10:13], v[174:177], v[222:225], v[10:13]
	v_mfma_f32_16x16x32_bf16 v[62:65], v[170:173], v[202:205], v[62:65]
	v_mfma_f32_16x16x32_bf16 v[58:61], v[178:181], v[202:205], v[58:61]
	v_mfma_f32_16x16x32_bf16 v[46:49], v[170:173], v[210:213], v[46:49]
	v_mfma_f32_16x16x32_bf16 v[42:45], v[178:181], v[210:213], v[42:45]
	v_mfma_f32_16x16x32_bf16 v[30:33], v[170:173], v[218:221], v[30:33]
	v_mfma_f32_16x16x32_bf16 v[26:29], v[178:181], v[218:221], v[26:29]
	v_mfma_f32_16x16x32_bf16 v[14:17], v[170:173], v[226:229], v[14:17]
	v_mfma_f32_16x16x32_bf16 v[10:13], v[178:181], v[226:229], v[10:13]
	v_mfma_f32_16x16x32_bf16 v[54:57], v[182:185], v[198:201], v[54:57]
	v_mfma_f32_16x16x32_bf16 v[50:53], v[190:193], v[198:201], v[50:53]
	v_mfma_f32_16x16x32_bf16 v[38:41], v[182:185], v[206:209], v[38:41]
	v_mfma_f32_16x16x32_bf16 v[34:37], v[190:193], v[206:209], v[34:37]
	v_mfma_f32_16x16x32_bf16 v[22:25], v[182:185], v[214:217], v[22:25]
	v_mfma_f32_16x16x32_bf16 v[18:21], v[190:193], v[214:217], v[18:21]
	v_mfma_f32_16x16x32_bf16 v[6:9], v[182:185], v[222:225], v[6:9]
	v_mfma_f32_16x16x32_bf16 v[2:5], v[190:193], v[222:225], v[2:5]
	v_mfma_f32_16x16x32_bf16 v[54:57], v[186:189], v[202:205], v[54:57]
	v_mfma_f32_16x16x32_bf16 v[50:53], v[194:197], v[202:205], v[50:53]
	v_mfma_f32_16x16x32_bf16 v[38:41], v[186:189], v[210:213], v[38:41]
	v_mfma_f32_16x16x32_bf16 v[34:37], v[194:197], v[210:213], v[34:37]
	v_mfma_f32_16x16x32_bf16 v[22:25], v[186:189], v[218:221], v[22:25]
	v_mfma_f32_16x16x32_bf16 v[18:21], v[194:197], v[218:221], v[18:21]
	v_mfma_f32_16x16x32_bf16 v[6:9], v[186:189], v[226:229], v[6:9]
	v_mfma_f32_16x16x32_bf16 v[2:5], v[194:197], v[226:229], v[2:5]
	s_setprio 0
	s_barrier
	s_add_i32 s40, s40, 2
	s_add_u32 s20, s20, 0x100
	s_addc_u32 s21, s21, 0
	s_cmp_gt_u32 s40, 3
	s_cbranch_scc0 .LBB0_700
	s_and_b64 vcc, exec, s[8:9]
	s_cbranch_vccz .LBB0_703
	s_barrier

; #define PG8_STAGE(bufoff, gbase, RR, ld) do { _Pragma("unroll") for (int _i = 0; _i < 2; ++_i) \
;         __builtin_amdgcn_global_load_lds((const unsigned*)((const char*)(gbase) + (RR)[_i] * (ld) + C2[_i]), (LAS unsigned*)(lds + (bufoff) + ldsw + _i * 8192), 16, 0, 0); } while (0)
; #define PG8_LDA(dst, b, h) do { _Pragma("unroll") for (int m = 0; m < 4; ++m) _Pragma("unroll") for (int k = 0; k < 2; ++k) dst[m][k] = *(const LAS bf16x8*)(lds + PG8_SA(b, h) + aoff + m * 2048 + k * 1024); } while (0)
; #define PG8_LDB(dst, b, h) do { _Pragma("unroll") for (int n = 0; n < 2; ++n) _Pragma("unroll") for (int k = 0; k < 2; ++k) dst[n][k] = *(const LAS bf16x8*)(lds + PG8_SB(b, h) + boff + n * 2048 + k * 1024); } while (0)
; #define PG8_SCHED __builtin_amdgcn_sched_barrier(0)
; template <class Sched, class Epi>
; __device__ __forceinline__ void gemm_run(LAS unsigned char* lds, const Sched& S, const Epi& E) {
;     ...
;         const bool has_next = S.next(ui + 1, nxt);
;         const char* nA = has_next ? nxt.A : cA; const char* nB = has_next ? nxt.B : cB; const unsigned nlda = has_next ? nxt.lda : lda, nldb = has_next ? nxt.ldb : ldb;
;         const int nt = cur.nt;
;         for (int t = 0; t < nt; t += 2) {
;             const bool last = (t == nt - 2);
;             const char* a1 = cA + (size_t)(t + 1) * kstep;
;             const char* a2 = last ? nA : cA + (size_t)(t + 2) * kstep; const char* b2 = last ? nB : cB + (size_t)(t + 2) * kstep;
;             const unsigned la2 = last ? nlda : lda, lb2 = last ? nldb : ldb;
;             const char* a3 = a2 + kstep; const char* b3 = b2 + kstep;
;             PG8_LDB(B0, 0, 0); PG8_LDB(B1, 0, 1); PG8_SCHED; PG8_LDA(At, 0, 0); PG8_STAGE(PG8_SA(1, 1), a1 + (size_t)HALF * lda, RA, lda);
;     ...
;         for (int a = 0; a < 2; ++a)
; #pragma unroll
;             for (int b = 0; b < 2; ++b)
; #pragma unroll
;                 for (int m = 0; m < 4; ++m)
; #pragma unroll
;                     for (int n = 0; n < 2; ++n) acc[a][b][m][n] = (f32x4){0.f, 0.f, 0.f, 0.f};
;         cur = nxt; cA = nA; cB = nB; lda = nlda; ldb = nldb; ++ui;
.LBB0_805:
	s_mov_b32 s57, s7
	s_lshl_b64 s[48:49], s[56:57], 7
	v_mul_lo_u32 v148, v191, s56
	v_lshl_add_u64 v[2:3], s[54:55], 0, v[150:151]
	v_lshl_add_u64 v[4:5], s[48:49], 0, v[148:149]
	v_mul_lo_u32 v148, v192, s56
	s_add_i32 s44, s81, -2
	v_lshl_add_u64 v[130:131], v[2:3], 0, v[4:5]
	v_lshl_add_u64 v[4:5], s[48:49], 0, v[148:149]
	s_add_u32 s45, s58, 0x100
	v_lshl_add_u64 v[132:133], v[2:3], 0, v[4:5]
	v_mov_b32_e32 v2, 0
	s_addc_u32 s46, s59, 0
	s_mov_b32 s6, 0
	s_mov_b64 s[58:59], 0
	v_mov_b32_e32 v3, v2
	v_mov_b32_e32 v4, v2
	v_mov_b32_e32 v5, v2
	v_mov_b32_e32 v10, v2
	v_mov_b32_e32 v11, v2
	v_mov_b32_e32 v12, v2
	v_mov_b32_e32 v13, v2
	v_mov_b32_e32 v18, v2
	v_mov_b32_e32 v19, v2
	v_mov_b32_e32 v20, v2
	v_mov_b32_e32 v21, v2
	v_mov_b32_e32 v26, v2
	v_mov_b32_e32 v27, v2
	v_mov_b32_e32 v28, v2
	v_mov_b32_e32 v29, v2
	v_mov_b32_e32 v34, v2
	v_mov_b32_e32 v35, v2
	v_mov_b32_e32 v36, v2
	v_mov_b32_e32 v37, v2
	v_mov_b32_e32 v42, v2
	v_mov_b32_e32 v43, v2
	v_mov_b32_e32 v44, v2
	v_mov_b32_e32 v45, v2
	v_mov_b32_e32 v50, v2
	v_mov_b32_e32 v51, v2
	v_mov_b32_e32 v52, v2
	v_mov_b32_e32 v53, v2
	v_mov_b32_e32 v58, v2
	v_mov_b32_e32 v59, v2
	v_mov_b32_e32 v60, v2
	v_mov_b32_e32 v61, v2
	v_mov_b32_e32 v6, v2
	v_mov_b32_e32 v7, v2
	v_mov_b32_e32 v8, v2
	v_mov_b32_e32 v9, v2
	v_mov_b32_e32 v14, v2
	v_mov_b32_e32 v15, v2
	v_mov_b32_e32 v16, v2
	v_mov_b32_e32 v17, v2
	v_mov_b32_e32 v22, v2
	v_mov_b32_e32 v23, v2
	v_mov_b32_e32 v24, v2
	v_mov_b32_e32 v25, v2
	v_mov_b32_e32 v30, v2
	v_mov_b32_e32 v31, v2
	v_mov_b32_e32 v32, v2
	v_mov_b32_e32 v33, v2
	v_mov_b32_e32 v38, v2
	v_mov_b32_e32 v39, v2
	v_mov_b32_e32 v40, v2
	v_mov_b32_e32 v41, v2
	v_mov_b32_e32 v46, v2
	v_mov_b32_e32 v47, v2
	v_mov_b32_e32 v48, v2
	v_mov_b32_e32 v49, v2
	v_mov_b32_e32 v54, v2
	v_mov_b32_e32 v55, v2
	v_mov_b32_e32 v56, v2
	v_mov_b32_e32 v57, v2
	v_mov_b32_e32 v62, v2
	v_mov_b32_e32 v63, v2
	v_mov_b32_e32 v64, v2
	v_mov_b32_e32 v65, v2
	v_mov_b32_e32 v66, v2
	v_mov_b32_e32 v67, v2
	v_mov_b32_e32 v68, v2
	v_mov_b32_e32 v69, v2
	v_mov_b32_e32 v74, v2
	v_mov_b32_e32 v75, v2
	v_mov_b32_e32 v76, v2
	v_mov_b32_e32 v77, v2
	v_mov_b32_e32 v82, v2
	v_mov_b32_e32 v83, v2
	v_mov_b32_e32 v84, v2
	v_mov_b32_e32 v85, v2
	v_mov_b32_e32 v90, v2
	v_mov_b32_e32 v91, v2
	v_mov_b32_e32 v92, v2
	v_mov_b32_e32 v93, v2
	v_mov_b32_e32 v98, v2
	v_mov_b32_e32 v99, v2
	v_mov_b32_e32 v100, v2
	v_mov_b32_e32 v101, v2
	v_mov_b32_e32 v106, v2
	v_mov_b32_e32 v107, v2
	v_mov_b32_e32 v108, v2
	v_mov_b32_e32 v109, v2
	v_mov_b32_e32 v114, v2
	v_mov_b32_e32 v115, v2
	v_mov_b32_e32 v116, v2
	v_mov_b32_e32 v117, v2
	v_mov_b32_e32 v122, v2
	v_mov_b32_e32 v123, v2
	v_mov_b32_e32 v124, v2
	v_mov_b32_e32 v125, v2
	v_mov_b32_e32 v70, v2
	v_mov_b32_e32 v71, v2
	v_mov_b32_e32 v72, v2
	v_mov_b32_e32 v73, v2
	v_mov_b32_e32 v78, v2
	v_mov_b32_e32 v79, v2
	v_mov_b32_e32 v80, v2
	v_mov_b32_e32 v81, v2
	v_mov_b32_e32 v86, v2
	v_mov_b32_e32 v87, v2
	v_mov_b32_e32 v88, v2
	v_mov_b32_e32 v89, v2
	v_mov_b32_e32 v94, v2
	v_mov_b32_e32 v95, v2
	v_mov_b32_e32 v96, v2
	v_mov_b32_e32 v97, v2
	v_mov_b32_e32 v102, v2
	v_mov_b32_e32 v103, v2
	v_mov_b32_e32 v104, v2
	v_mov_b32_e32 v105, v2
	v_mov_b32_e32 v110, v2
	v_mov_b32_e32 v111, v2
	v_mov_b32_e32 v112, v2
	v_mov_b32_e32 v113, v2
	v_mov_b32_e32 v118, v2
	v_mov_b32_e32 v119, v2
	v_mov_b32_e32 v120, v2
	v_mov_b32_e32 v121, v2
	v_mov_b32_e32 v126, v2
	v_mov_b32_e32 v127, v2
	v_mov_b32_e32 v128, v2
	v_mov_b32_e32 v129, v2
	.p2align 6
.LBB0_806:
	ds_read_b128 v[134:137], v193
	ds_read_b128 v[138:141], v193 offset:1024
	ds_read_b128 v[142:145], v193 offset:2048
	ds_read_b128 v[152:155], v193 offset:3072
	ds_read_b128 v[156:159], v194
	ds_read_b128 v[160:163], v194 offset:1024
	ds_read_b128 v[164:167], v194 offset:2048
	ds_read_b128 v[168:171], v194 offset:3072
	s_add_i32 s47, s6, 2
	s_add_u32 s48, s54, s58
	s_addc_u32 s49, s55, s59
	s_add_u32 s48, s48, 0x100
	s_addc_u32 s49, s49, 0
	s_add_u32 s50, s45, s58
	s_addc_u32 s51, s46, s59
	s_cmp_eq_u32 s44, s6
	s_cselect_b32 s6, s39, s82
	s_cselect_b32 s61, s31, s49
	s_cselect_b32 s60, s30, s48
	s_cselect_b32 s62, s80, s56
	s_cselect_b32 s49, s41, s51
	s_cselect_b32 s48, s40, s50
	v_lshl_add_u64 v[216:217], v[130:131], 0, s[58:59]
	s_add_i32 m0, s43, 0xc000
	ds_read_b128 v[172:175], v195
	ds_read_b128 v[176:179], v195 offset:1024
	ds_read_b128 v[180:183], v195 offset:2048
	ds_read_b128 v[196:199], v195 offset:3072
	ds_read_b128 v[200:203], v195 offset:4096
	ds_read_b128 v[204:207], v195 offset:5120
	ds_read_b128 v[208:211], v195 offset:6144
	ds_read_b128 v[212:215], v195 offset:7168
	global_load_lds_dwordx4 v[216:217], off
	v_lshl_add_u64 v[216:217], v[132:133], 0, s[58:59]
	s_add_i32 m0, s43, 0xe000
	s_nop 0
	global_load_lds_dwordx4 v[216:217], off
	s_waitcnt vmcnt(8)
	s_waitcnt lgkmcnt(0)
	s_barrier
; #define PG8_STAGE(bufoff, gbase, RR, ld) do { _Pragma("unroll") for (int _i = 0; _i < 2; ++_i) \
;         __builtin_amdgcn_global_load_lds((const unsigned*)((const char*)(gbase) + (RR)[_i] * (ld) + C2[_i]), (LAS unsigned*)(lds + (bufoff) + ldsw + _i * 8192), 16, 0, 0); } while (0)
; #define PG8_LDA(dst, b, h) do { _Pragma("unroll") for (int m = 0; m < 4; ++m) _Pragma("unroll") for (int k = 0; k < 2; ++k) dst[m][k] = *(const LAS bf16x8*)(lds + PG8_SA(b, h) + aoff + m * 2048 + k * 1024); } while (0)
; #define PG8_MMA(ai, bj, At, Bt) do { __builtin_amdgcn_s_setprio(1); _Pragma("unroll") for (int m = 0; m < 4; ++m) _Pragma("unroll") for (int n = 0; n < 2; ++n) _Pragma("unroll") for (int k = 0; k < 2; ++k) \
;         acc[ai][bj][m][n] = __builtin_amdgcn_mfma_f32_16x16x32_bf16(Bt[n][k], At[m][k], acc[ai][bj][m][n], 0, 0, 0); __builtin_amdgcn_s_setprio(0); } while (0)
; #define PG8_WAIT_V(n) asm volatile("s_waitcnt vmcnt(" #n ")" ::: "memory")
; #define PG8_WAIT_L(n) asm volatile("s_waitcnt lgkmcnt(" #n ")" ::: "memory")
; #define PG8_BAR __builtin_amdgcn_s_barrier()
; #define PG8_SCHED __builtin_amdgcn_sched_barrier(0)
; template <class Sched, class Epi>
; __device__ __forceinline__ void gemm_run(LAS unsigned char* lds, const Sched& S, const Epi& E) {
;     ...
;             PG8_WAIT_V(8); PG8_WAIT_L(0); PG8_BAR; PG8_MMA(0, 0, At, B0); PG8_MMA(0, 1, At, B1); PG8_BAR; PG8_SCHED;
;             PG8_LDA(At, 0, 1); PG8_STAGE(PG8_SB(0, 0), b2, RB, lb2); PG8_STAGE(PG8_SB(0, 1), b2 + (size_t)HALF * lb2, RB, lb2); PG8_STAGE(PG8_SA(0, 0), a2, RA, la2);
;             PG8_WAIT_V(8); PG8_WAIT_L(0); PG8_BAR; PG8_MMA(1, 0, At, B0); PG8_MMA(1, 1, At, B1); PG8_BAR; PG8_SCHED;
	s_setprio 1
	s_waitcnt lgkmcnt(0)
	v_mfma_f32_16x16x32_bf16 v[126:129], v[134:137], v[172:175], v[126:129]
	v_mfma_f32_16x16x32_bf16 v[118:121], v[142:145], v[172:175], v[118:121]
	v_mfma_f32_16x16x32_bf16 v[110:113], v[134:137], v[180:183], v[110:113]
	v_mfma_f32_16x16x32_bf16 v[102:105], v[142:145], v[180:183], v[102:105]
	v_mfma_f32_16x16x32_bf16 v[94:97], v[134:137], v[200:203], v[94:97]
	v_mfma_f32_16x16x32_bf16 v[86:89], v[142:145], v[200:203], v[86:89]
	v_mfma_f32_16x16x32_bf16 v[78:81], v[134:137], v[208:211], v[78:81]
	v_mfma_f32_16x16x32_bf16 v[70:73], v[142:145], v[208:211], v[70:73]
	v_mfma_f32_16x16x32_bf16 v[126:129], v[138:141], v[176:179], v[126:129]
	v_mfma_f32_16x16x32_bf16 v[118:121], v[152:155], v[176:179], v[118:121]
	v_mfma_f32_16x16x32_bf16 v[110:113], v[138:141], v[196:199], v[110:113]
	v_mfma_f32_16x16x32_bf16 v[102:105], v[152:155], v[196:199], v[102:105]
	v_mfma_f32_16x16x32_bf16 v[94:97], v[138:141], v[204:207], v[94:97]
	v_mfma_f32_16x16x32_bf16 v[86:89], v[152:155], v[204:207], v[86:89]
	v_mfma_f32_16x16x32_bf16 v[78:81], v[138:141], v[212:215], v[78:81]
	v_mfma_f32_16x16x32_bf16 v[70:73], v[152:155], v[212:215], v[70:73]
	v_mfma_f32_16x16x32_bf16 v[122:125], v[156:159], v[172:175], v[122:125]
	v_mfma_f32_16x16x32_bf16 v[114:117], v[164:167], v[172:175], v[114:117]
	v_mfma_f32_16x16x32_bf16 v[106:109], v[156:159], v[180:183], v[106:109]
	v_mfma_f32_16x16x32_bf16 v[98:101], v[164:167], v[180:183], v[98:101]
	v_mfma_f32_16x16x32_bf16 v[90:93], v[156:159], v[200:203], v[90:93]
	v_mfma_f32_16x16x32_bf16 v[82:85], v[164:167], v[200:203], v[82:85]
	v_mfma_f32_16x16x32_bf16 v[74:77], v[156:159], v[208:211], v[74:77]
	v_mfma_f32_16x16x32_bf16 v[66:69], v[164:167], v[208:211], v[66:69]
	v_mfma_f32_16x16x32_bf16 v[122:125], v[160:163], v[176:179], v[122:125]
	v_mfma_f32_16x16x32_bf16 v[114:117], v[168:171], v[176:179], v[114:117]
	v_mfma_f32_16x16x32_bf16 v[106:109], v[160:163], v[196:199], v[106:109]
	v_mfma_f32_16x16x32_bf16 v[98:101], v[168:171], v[196:199], v[98:101]
	v_mfma_f32_16x16x32_bf16 v[90:93], v[160:163], v[204:207], v[90:93]
	v_mfma_f32_16x16x32_bf16 v[82:85], v[168:171], v[204:207], v[82:85]
	v_mfma_f32_16x16x32_bf16 v[74:77], v[160:163], v[212:215], v[74:77]
	v_mfma_f32_16x16x32_bf16 v[66:69], v[168:171], v[212:215], v[66:69]
	s_setprio 0
	s_barrier
	v_mul_lo_u32 v148, s6, v185
	v_lshl_add_u64 v[216:217], s[48:49], 0, v[148:149]
	s_add_i32 s50, s74, s3
	v_lshl_add_u64 v[216:217], v[216:217], 0, v[146:147]
	s_mov_b32 m0, s50
	ds_read_b128 v[172:175], v195 offset:16384
	ds_read_b128 v[176:179], v195 offset:17408
	ds_read_b128 v[180:183], v195 offset:18432
	ds_read_b128 v[196:199], v195 offset:19456
	ds_read_b128 v[200:203], v195 offset:20480
	ds_read_b128 v[204:207], v195 offset:21504
	ds_read_b128 v[208:211], v195 offset:22528
	ds_read_b128 v[212:215], v195 offset:23552
	global_load_lds_dwordx4 v[216:217], off
	v_mul_lo_u32 v218, s6, v187
	v_mov_b32_e32 v219, v149
	s_add_i32 m0, s50, 0x2000
	s_lshl_b64 s[50:51], s[6:7], 7
	v_lshl_add_u64 v[220:221], s[48:49], 0, v[218:219]
	s_add_u32 s48, s48, s50
	s_addc_u32 s49, s49, s51
	v_lshl_add_u64 v[220:221], v[220:221], 0, v[146:147]
	v_lshl_add_u64 v[222:223], s[48:49], 0, v[148:149]
	s_add_i32 s6, s75, s3
	global_load_lds_dwordx4 v[220:221], off
	v_lshl_add_u64 v[222:223], v[222:223], 0, v[146:147]
	s_mov_b32 m0, s6
	v_lshl_add_u64 v[218:219], s[48:49], 0, v[218:219]
	v_mul_lo_u32 v148, s62, v184
	global_load_lds_dwordx4 v[222:223], off
	v_lshl_add_u64 v[218:219], v[218:219], 0, v[146:147]
	s_add_i32 m0, s6, 0x2000
	v_lshl_add_u64 v[224:225], s[60:61], 0, v[148:149]
	v_mul_lo_u32 v226, s62, v186
	v_mov_b32_e32 v227, v149
	global_load_lds_dwordx4 v[218:219], off
	v_lshl_add_u64 v[224:225], v[224:225], 0, v[146:147]
	s_mov_b32 m0, s43
	v_lshl_add_u64 v[228:229], s[60:61], 0, v[226:227]
	global_load_lds_dwordx4 v[224:225], off
	v_lshl_add_u64 v[228:229], v[228:229], 0, v[146:147]
	s_mov_b32 m0, s65
	s_nop 0
	global_load_lds_dwordx4 v[228:229], off
	s_waitcnt vmcnt(8)
	s_waitcnt lgkmcnt(0)
	s_barrier
	s_setprio 1
	s_waitcnt lgkmcnt(0)
	v_mfma_f32_16x16x32_bf16 v[62:65], v[134:137], v[172:175], v[62:65]
	v_mfma_f32_16x16x32_bf16 v[54:57], v[142:145], v[172:175], v[54:57]
	v_mfma_f32_16x16x32_bf16 v[46:49], v[134:137], v[180:183], v[46:49]
	v_mfma_f32_16x16x32_bf16 v[38:41], v[142:145], v[180:183], v[38:41]
	v_mfma_f32_16x16x32_bf16 v[30:33], v[134:137], v[200:203], v[30:33]
	v_mfma_f32_16x16x32_bf16 v[22:25], v[142:145], v[200:203], v[22:25]
	v_mfma_f32_16x16x32_bf16 v[14:17], v[134:137], v[208:211], v[14:17]
	v_mfma_f32_16x16x32_bf16 v[6:9], v[142:145], v[208:211], v[6:9]
	v_mfma_f32_16x16x32_bf16 v[62:65], v[138:141], v[176:179], v[62:65]
	v_mfma_f32_16x16x32_bf16 v[54:57], v[152:155], v[176:179], v[54:57]
	v_mfma_f32_16x16x32_bf16 v[46:49], v[138:141], v[196:199], v[46:49]
	v_mfma_f32_16x16x32_bf16 v[38:41], v[152:155], v[196:199], v[38:41]
	v_mfma_f32_16x16x32_bf16 v[30:33], v[138:141], v[204:207], v[30:33]
	v_mfma_f32_16x16x32_bf16 v[22:25], v[152:155], v[204:207], v[22:25]
	v_mfma_f32_16x16x32_bf16 v[14:17], v[138:141], v[212:215], v[14:17]
	v_mfma_f32_16x16x32_bf16 v[6:9], v[152:155], v[212:215], v[6:9]
	v_mfma_f32_16x16x32_bf16 v[58:61], v[156:159], v[172:175], v[58:61]
	v_mfma_f32_16x16x32_bf16 v[50:53], v[164:167], v[172:175], v[50:53]
	v_mfma_f32_16x16x32_bf16 v[42:45], v[156:159], v[180:183], v[42:45]
	v_mfma_f32_16x16x32_bf16 v[34:37], v[164:167], v[180:183], v[34:37]
	v_mfma_f32_16x16x32_bf16 v[26:29], v[156:159], v[200:203], v[26:29]
	v_mfma_f32_16x16x32_bf16 v[18:21], v[164:167], v[200:203], v[18:21]
	v_mfma_f32_16x16x32_bf16 v[10:13], v[156:159], v[208:211], v[10:13]
	v_mfma_f32_16x16x32_bf16 v[2:5], v[164:167], v[208:211], v[2:5]
	v_mfma_f32_16x16x32_bf16 v[58:61], v[160:163], v[176:179], v[58:61]
	v_mfma_f32_16x16x32_bf16 v[50:53], v[168:171], v[176:179], v[50:53]
	v_mfma_f32_16x16x32_bf16 v[42:45], v[160:163], v[196:199], v[42:45]
	v_mfma_f32_16x16x32_bf16 v[34:37], v[168:171], v[196:199], v[34:37]
	v_mfma_f32_16x16x32_bf16 v[26:29], v[160:163], v[204:207], v[26:29]
	v_mfma_f32_16x16x32_bf16 v[18:21], v[168:171], v[204:207], v[18:21]
	v_mfma_f32_16x16x32_bf16 v[10:13], v[160:163], v[212:215], v[10:13]
	v_mfma_f32_16x16x32_bf16 v[2:5], v[168:171], v[212:215], v[2:5]
	s_setprio 0
	s_barrier
; #define PG8_STAGE(bufoff, gbase, RR, ld) do { _Pragma("unroll") for (int _i = 0; _i < 2; ++_i) \
;         __builtin_amdgcn_global_load_lds((const unsigned*)((const char*)(gbase) + (RR)[_i] * (ld) + C2[_i]), (LAS unsigned*)(lds + (bufoff) + ldsw + _i * 8192), 16, 0, 0); } while (0)
; #define PG8_LDA(dst, b, h) do { _Pragma("unroll") for (int m = 0; m < 4; ++m) _Pragma("unroll") for (int k = 0; k < 2; ++k) dst[m][k] = *(const LAS bf16x8*)(lds + PG8_SA(b, h) + aoff + m * 2048 + k * 1024); } while (0)
; #define PG8_LDB(dst, b, h) do { _Pragma("unroll") for (int n = 0; n < 2; ++n) _Pragma("unroll") for (int k = 0; k < 2; ++k) dst[n][k] = *(const LAS bf16x8*)(lds + PG8_SB(b, h) + boff + n * 2048 + k * 1024); } while (0)
; #define PG8_MMA(ai, bj, At, Bt) do { __builtin_amdgcn_s_setprio(1); _Pragma("unroll") for (int m = 0; m < 4; ++m) _Pragma("unroll") for (int n = 0; n < 2; ++n) _Pragma("unroll") for (int k = 0; k < 2; ++k) \
;         acc[ai][bj][m][n] = __builtin_amdgcn_mfma_f32_16x16x32_bf16(Bt[n][k], At[m][k], acc[ai][bj][m][n], 0, 0, 0); __builtin_amdgcn_s_setprio(0); } while (0)
; #define PG8_WAIT_V(n) asm volatile("s_waitcnt vmcnt(" #n ")" ::: "memory")
; #define PG8_WAIT_L(n) asm volatile("s_waitcnt lgkmcnt(" #n ")" ::: "memory")
; #define PG8_BAR __builtin_amdgcn_s_barrier()
; #define PG8_SCHED __builtin_amdgcn_sched_barrier(0)
; template <class Sched, class Epi>
; __device__ __forceinline__ void gemm_run(LAS unsigned char* lds, const Sched& S, const Epi& E) {
;     ...
;             PG8_LDB(B0, 1, 0); PG8_LDB(B1, 1, 1); PG8_SCHED; PG8_LDA(At, 1, 0); PG8_STAGE(PG8_SA(0, 1), a2 + (size_t)HALF * la2, RA, la2);
;             PG8_WAIT_V(8); PG8_WAIT_L(0); PG8_BAR; PG8_MMA(0, 0, At, B0); PG8_MMA(0, 1, At, B1); PG8_BAR; PG8_SCHED;
	s_add_i32 s6, 0, 0x18000
	s_add_i32 s50, 0, 0x1c000
	v_add_u32_e32 v152, s6, v189
	v_add_u32_e32 v168, s50, v189
	ds_read_b128 v[134:137], v152
	ds_read_b128 v[138:141], v152 offset:1024
	ds_read_b128 v[142:145], v152 offset:2048
	ds_read_b128 v[152:155], v152 offset:3072
	ds_read_b128 v[156:159], v168
	ds_read_b128 v[160:163], v168 offset:1024
	ds_read_b128 v[164:167], v168 offset:2048
	ds_read_b128 v[168:171], v168 offset:3072
	s_mov_b32 s63, s7
	s_lshl_b64 s[48:49], s[62:63], 7
	s_add_u32 s48, s60, s48
	s_addc_u32 s49, s61, s49
	v_lshl_add_u64 v[230:231], s[48:49], 0, v[148:149]
	s_mov_b32 m0, s66
	v_lshl_add_u64 v[230:231], v[230:231], 0, v[146:147]
	v_lshl_add_u64 v[226:227], s[48:49], 0, v[226:227]
	ds_read_b128 v[172:175], v195 offset:32768
	ds_read_b128 v[176:179], v195 offset:33792
	ds_read_b128 v[180:183], v195 offset:34816
	ds_read_b128 v[196:199], v195 offset:35840
	ds_read_b128 v[200:203], v195 offset:36864
	ds_read_b128 v[204:207], v195 offset:37888
	ds_read_b128 v[208:211], v195 offset:38912
	ds_read_b128 v[212:215], v195 offset:39936
	global_load_lds_dwordx4 v[230:231], off
	v_lshl_add_u64 v[226:227], v[226:227], 0, v[146:147]
	s_mov_b32 m0, s67
	s_nop 0
	global_load_lds_dwordx4 v[226:227], off
	s_waitcnt vmcnt(8)
	s_waitcnt lgkmcnt(0)
	s_barrier
	s_setprio 1
	s_waitcnt lgkmcnt(0)
	v_mfma_f32_16x16x32_bf16 v[126:129], v[134:137], v[172:175], v[126:129]
	v_mfma_f32_16x16x32_bf16 v[118:121], v[142:145], v[172:175], v[118:121]
	v_mfma_f32_16x16x32_bf16 v[110:113], v[134:137], v[180:183], v[110:113]
	v_mfma_f32_16x16x32_bf16 v[102:105], v[142:145], v[180:183], v[102:105]
	v_mfma_f32_16x16x32_bf16 v[94:97], v[134:137], v[200:203], v[94:97]
	v_mfma_f32_16x16x32_bf16 v[86:89], v[142:145], v[200:203], v[86:89]
	v_mfma_f32_16x16x32_bf16 v[78:81], v[134:137], v[208:211], v[78:81]
	v_mfma_f32_16x16x32_bf16 v[70:73], v[142:145], v[208:211], v[70:73]
	v_mfma_f32_16x16x32_bf16 v[126:129], v[138:141], v[176:179], v[126:129]
	v_mfma_f32_16x16x32_bf16 v[118:121], v[152:155], v[176:179], v[118:121]
	v_mfma_f32_16x16x32_bf16 v[110:113], v[138:141], v[196:199], v[110:113]
	v_mfma_f32_16x16x32_bf16 v[102:105], v[152:155], v[196:199], v[102:105]
	v_mfma_f32_16x16x32_bf16 v[94:97], v[138:141], v[204:207], v[94:97]
	v_mfma_f32_16x16x32_bf16 v[86:89], v[152:155], v[204:207], v[86:89]
	v_mfma_f32_16x16x32_bf16 v[78:81], v[138:141], v[212:215], v[78:81]
	v_mfma_f32_16x16x32_bf16 v[70:73], v[152:155], v[212:215], v[70:73]
	v_mfma_f32_16x16x32_bf16 v[122:125], v[156:159], v[172:175], v[122:125]
	v_mfma_f32_16x16x32_bf16 v[114:117], v[164:167], v[172:175], v[114:117]
	v_mfma_f32_16x16x32_bf16 v[106:109], v[156:159], v[180:183], v[106:109]
	v_mfma_f32_16x16x32_bf16 v[98:101], v[164:167], v[180:183], v[98:101]
	v_mfma_f32_16x16x32_bf16 v[90:93], v[156:159], v[200:203], v[90:93]
	v_mfma_f32_16x16x32_bf16 v[82:85], v[164:167], v[200:203], v[82:85]
	v_mfma_f32_16x16x32_bf16 v[74:77], v[156:159], v[208:211], v[74:77]
	v_mfma_f32_16x16x32_bf16 v[66:69], v[164:167], v[208:211], v[66:69]
	v_mfma_f32_16x16x32_bf16 v[122:125], v[160:163], v[176:179], v[122:125]
	v_mfma_f32_16x16x32_bf16 v[114:117], v[168:171], v[176:179], v[114:117]
	v_mfma_f32_16x16x32_bf16 v[106:109], v[160:163], v[196:199], v[106:109]
	v_mfma_f32_16x16x32_bf16 v[98:101], v[168:171], v[196:199], v[98:101]
	v_mfma_f32_16x16x32_bf16 v[90:93], v[160:163], v[204:207], v[90:93]
	v_mfma_f32_16x16x32_bf16 v[82:85], v[168:171], v[204:207], v[82:85]
	v_mfma_f32_16x16x32_bf16 v[74:77], v[160:163], v[212:215], v[74:77]
	v_mfma_f32_16x16x32_bf16 v[66:69], v[168:171], v[212:215], v[66:69]
	s_setprio 0
	s_barrier
; #define PG8_STAGE(bufoff, gbase, RR, ld) do { _Pragma("unroll") for (int _i = 0; _i < 2; ++_i) \
;         __builtin_amdgcn_global_load_lds((const unsigned*)((const char*)(gbase) + (RR)[_i] * (ld) + C2[_i]), (LAS unsigned*)(lds + (bufoff) + ldsw + _i * 8192), 16, 0, 0); } while (0)
; #define PG8_LDA(dst, b, h) do { _Pragma("unroll") for (int m = 0; m < 4; ++m) _Pragma("unroll") for (int k = 0; k < 2; ++k) dst[m][k] = *(const LAS bf16x8*)(lds + PG8_SA(b, h) + aoff + m * 2048 + k * 1024); } while (0)
; #define PG8_MMA(ai, bj, At, Bt) do { __builtin_amdgcn_s_setprio(1); _Pragma("unroll") for (int m = 0; m < 4; ++m) _Pragma("unroll") for (int n = 0; n < 2; ++n) _Pragma("unroll") for (int k = 0; k < 2; ++k) \
;         acc[ai][bj][m][n] = __builtin_amdgcn_mfma_f32_16x16x32_bf16(Bt[n][k], At[m][k], acc[ai][bj][m][n], 0, 0, 0); __builtin_amdgcn_s_setprio(0); } while (0)
; #define PG8_WAIT_V(n) asm volatile("s_waitcnt vmcnt(" #n ")" ::: "memory")
; #define PG8_WAIT_L(n) asm volatile("s_waitcnt lgkmcnt(" #n ")" ::: "memory")
; #define PG8_BAR __builtin_amdgcn_s_barrier()
; #define PG8_SCHED __builtin_amdgcn_sched_barrier(0)
; template <class Sched, class Epi>
; __device__ __forceinline__ void gemm_run(LAS unsigned char* lds, const Sched& S, const Epi& E) {
;     ...
;             PG8_LDA(At, 1, 1); PG8_STAGE(PG8_SB(1, 0), b3, RB, lb2); PG8_STAGE(PG8_SB(1, 1), b3 + (size_t)HALF * lb2, RB, lb2); PG8_STAGE(PG8_SA(1, 0), a3, RA, la2);
;             PG8_WAIT_V(8); PG8_WAIT_L(0); PG8_BAR; PG8_MMA(1, 0, At, B0); PG8_MMA(1, 1, At, B1); PG8_BAR; PG8_SCHED;
;         }
;         if (wr == 0) PG8_BAR;
	s_add_i32 s6, s6, s3
	v_lshl_add_u64 v[216:217], v[216:217], 0, s[8:9]
	s_mov_b32 m0, s6
	ds_read_b128 v[172:175], v195 offset:49152
	ds_read_b128 v[176:179], v195 offset:50176
	ds_read_b128 v[180:183], v195 offset:51200
	ds_read_b128 v[196:199], v195 offset:52224
	ds_read_b128 v[200:203], v195 offset:53248
	ds_read_b128 v[204:207], v195 offset:54272
	ds_read_b128 v[208:211], v195 offset:55296
	ds_read_b128 v[212:215], v195 offset:56320
	global_load_lds_dwordx4 v[216:217], off
	v_lshl_add_u64 v[216:217], v[220:221], 0, s[8:9]
	s_add_i32 m0, s6, 0x2000
	s_add_i32 s6, s50, s3
	global_load_lds_dwordx4 v[216:217], off
	v_lshl_add_u64 v[216:217], v[222:223], 0, s[8:9]
	s_mov_b32 m0, s6
	s_nop 0
	global_load_lds_dwordx4 v[216:217], off
	v_lshl_add_u64 v[216:217], v[218:219], 0, s[8:9]
	s_add_i32 m0, s6, 0x2000
	s_nop 0
	global_load_lds_dwordx4 v[216:217], off
	v_lshl_add_u64 v[216:217], v[224:225], 0, s[8:9]
	s_mov_b32 m0, s68
	s_nop 0
	global_load_lds_dwordx4 v[216:217], off
	v_lshl_add_u64 v[216:217], v[228:229], 0, s[8:9]
	s_mov_b32 m0, s69
	s_nop 0
	global_load_lds_dwordx4 v[216:217], off
	s_waitcnt vmcnt(8)
	s_waitcnt lgkmcnt(0)
	s_barrier
	s_setprio 1
	s_waitcnt lgkmcnt(0)
	v_mfma_f32_16x16x32_bf16 v[62:65], v[134:137], v[172:175], v[62:65]
	v_mfma_f32_16x16x32_bf16 v[54:57], v[142:145], v[172:175], v[54:57]
	v_mfma_f32_16x16x32_bf16 v[46:49], v[134:137], v[180:183], v[46:49]
	v_mfma_f32_16x16x32_bf16 v[38:41], v[142:145], v[180:183], v[38:41]
	v_mfma_f32_16x16x32_bf16 v[30:33], v[134:137], v[200:203], v[30:33]
	v_mfma_f32_16x16x32_bf16 v[22:25], v[142:145], v[200:203], v[22:25]
	v_mfma_f32_16x16x32_bf16 v[14:17], v[134:137], v[208:211], v[14:17]
	v_mfma_f32_16x16x32_bf16 v[6:9], v[142:145], v[208:211], v[6:9]
	v_mfma_f32_16x16x32_bf16 v[62:65], v[138:141], v[176:179], v[62:65]
	v_mfma_f32_16x16x32_bf16 v[54:57], v[152:155], v[176:179], v[54:57]
	v_mfma_f32_16x16x32_bf16 v[46:49], v[138:141], v[196:199], v[46:49]
	v_mfma_f32_16x16x32_bf16 v[38:41], v[152:155], v[196:199], v[38:41]
	v_mfma_f32_16x16x32_bf16 v[30:33], v[138:141], v[204:207], v[30:33]
	v_mfma_f32_16x16x32_bf16 v[22:25], v[152:155], v[204:207], v[22:25]
	v_mfma_f32_16x16x32_bf16 v[14:17], v[138:141], v[212:215], v[14:17]
	v_mfma_f32_16x16x32_bf16 v[6:9], v[152:155], v[212:215], v[6:9]
	v_mfma_f32_16x16x32_bf16 v[58:61], v[156:159], v[172:175], v[58:61]
	v_mfma_f32_16x16x32_bf16 v[50:53], v[164:167], v[172:175], v[50:53]
	v_mfma_f32_16x16x32_bf16 v[42:45], v[156:159], v[180:183], v[42:45]
	v_mfma_f32_16x16x32_bf16 v[34:37], v[164:167], v[180:183], v[34:37]
	v_mfma_f32_16x16x32_bf16 v[26:29], v[156:159], v[200:203], v[26:29]
	v_mfma_f32_16x16x32_bf16 v[18:21], v[164:167], v[200:203], v[18:21]
	v_mfma_f32_16x16x32_bf16 v[10:13], v[156:159], v[208:211], v[10:13]
	v_mfma_f32_16x16x32_bf16 v[2:5], v[164:167], v[208:211], v[2:5]
	v_mfma_f32_16x16x32_bf16 v[58:61], v[160:163], v[176:179], v[58:61]
	v_mfma_f32_16x16x32_bf16 v[50:53], v[168:171], v[176:179], v[50:53]
	v_mfma_f32_16x16x32_bf16 v[42:45], v[160:163], v[196:199], v[42:45]
	v_mfma_f32_16x16x32_bf16 v[34:37], v[168:171], v[196:199], v[34:37]
	v_mfma_f32_16x16x32_bf16 v[26:29], v[160:163], v[204:207], v[26:29]
	v_mfma_f32_16x16x32_bf16 v[18:21], v[168:171], v[204:207], v[18:21]
	v_mfma_f32_16x16x32_bf16 v[10:13], v[160:163], v[212:215], v[10:13]
	v_mfma_f32_16x16x32_bf16 v[2:5], v[168:171], v[212:215], v[2:5]
	s_setprio 0
	s_barrier
	s_add_u32 s58, s58, 0x100
	s_addc_u32 s59, s59, 0
	s_cmp_ge_i32 s47, s81
	s_mov_b32 s6, s47
	s_cbranch_scc0 .LBB0_806
	s_and_b64 vcc, exec, s[10:11]
	s_cbranch_vccz .LBB0_809
	s_barrier

; #define PG8_STAGE(bufoff, gbase, RR, ld) do { _Pragma("unroll") for (int _i = 0; _i < 2; ++_i) \
;         __builtin_amdgcn_global_load_lds((const unsigned*)((const char*)(gbase) + (RR)[_i] * (ld) + C2[_i]), (LAS unsigned*)(lds + (bufoff) + ldsw + _i * 8192), 16, 0, 0); } while (0)
; #define PG8_LDA(dst, b, h) do { _Pragma("unroll") for (int m = 0; m < 4; ++m) _Pragma("unroll") for (int k = 0; k < 2; ++k) dst[m][k] = *(const LAS bf16x8*)(lds + PG8_SA(b, h) + aoff + m * 2048 + k * 1024); } while (0)
; #define PG8_WAIT_V(n) asm volatile("s_waitcnt vmcnt(" #n ")" ::: "memory")
; #define PG8_WAIT_L(n) asm volatile("s_waitcnt lgkmcnt(" #n ")" ::: "memory")
; template <class Sched, class Epi>
; __device__ __forceinline__ void gemm_run(LAS unsigned char* lds, const Sched& S, const Epi& E) {
;     ...
;         const bool has_next = S.next(ui + 1, nxt);
;         const char* nA = has_next ? nxt.A : cA; const char* nB = has_next ? nxt.B : cB; const unsigned nlda = has_next ? nxt.lda : lda, nldb = has_next ? nxt.ldb : ldb;
;         const int nt = cur.nt;
;         for (int t = 0; t < nt; t += 2) {
;             const bool last = (t == nt - 2);
;             const char* a1 = cA + (size_t)(t + 1) * kstep;
;             const char* a2 = last ? nA : cA + (size_t)(t + 2) * kstep; const char* b2 = last ? nB : cB + (size_t)(t + 2) * kstep;
;             const unsigned la2 = last ? nlda : lda, lb2 = last ? nldb : ldb;
;             const char* a3 = a2 + kstep; const char* b3 = b2 + kstep;
;             PG8_LDB(B0, 0, 0); PG8_LDB(B1, 0, 1); PG8_SCHED; PG8_LDA(At, 0, 0); PG8_STAGE(PG8_SA(1, 1), a1 + (size_t)HALF * lda, RA, lda);
;             PG8_WAIT_V(8); PG8_WAIT_L(0); PG8_BAR; PG8_MMA(0, 0, At, B0); PG8_MMA(0, 1, At, B1); PG8_BAR; PG8_SCHED;
;             PG8_LDA(At, 0, 1); PG8_STAGE(PG8_SB(0, 0), b2, RB, lb2); PG8_STAGE(PG8_SB(0, 1), b2 + (size_t)HALF * lb2, RB, lb2); PG8_STAGE(PG8_SA(0, 0), a2, RA, la2);
;             PG8_WAIT_V(8); PG8_WAIT_L(0); PG8_BAR; PG8_MMA(1, 0, At, B0); PG8_MMA(1, 1, At, B1); PG8_BAR; PG8_SCHED;
;     ...
;         for (int a = 0; a < 2; ++a)
; #pragma unroll
;             for (int b = 0; b < 2; ++b)
; #pragma unroll
;                 for (int m = 0; m < 4; ++m)
; #pragma unroll
;                     for (int n = 0; n < 2; ++n) acc[a][b][m][n] = (f32x4){0.f, 0.f, 0.f, 0.f};
;         cur = nxt; cA = nA; cB = nB; lda = nlda; ldb = nldb; ++ui;
.LBB0_893:
	s_add_u32 s19, s38, 0x100
	v_mov_b32_e32 v2, 0
	s_addc_u32 s31, s39, 0
	v_lshl_add_u64 v[130:131], s[36:37], 0, v[168:169]
	v_lshl_add_u64 v[132:133], s[36:37], 0, v[170:171]
	s_mov_b32 s44, -2
	s_mov_b64 s[38:39], 0
	s_waitcnt lgkmcnt(0)
	v_mov_b32_e32 v3, v2
	v_mov_b32_e32 v4, v2
	v_mov_b32_e32 v5, v2
	v_mov_b32_e32 v6, v2
	v_mov_b32_e32 v7, v2
	v_mov_b32_e32 v8, v2
	v_mov_b32_e32 v9, v2
	v_mov_b32_e32 v18, v2
	v_mov_b32_e32 v19, v2
	v_mov_b32_e32 v20, v2
	v_mov_b32_e32 v21, v2
	v_mov_b32_e32 v22, v2
	v_mov_b32_e32 v23, v2
	v_mov_b32_e32 v24, v2
	v_mov_b32_e32 v25, v2
	v_mov_b32_e32 v34, v2
	v_mov_b32_e32 v35, v2
	v_mov_b32_e32 v36, v2
	v_mov_b32_e32 v37, v2
	v_mov_b32_e32 v38, v2
	v_mov_b32_e32 v39, v2
	v_mov_b32_e32 v40, v2
	v_mov_b32_e32 v41, v2
	v_mov_b32_e32 v50, v2
	v_mov_b32_e32 v51, v2
	v_mov_b32_e32 v52, v2
	v_mov_b32_e32 v53, v2
	v_mov_b32_e32 v54, v2
	v_mov_b32_e32 v55, v2
	v_mov_b32_e32 v56, v2
	v_mov_b32_e32 v57, v2
	v_mov_b32_e32 v10, v2
	v_mov_b32_e32 v11, v2
	v_mov_b32_e32 v12, v2
	v_mov_b32_e32 v13, v2
	v_mov_b32_e32 v14, v2
	v_mov_b32_e32 v15, v2
	v_mov_b32_e32 v16, v2
	v_mov_b32_e32 v17, v2
	v_mov_b32_e32 v26, v2
	v_mov_b32_e32 v27, v2
	v_mov_b32_e32 v28, v2
	v_mov_b32_e32 v29, v2
	v_mov_b32_e32 v30, v2
	v_mov_b32_e32 v31, v2
	v_mov_b32_e32 v32, v2
	v_mov_b32_e32 v33, v2
	v_mov_b32_e32 v42, v2
	v_mov_b32_e32 v43, v2
	v_mov_b32_e32 v44, v2
	v_mov_b32_e32 v45, v2
	v_mov_b32_e32 v46, v2
	v_mov_b32_e32 v47, v2
	v_mov_b32_e32 v48, v2
	v_mov_b32_e32 v49, v2
	v_mov_b32_e32 v58, v2
	v_mov_b32_e32 v59, v2
	v_mov_b32_e32 v60, v2
	v_mov_b32_e32 v61, v2
	v_mov_b32_e32 v62, v2
	v_mov_b32_e32 v63, v2
	v_mov_b32_e32 v64, v2
	v_mov_b32_e32 v65, v2
	v_mov_b32_e32 v66, v2
	v_mov_b32_e32 v67, v2
	v_mov_b32_e32 v68, v2
	v_mov_b32_e32 v69, v2
	v_mov_b32_e32 v70, v2
	v_mov_b32_e32 v71, v2
	v_mov_b32_e32 v72, v2
	v_mov_b32_e32 v73, v2
	v_mov_b32_e32 v82, v2
	v_mov_b32_e32 v83, v2
	v_mov_b32_e32 v84, v2
	v_mov_b32_e32 v85, v2
	v_mov_b32_e32 v86, v2
	v_mov_b32_e32 v87, v2
	v_mov_b32_e32 v88, v2
	v_mov_b32_e32 v89, v2
	v_mov_b32_e32 v98, v2
	v_mov_b32_e32 v99, v2
	v_mov_b32_e32 v100, v2
	v_mov_b32_e32 v101, v2
	v_mov_b32_e32 v102, v2
	v_mov_b32_e32 v103, v2
	v_mov_b32_e32 v104, v2
	v_mov_b32_e32 v105, v2
	v_mov_b32_e32 v114, v2
	v_mov_b32_e32 v115, v2
	v_mov_b32_e32 v116, v2
	v_mov_b32_e32 v117, v2
	v_mov_b32_e32 v118, v2
	v_mov_b32_e32 v119, v2
	v_mov_b32_e32 v120, v2
	v_mov_b32_e32 v121, v2
	v_mov_b32_e32 v74, v2
	v_mov_b32_e32 v75, v2
	v_mov_b32_e32 v76, v2
	v_mov_b32_e32 v77, v2
	v_mov_b32_e32 v78, v2
	v_mov_b32_e32 v79, v2
	v_mov_b32_e32 v80, v2
	v_mov_b32_e32 v81, v2
	v_mov_b32_e32 v90, v2
	v_mov_b32_e32 v91, v2
	v_mov_b32_e32 v92, v2
	v_mov_b32_e32 v93, v2
	v_mov_b32_e32 v94, v2
	v_mov_b32_e32 v95, v2
	v_mov_b32_e32 v96, v2
	v_mov_b32_e32 v97, v2
	v_mov_b32_e32 v106, v2
	v_mov_b32_e32 v107, v2
	v_mov_b32_e32 v108, v2
	v_mov_b32_e32 v109, v2
	v_mov_b32_e32 v110, v2
	v_mov_b32_e32 v111, v2
	v_mov_b32_e32 v112, v2
	v_mov_b32_e32 v113, v2
	v_mov_b32_e32 v122, v2
	v_mov_b32_e32 v123, v2
	v_mov_b32_e32 v124, v2
	v_mov_b32_e32 v125, v2
	v_mov_b32_e32 v126, v2
	v_mov_b32_e32 v127, v2
	v_mov_b32_e32 v128, v2
	v_mov_b32_e32 v129, v2
	.p2align 6
.LBB0_894:
	ds_read_b128 v[134:137], v191
	ds_read_b128 v[138:141], v191 offset:1024
	ds_read_b128 v[142:145], v191 offset:2048
	ds_read_b128 v[146:149], v191 offset:3072
	ds_read_b128 v[150:153], v192
	ds_read_b128 v[172:175], v192 offset:1024
	ds_read_b128 v[176:179], v192 offset:2048
	ds_read_b128 v[180:183], v192 offset:3072
	s_add_u32 s40, s36, s38
	s_addc_u32 s41, s37, s39
	s_add_u32 s40, s40, 0x100
	s_addc_u32 s41, s41, 0
	s_add_u32 s45, s19, s38
	s_addc_u32 s46, s31, s39
	s_cmpk_eq_i32 s38, 0xf00
	s_cselect_b32 s43, s21, s41
	s_cselect_b32 s42, s20, s40
	s_cselect_b32 s41, s29, s46
	s_cselect_b32 s40, s28, s45
	v_lshl_add_u64 v[224:225], v[130:131], 0, s[38:39]
	s_add_i32 m0, s33, 0xc000
	ds_read_b128 v[184:187], v193
	ds_read_b128 v[196:199], v193 offset:1024
	ds_read_b128 v[200:203], v193 offset:2048
	ds_read_b128 v[204:207], v193 offset:3072
	ds_read_b128 v[208:211], v193 offset:4096
	ds_read_b128 v[212:215], v193 offset:5120
	ds_read_b128 v[216:219], v193 offset:6144
	ds_read_b128 v[220:223], v193 offset:7168
	global_load_lds_dwordx4 v[224:225], off
	v_lshl_add_u64 v[224:225], v[132:133], 0, s[38:39]
	s_add_i32 m0, s33, 0xe000
	s_nop 0
	global_load_lds_dwordx4 v[224:225], off
	s_waitcnt vmcnt(8)
	s_waitcnt lgkmcnt(0)
	s_barrier
	s_setprio 1
	s_waitcnt lgkmcnt(0)
	v_mfma_f32_16x16x32_bf16 v[126:129], v[134:137], v[184:187], v[126:129]
	v_mfma_f32_16x16x32_bf16 v[122:125], v[142:145], v[184:187], v[122:125]
	v_mfma_f32_16x16x32_bf16 v[110:113], v[134:137], v[200:203], v[110:113]
	v_mfma_f32_16x16x32_bf16 v[106:109], v[142:145], v[200:203], v[106:109]
	v_mfma_f32_16x16x32_bf16 v[94:97], v[134:137], v[208:211], v[94:97]
	v_mfma_f32_16x16x32_bf16 v[90:93], v[142:145], v[208:211], v[90:93]
	v_mfma_f32_16x16x32_bf16 v[78:81], v[134:137], v[216:219], v[78:81]
	v_mfma_f32_16x16x32_bf16 v[74:77], v[142:145], v[216:219], v[74:77]
	v_mfma_f32_16x16x32_bf16 v[126:129], v[138:141], v[196:199], v[126:129]
	v_mfma_f32_16x16x32_bf16 v[122:125], v[146:149], v[196:199], v[122:125]
	v_mfma_f32_16x16x32_bf16 v[110:113], v[138:141], v[204:207], v[110:113]
	v_mfma_f32_16x16x32_bf16 v[106:109], v[146:149], v[204:207], v[106:109]
	v_mfma_f32_16x16x32_bf16 v[94:97], v[138:141], v[212:215], v[94:97]
	v_mfma_f32_16x16x32_bf16 v[90:93], v[146:149], v[212:215], v[90:93]
	v_mfma_f32_16x16x32_bf16 v[78:81], v[138:141], v[220:223], v[78:81]
	v_mfma_f32_16x16x32_bf16 v[74:77], v[146:149], v[220:223], v[74:77]
	v_mfma_f32_16x16x32_bf16 v[118:121], v[150:153], v[184:187], v[118:121]
	v_mfma_f32_16x16x32_bf16 v[114:117], v[176:179], v[184:187], v[114:117]
	v_mfma_f32_16x16x32_bf16 v[102:105], v[150:153], v[200:203], v[102:105]
	v_mfma_f32_16x16x32_bf16 v[98:101], v[176:179], v[200:203], v[98:101]
	v_mfma_f32_16x16x32_bf16 v[86:89], v[150:153], v[208:211], v[86:89]
	v_mfma_f32_16x16x32_bf16 v[82:85], v[176:179], v[208:211], v[82:85]
	v_mfma_f32_16x16x32_bf16 v[70:73], v[150:153], v[216:219], v[70:73]
	v_mfma_f32_16x16x32_bf16 v[66:69], v[176:179], v[216:219], v[66:69]
	v_mfma_f32_16x16x32_bf16 v[118:121], v[172:175], v[196:199], v[118:121]
	v_mfma_f32_16x16x32_bf16 v[114:117], v[180:183], v[196:199], v[114:117]
	v_mfma_f32_16x16x32_bf16 v[102:105], v[172:175], v[204:207], v[102:105]
	v_mfma_f32_16x16x32_bf16 v[98:101], v[180:183], v[204:207], v[98:101]
	v_mfma_f32_16x16x32_bf16 v[86:89], v[172:175], v[212:215], v[86:89]
	v_mfma_f32_16x16x32_bf16 v[82:85], v[180:183], v[212:215], v[82:85]
	v_mfma_f32_16x16x32_bf16 v[70:73], v[172:175], v[220:223], v[70:73]
	v_mfma_f32_16x16x32_bf16 v[66:69], v[180:183], v[220:223], v[66:69]
	s_setprio 0
	s_barrier
; #define PG8_STAGE(bufoff, gbase, RR, ld) do { _Pragma("unroll") for (int _i = 0; _i < 2; ++_i) \
;         __builtin_amdgcn_global_load_lds((const unsigned*)((const char*)(gbase) + (RR)[_i] * (ld) + C2[_i]), (LAS unsigned*)(lds + (bufoff) + ldsw + _i * 8192), 16, 0, 0); } while (0)
; #define PG8_LDA(dst, b, h) do { _Pragma("unroll") for (int m = 0; m < 4; ++m) _Pragma("unroll") for (int k = 0; k < 2; ++k) dst[m][k] = *(const LAS bf16x8*)(lds + PG8_SA(b, h) + aoff + m * 2048 + k * 1024); } while (0)
; #define PG8_LDB(dst, b, h) do { _Pragma("unroll") for (int n = 0; n < 2; ++n) _Pragma("unroll") for (int k = 0; k < 2; ++k) dst[n][k] = *(const LAS bf16x8*)(lds + PG8_SB(b, h) + boff + n * 2048 + k * 1024); } while (0)
; #define PG8_MMA(ai, bj, At, Bt) do { __builtin_amdgcn_s_setprio(1); _Pragma("unroll") for (int m = 0; m < 4; ++m) _Pragma("unroll") for (int n = 0; n < 2; ++n) _Pragma("unroll") for (int k = 0; k < 2; ++k) \
;         acc[ai][bj][m][n] = __builtin_amdgcn_mfma_f32_16x16x32_bf16(Bt[n][k], At[m][k], acc[ai][bj][m][n], 0, 0, 0); __builtin_amdgcn_s_setprio(0); } while (0)
; #define PG8_WAIT_V(n) asm volatile("s_waitcnt vmcnt(" #n ")" ::: "memory")
; #define PG8_WAIT_L(n) asm volatile("s_waitcnt lgkmcnt(" #n ")" ::: "memory")
; #define PG8_BAR __builtin_amdgcn_s_barrier()
; #define PG8_SCHED __builtin_amdgcn_sched_barrier(0)
; template <class Sched, class Epi>
; __device__ __forceinline__ void gemm_run(LAS unsigned char* lds, const Sched& S, const Epi& E) {
;     ...
;             PG8_LDA(At, 0, 1); PG8_STAGE(PG8_SB(0, 0), b2, RB, lb2); PG8_STAGE(PG8_SB(0, 1), b2 + (size_t)HALF * lb2, RB, lb2); PG8_STAGE(PG8_SA(0, 0), a2, RA, la2);
;             PG8_WAIT_V(8); PG8_WAIT_L(0); PG8_BAR; PG8_MMA(1, 0, At, B0); PG8_MMA(1, 1, At, B1); PG8_BAR; PG8_SCHED;
;             PG8_LDB(B0, 1, 0); PG8_LDB(B1, 1, 1); PG8_SCHED; PG8_LDA(At, 1, 0); PG8_STAGE(PG8_SA(0, 1), a2 + (size_t)HALF * la2, RA, la2);
;             PG8_WAIT_V(8); PG8_WAIT_L(0); PG8_BAR; PG8_MMA(0, 0, At, B0); PG8_MMA(0, 1, At, B1); PG8_BAR; PG8_SCHED;
	v_lshl_add_u64 v[224:225], s[40:41], 0, v[156:157]
	s_add_i32 s45, s61, s3
	v_lshl_add_u64 v[224:225], v[224:225], 0, v[154:155]
	s_mov_b32 m0, s45
	ds_read_b128 v[184:187], v193 offset:16384
	ds_read_b128 v[196:199], v193 offset:17408
	ds_read_b128 v[200:203], v193 offset:18432
	ds_read_b128 v[204:207], v193 offset:19456
	ds_read_b128 v[208:211], v193 offset:20480
	ds_read_b128 v[212:215], v193 offset:21504
	ds_read_b128 v[216:219], v193 offset:22528
	ds_read_b128 v[220:223], v193 offset:23552
	global_load_lds_dwordx4 v[224:225], off
	s_add_i32 m0, s45, 0x2000
	s_add_u32 s46, s40, 0x80000
	v_lshl_add_u64 v[226:227], s[40:41], 0, v[160:161]
	s_addc_u32 s47, s41, 0
	v_lshl_add_u64 v[226:227], v[226:227], 0, v[154:155]
	v_lshl_add_u64 v[228:229], s[46:47], 0, v[156:157]
	s_add_i32 s45, s62, s3
	global_load_lds_dwordx4 v[226:227], off
	v_lshl_add_u64 v[228:229], v[228:229], 0, v[154:155]
	s_mov_b32 m0, s45
	v_lshl_add_u64 v[230:231], s[42:43], 0, v[164:165]
	global_load_lds_dwordx4 v[228:229], off
	v_lshl_add_u64 v[228:229], s[46:47], 0, v[160:161]
	v_lshl_add_u64 v[228:229], v[228:229], 0, v[154:155]
	s_add_i32 m0, s45, 0x2000
	v_lshl_add_u64 v[230:231], v[230:231], 0, v[154:155]
	global_load_lds_dwordx4 v[228:229], off
	v_lshl_add_u64 v[228:229], s[42:43], 0, v[162:163]
	v_lshl_add_u64 v[228:229], v[228:229], 0, v[154:155]
	s_mov_b32 m0, s33
	s_nop 0
	global_load_lds_dwordx4 v[228:229], off
	s_mov_b32 m0, s35
	s_nop 0
	global_load_lds_dwordx4 v[230:231], off
	s_waitcnt vmcnt(8)
	s_waitcnt lgkmcnt(0)
	s_barrier
	s_setprio 1
	s_waitcnt lgkmcnt(0)
	v_mfma_f32_16x16x32_bf16 v[62:65], v[134:137], v[184:187], v[62:65]
	v_mfma_f32_16x16x32_bf16 v[58:61], v[142:145], v[184:187], v[58:61]
	v_mfma_f32_16x16x32_bf16 v[46:49], v[134:137], v[200:203], v[46:49]
	v_mfma_f32_16x16x32_bf16 v[42:45], v[142:145], v[200:203], v[42:45]
	v_mfma_f32_16x16x32_bf16 v[30:33], v[134:137], v[208:211], v[30:33]
	v_mfma_f32_16x16x32_bf16 v[26:29], v[142:145], v[208:211], v[26:29]
	v_mfma_f32_16x16x32_bf16 v[14:17], v[134:137], v[216:219], v[14:17]
	v_mfma_f32_16x16x32_bf16 v[10:13], v[142:145], v[216:219], v[10:13]
	v_mfma_f32_16x16x32_bf16 v[62:65], v[138:141], v[196:199], v[62:65]
	v_mfma_f32_16x16x32_bf16 v[58:61], v[146:149], v[196:199], v[58:61]
	v_mfma_f32_16x16x32_bf16 v[46:49], v[138:141], v[204:207], v[46:49]
	v_mfma_f32_16x16x32_bf16 v[42:45], v[146:149], v[204:207], v[42:45]
	v_mfma_f32_16x16x32_bf16 v[30:33], v[138:141], v[212:215], v[30:33]
	v_mfma_f32_16x16x32_bf16 v[26:29], v[146:149], v[212:215], v[26:29]
	v_mfma_f32_16x16x32_bf16 v[14:17], v[138:141], v[220:223], v[14:17]
	v_mfma_f32_16x16x32_bf16 v[10:13], v[146:149], v[220:223], v[10:13]
	v_mfma_f32_16x16x32_bf16 v[54:57], v[150:153], v[184:187], v[54:57]
	v_mfma_f32_16x16x32_bf16 v[50:53], v[176:179], v[184:187], v[50:53]
	v_mfma_f32_16x16x32_bf16 v[38:41], v[150:153], v[200:203], v[38:41]
	v_mfma_f32_16x16x32_bf16 v[34:37], v[176:179], v[200:203], v[34:37]
	v_mfma_f32_16x16x32_bf16 v[22:25], v[150:153], v[208:211], v[22:25]
	v_mfma_f32_16x16x32_bf16 v[18:21], v[176:179], v[208:211], v[18:21]
	v_mfma_f32_16x16x32_bf16 v[6:9], v[150:153], v[216:219], v[6:9]
	v_mfma_f32_16x16x32_bf16 v[2:5], v[176:179], v[216:219], v[2:5]
	v_mfma_f32_16x16x32_bf16 v[54:57], v[172:175], v[196:199], v[54:57]
	v_mfma_f32_16x16x32_bf16 v[50:53], v[180:183], v[196:199], v[50:53]
	v_mfma_f32_16x16x32_bf16 v[38:41], v[172:175], v[204:207], v[38:41]
	v_mfma_f32_16x16x32_bf16 v[34:37], v[180:183], v[204:207], v[34:37]
	v_mfma_f32_16x16x32_bf16 v[22:25], v[172:175], v[212:215], v[22:25]
	v_mfma_f32_16x16x32_bf16 v[18:21], v[180:183], v[212:215], v[18:21]
	v_mfma_f32_16x16x32_bf16 v[6:9], v[172:175], v[220:223], v[6:9]
	v_mfma_f32_16x16x32_bf16 v[2:5], v[180:183], v[220:223], v[2:5]
	s_setprio 0
	s_barrier
	s_add_i32 s45, 0, 0x18000
	s_add_i32 s46, 0, 0x1c000
	v_add_u32_e32 v146, s45, v190
	v_add_u32_e32 v180, s46, v190
	ds_read_b128 v[134:137], v146
	ds_read_b128 v[138:141], v146 offset:1024
	ds_read_b128 v[142:145], v146 offset:2048
	ds_read_b128 v[146:149], v146 offset:3072
	ds_read_b128 v[150:153], v180
	ds_read_b128 v[172:175], v180 offset:1024
	ds_read_b128 v[176:179], v180 offset:2048
	ds_read_b128 v[180:183], v180 offset:3072
	s_add_u32 s42, s42, 0x80000
	s_addc_u32 s43, s43, 0
	v_lshl_add_u64 v[232:233], s[42:43], 0, v[162:163]
	s_mov_b32 m0, s52
	v_lshl_add_u64 v[232:233], v[232:233], 0, v[154:155]
	ds_read_b128 v[184:187], v193 offset:32768
	ds_read_b128 v[196:199], v193 offset:33792
	ds_read_b128 v[200:203], v193 offset:34816
	ds_read_b128 v[204:207], v193 offset:35840
	ds_read_b128 v[208:211], v193 offset:36864
	ds_read_b128 v[212:215], v193 offset:37888
	ds_read_b128 v[216:219], v193 offset:38912
	ds_read_b128 v[220:223], v193 offset:39936
	global_load_lds_dwordx4 v[232:233], off
	v_lshl_add_u64 v[232:233], s[42:43], 0, v[164:165]
	v_lshl_add_u64 v[232:233], v[232:233], 0, v[154:155]
	s_mov_b32 m0, s53
	s_nop 0
	global_load_lds_dwordx4 v[232:233], off
	s_waitcnt vmcnt(8)
	s_waitcnt lgkmcnt(0)
	s_barrier
; #define PG8_STAGE(bufoff, gbase, RR, ld) do { _Pragma("unroll") for (int _i = 0; _i < 2; ++_i) \
;         __builtin_amdgcn_global_load_lds((const unsigned*)((const char*)(gbase) + (RR)[_i] * (ld) + C2[_i]), (LAS unsigned*)(lds + (bufoff) + ldsw + _i * 8192), 16, 0, 0); } while (0)
; #define PG8_LDA(dst, b, h) do { _Pragma("unroll") for (int m = 0; m < 4; ++m) _Pragma("unroll") for (int k = 0; k < 2; ++k) dst[m][k] = *(const LAS bf16x8*)(lds + PG8_SA(b, h) + aoff + m * 2048 + k * 1024); } while (0)
; #define PG8_MMA(ai, bj, At, Bt) do { __builtin_amdgcn_s_setprio(1); _Pragma("unroll") for (int m = 0; m < 4; ++m) _Pragma("unroll") for (int n = 0; n < 2; ++n) _Pragma("unroll") for (int k = 0; k < 2; ++k) \
;         acc[ai][bj][m][n] = __builtin_amdgcn_mfma_f32_16x16x32_bf16(Bt[n][k], At[m][k], acc[ai][bj][m][n], 0, 0, 0); __builtin_amdgcn_s_setprio(0); } while (0)
; #define PG8_WAIT_V(n) asm volatile("s_waitcnt vmcnt(" #n ")" ::: "memory")
; #define PG8_WAIT_L(n) asm volatile("s_waitcnt lgkmcnt(" #n ")" ::: "memory")
; #define PG8_BAR __builtin_amdgcn_s_barrier()
; #define PG8_SCHED __builtin_amdgcn_sched_barrier(0)
; template <class Sched, class Epi>
; __device__ __forceinline__ void gemm_run(LAS unsigned char* lds, const Sched& S, const Epi& E) {
;     ...
;             PG8_WAIT_V(8); PG8_WAIT_L(0); PG8_BAR; PG8_MMA(0, 0, At, B0); PG8_MMA(0, 1, At, B1); PG8_BAR; PG8_SCHED;
;             PG8_LDA(At, 1, 1); PG8_STAGE(PG8_SB(1, 0), b3, RB, lb2); PG8_STAGE(PG8_SB(1, 1), b3 + (size_t)HALF * lb2, RB, lb2); PG8_STAGE(PG8_SA(1, 0), a3, RA, la2);
;             PG8_WAIT_V(8); PG8_WAIT_L(0); PG8_BAR; PG8_MMA(1, 0, At, B0); PG8_MMA(1, 1, At, B1); PG8_BAR; PG8_SCHED;
;         }
;         if (wr == 0) PG8_BAR;
	s_setprio 1
	s_waitcnt lgkmcnt(0)
	v_mfma_f32_16x16x32_bf16 v[126:129], v[134:137], v[184:187], v[126:129]
	v_mfma_f32_16x16x32_bf16 v[122:125], v[142:145], v[184:187], v[122:125]
	v_mfma_f32_16x16x32_bf16 v[110:113], v[134:137], v[200:203], v[110:113]
	v_mfma_f32_16x16x32_bf16 v[106:109], v[142:145], v[200:203], v[106:109]
	v_mfma_f32_16x16x32_bf16 v[94:97], v[134:137], v[208:211], v[94:97]
	v_mfma_f32_16x16x32_bf16 v[90:93], v[142:145], v[208:211], v[90:93]
	v_mfma_f32_16x16x32_bf16 v[78:81], v[134:137], v[216:219], v[78:81]
	v_mfma_f32_16x16x32_bf16 v[74:77], v[142:145], v[216:219], v[74:77]
	v_mfma_f32_16x16x32_bf16 v[126:129], v[138:141], v[196:199], v[126:129]
	v_mfma_f32_16x16x32_bf16 v[122:125], v[146:149], v[196:199], v[122:125]
	v_mfma_f32_16x16x32_bf16 v[110:113], v[138:141], v[204:207], v[110:113]
	v_mfma_f32_16x16x32_bf16 v[106:109], v[146:149], v[204:207], v[106:109]
	v_mfma_f32_16x16x32_bf16 v[94:97], v[138:141], v[212:215], v[94:97]
	v_mfma_f32_16x16x32_bf16 v[90:93], v[146:149], v[212:215], v[90:93]
	v_mfma_f32_16x16x32_bf16 v[78:81], v[138:141], v[220:223], v[78:81]
	v_mfma_f32_16x16x32_bf16 v[74:77], v[146:149], v[220:223], v[74:77]
	v_mfma_f32_16x16x32_bf16 v[118:121], v[150:153], v[184:187], v[118:121]
	v_mfma_f32_16x16x32_bf16 v[114:117], v[176:179], v[184:187], v[114:117]
	v_mfma_f32_16x16x32_bf16 v[102:105], v[150:153], v[200:203], v[102:105]
	v_mfma_f32_16x16x32_bf16 v[98:101], v[176:179], v[200:203], v[98:101]
	v_mfma_f32_16x16x32_bf16 v[86:89], v[150:153], v[208:211], v[86:89]
	v_mfma_f32_16x16x32_bf16 v[82:85], v[176:179], v[208:211], v[82:85]
	v_mfma_f32_16x16x32_bf16 v[70:73], v[150:153], v[216:219], v[70:73]
	v_mfma_f32_16x16x32_bf16 v[66:69], v[176:179], v[216:219], v[66:69]
	v_mfma_f32_16x16x32_bf16 v[118:121], v[172:175], v[196:199], v[118:121]
	v_mfma_f32_16x16x32_bf16 v[114:117], v[180:183], v[196:199], v[114:117]
	v_mfma_f32_16x16x32_bf16 v[102:105], v[172:175], v[204:207], v[102:105]
	v_mfma_f32_16x16x32_bf16 v[98:101], v[180:183], v[204:207], v[98:101]
	v_mfma_f32_16x16x32_bf16 v[86:89], v[172:175], v[212:215], v[86:89]
	v_mfma_f32_16x16x32_bf16 v[82:85], v[180:183], v[212:215], v[82:85]
	v_mfma_f32_16x16x32_bf16 v[70:73], v[172:175], v[220:223], v[70:73]
	v_mfma_f32_16x16x32_bf16 v[66:69], v[180:183], v[220:223], v[66:69]
	s_setprio 0
	s_barrier
	s_add_i32 s42, s45, s3
	v_lshl_add_u64 v[224:225], v[224:225], 0, s[10:11]
	s_mov_b32 m0, s42
	ds_read_b128 v[184:187], v193 offset:49152
	ds_read_b128 v[196:199], v193 offset:50176
	ds_read_b128 v[200:203], v193 offset:51200
	ds_read_b128 v[204:207], v193 offset:52224
	ds_read_b128 v[208:211], v193 offset:53248
	ds_read_b128 v[212:215], v193 offset:54272
	ds_read_b128 v[216:219], v193 offset:55296
	ds_read_b128 v[220:223], v193 offset:56320
	global_load_lds_dwordx4 v[224:225], off
	s_add_i32 m0, s42, 0x2000
	s_add_u32 s40, s40, 0x80080
	v_lshl_add_u64 v[224:225], v[226:227], 0, s[10:11]
	s_addc_u32 s41, s41, 0
	global_load_lds_dwordx4 v[224:225], off
	v_lshl_add_u64 v[224:225], s[40:41], 0, v[156:157]
	s_add_i32 s42, s46, s3
	v_lshl_add_u64 v[224:225], v[224:225], 0, v[154:155]
	s_mov_b32 m0, s42
	s_nop 0
	global_load_lds_dwordx4 v[224:225], off
	v_lshl_add_u64 v[224:225], s[40:41], 0, v[160:161]
	v_lshl_add_u64 v[224:225], v[224:225], 0, v[154:155]
	s_add_i32 m0, s42, 0x2000
	s_nop 0
	global_load_lds_dwordx4 v[224:225], off
	v_lshl_add_u64 v[224:225], v[228:229], 0, s[10:11]
	s_mov_b32 m0, s55
	s_nop 0
	global_load_lds_dwordx4 v[224:225], off
	v_lshl_add_u64 v[224:225], v[230:231], 0, s[10:11]
	s_mov_b32 m0, s56
	s_nop 0
	global_load_lds_dwordx4 v[224:225], off
	s_waitcnt vmcnt(8)
	s_waitcnt lgkmcnt(0)
	s_barrier
	s_setprio 1
	s_waitcnt lgkmcnt(0)
	v_mfma_f32_16x16x32_bf16 v[62:65], v[134:137], v[184:187], v[62:65]
	v_mfma_f32_16x16x32_bf16 v[58:61], v[142:145], v[184:187], v[58:61]
	v_mfma_f32_16x16x32_bf16 v[46:49], v[134:137], v[200:203], v[46:49]
	v_mfma_f32_16x16x32_bf16 v[42:45], v[142:145], v[200:203], v[42:45]
	v_mfma_f32_16x16x32_bf16 v[30:33], v[134:137], v[208:211], v[30:33]
	v_mfma_f32_16x16x32_bf16 v[26:29], v[142:145], v[208:211], v[26:29]
	v_mfma_f32_16x16x32_bf16 v[14:17], v[134:137], v[216:219], v[14:17]
	v_mfma_f32_16x16x32_bf16 v[10:13], v[142:145], v[216:219], v[10:13]
	v_mfma_f32_16x16x32_bf16 v[62:65], v[138:141], v[196:199], v[62:65]
	v_mfma_f32_16x16x32_bf16 v[58:61], v[146:149], v[196:199], v[58:61]
	v_mfma_f32_16x16x32_bf16 v[46:49], v[138:141], v[204:207], v[46:49]
	v_mfma_f32_16x16x32_bf16 v[42:45], v[146:149], v[204:207], v[42:45]
	v_mfma_f32_16x16x32_bf16 v[30:33], v[138:141], v[212:215], v[30:33]
	v_mfma_f32_16x16x32_bf16 v[26:29], v[146:149], v[212:215], v[26:29]
	v_mfma_f32_16x16x32_bf16 v[14:17], v[138:141], v[220:223], v[14:17]
	v_mfma_f32_16x16x32_bf16 v[10:13], v[146:149], v[220:223], v[10:13]
	v_mfma_f32_16x16x32_bf16 v[54:57], v[150:153], v[184:187], v[54:57]
	v_mfma_f32_16x16x32_bf16 v[50:53], v[176:179], v[184:187], v[50:53]
	v_mfma_f32_16x16x32_bf16 v[38:41], v[150:153], v[200:203], v[38:41]
	v_mfma_f32_16x16x32_bf16 v[34:37], v[176:179], v[200:203], v[34:37]
	v_mfma_f32_16x16x32_bf16 v[22:25], v[150:153], v[208:211], v[22:25]
	v_mfma_f32_16x16x32_bf16 v[18:21], v[176:179], v[208:211], v[18:21]
	v_mfma_f32_16x16x32_bf16 v[6:9], v[150:153], v[216:219], v[6:9]
	v_mfma_f32_16x16x32_bf16 v[2:5], v[176:179], v[216:219], v[2:5]
	v_mfma_f32_16x16x32_bf16 v[54:57], v[172:175], v[196:199], v[54:57]
	v_mfma_f32_16x16x32_bf16 v[50:53], v[180:183], v[196:199], v[50:53]
	v_mfma_f32_16x16x32_bf16 v[38:41], v[172:175], v[204:207], v[38:41]
	v_mfma_f32_16x16x32_bf16 v[34:37], v[180:183], v[204:207], v[34:37]
	v_mfma_f32_16x16x32_bf16 v[22:25], v[172:175], v[212:215], v[22:25]
	v_mfma_f32_16x16x32_bf16 v[18:21], v[180:183], v[212:215], v[18:21]
	v_mfma_f32_16x16x32_bf16 v[6:9], v[172:175], v[220:223], v[6:9]
	v_mfma_f32_16x16x32_bf16 v[2:5], v[180:183], v[220:223], v[2:5]
	s_setprio 0
	s_barrier
	s_add_i32 s44, s44, 2
	s_add_u32 s38, s38, 0x100
	s_addc_u32 s39, s39, 0
	s_cmp_gt_u32 s44, 29
	s_cbranch_scc0 .LBB0_894
	s_and_b64 vcc, exec, s[12:13]
	s_cbranch_vccz .LBB0_897
	s_barrier

; #define PG8_STAGE(bufoff, gbase, RR, ld) do { _Pragma("unroll") for (int _i = 0; _i < 2; ++_i) \
;         __builtin_amdgcn_global_load_lds((const unsigned*)((const char*)(gbase) + (RR)[_i] * (ld) + C2[_i]), (LAS unsigned*)(lds + (bufoff) + ldsw + _i * 8192), 16, 0, 0); } while (0)
; #define PG8_LDA(dst, b, h) do { _Pragma("unroll") for (int m = 0; m < 4; ++m) _Pragma("unroll") for (int k = 0; k < 2; ++k) dst[m][k] = *(const LAS bf16x8*)(lds + PG8_SA(b, h) + aoff + m * 2048 + k * 1024); } while (0)
; #define PG8_WAIT_V(n) asm volatile("s_waitcnt vmcnt(" #n ")" ::: "memory")
; #define PG8_WAIT_L(n) asm volatile("s_waitcnt lgkmcnt(" #n ")" ::: "memory")
; template <class Sched, class Epi>
; __device__ __forceinline__ void gemm_run(LAS unsigned char* lds, const Sched& S, const Epi& E) {
;     ...
;         const bool has_next = S.next(ui + 1, nxt);
;         const char* nA = has_next ? nxt.A : cA; const char* nB = has_next ? nxt.B : cB; const unsigned nlda = has_next ? nxt.lda : lda, nldb = has_next ? nxt.ldb : ldb;
;         const int nt = cur.nt;
;         for (int t = 0; t < nt; t += 2) {
;             const bool last = (t == nt - 2);
;             const char* a1 = cA + (size_t)(t + 1) * kstep;
;             const char* a2 = last ? nA : cA + (size_t)(t + 2) * kstep; const char* b2 = last ? nB : cB + (size_t)(t + 2) * kstep;
;             const unsigned la2 = last ? nlda : lda, lb2 = last ? nldb : ldb;
;             const char* a3 = a2 + kstep; const char* b3 = b2 + kstep;
;             PG8_LDB(B0, 0, 0); PG8_LDB(B1, 0, 1); PG8_SCHED; PG8_LDA(At, 0, 0); PG8_STAGE(PG8_SA(1, 1), a1 + (size_t)HALF * lda, RA, lda);
;             PG8_WAIT_V(8); PG8_WAIT_L(0); PG8_BAR; PG8_MMA(0, 0, At, B0); PG8_MMA(0, 1, At, B1); PG8_BAR; PG8_SCHED;
;             PG8_LDA(At, 0, 1); PG8_STAGE(PG8_SB(0, 0), b2, RB, lb2); PG8_STAGE(PG8_SB(0, 1), b2 + (size_t)HALF * lb2, RB, lb2); PG8_STAGE(PG8_SA(0, 0), a2, RA, la2);
;             PG8_WAIT_V(8); PG8_WAIT_L(0); PG8_BAR; PG8_MMA(1, 0, At, B0); PG8_MMA(1, 1, At, B1); PG8_BAR; PG8_SCHED;
;     ...
;         for (int a = 0; a < 2; ++a)
; #pragma unroll
;             for (int b = 0; b < 2; ++b)
; #pragma unroll
;                 for (int m = 0; m < 4; ++m)
; #pragma unroll
;                     for (int n = 0; n < 2; ++n) acc[a][b][m][n] = (f32x4){0.f, 0.f, 0.f, 0.f};
;         cur = nxt; cA = nA; cB = nB; lda = nlda; ldb = nldb; ++ui;
.LBB0_998:
	s_add_u32 s15, s30, 0x100
	v_mov_b32_e32 v2, 0
	s_addc_u32 s54, s31, 0
	v_lshl_add_u64 v[146:147], s[28:29], 0, v[142:143]
	v_lshl_add_u64 v[148:149], s[28:29], 0, v[144:145]
	s_mov_b32 s55, -2
	s_mov_b64 s[30:31], 0
	v_mov_b32_e32 v3, v2
	v_mov_b32_e32 v4, v2
	v_mov_b32_e32 v5, v2
	v_mov_b32_e32 v6, v2
	v_mov_b32_e32 v7, v2
	v_mov_b32_e32 v8, v2
	v_mov_b32_e32 v9, v2
	v_mov_b32_e32 v18, v2
	v_mov_b32_e32 v19, v2
	v_mov_b32_e32 v20, v2
	v_mov_b32_e32 v21, v2
	v_mov_b32_e32 v22, v2
	v_mov_b32_e32 v23, v2
	v_mov_b32_e32 v24, v2
	v_mov_b32_e32 v25, v2
	v_mov_b32_e32 v34, v2
	v_mov_b32_e32 v35, v2
	v_mov_b32_e32 v36, v2
	v_mov_b32_e32 v37, v2
	v_mov_b32_e32 v38, v2
	v_mov_b32_e32 v39, v2
	v_mov_b32_e32 v40, v2
	v_mov_b32_e32 v41, v2
	v_mov_b32_e32 v50, v2
	v_mov_b32_e32 v51, v2
	v_mov_b32_e32 v52, v2
	v_mov_b32_e32 v53, v2
	v_mov_b32_e32 v54, v2
	v_mov_b32_e32 v55, v2
	v_mov_b32_e32 v56, v2
	v_mov_b32_e32 v57, v2
	v_mov_b32_e32 v10, v2
	v_mov_b32_e32 v11, v2
	v_mov_b32_e32 v12, v2
	v_mov_b32_e32 v13, v2
	v_mov_b32_e32 v14, v2
	v_mov_b32_e32 v15, v2
	v_mov_b32_e32 v16, v2
	v_mov_b32_e32 v17, v2
	v_mov_b32_e32 v26, v2
	v_mov_b32_e32 v27, v2
	v_mov_b32_e32 v28, v2
	v_mov_b32_e32 v29, v2
	v_mov_b32_e32 v30, v2
	v_mov_b32_e32 v31, v2
	v_mov_b32_e32 v32, v2
	v_mov_b32_e32 v33, v2
	v_mov_b32_e32 v42, v2
	v_mov_b32_e32 v43, v2
	v_mov_b32_e32 v44, v2
	v_mov_b32_e32 v45, v2
	v_mov_b32_e32 v46, v2
	v_mov_b32_e32 v47, v2
	v_mov_b32_e32 v48, v2
	v_mov_b32_e32 v49, v2
	v_mov_b32_e32 v58, v2
	v_mov_b32_e32 v59, v2
	v_mov_b32_e32 v60, v2
	v_mov_b32_e32 v61, v2
	v_mov_b32_e32 v62, v2
	v_mov_b32_e32 v63, v2
	v_mov_b32_e32 v64, v2
	v_mov_b32_e32 v65, v2
	v_mov_b32_e32 v66, v2
	v_mov_b32_e32 v67, v2
	v_mov_b32_e32 v68, v2
	v_mov_b32_e32 v69, v2
	v_mov_b32_e32 v70, v2
	v_mov_b32_e32 v71, v2
	v_mov_b32_e32 v72, v2
	v_mov_b32_e32 v73, v2
	v_mov_b32_e32 v82, v2
	v_mov_b32_e32 v83, v2
	v_mov_b32_e32 v84, v2
	v_mov_b32_e32 v85, v2
	v_mov_b32_e32 v86, v2
	v_mov_b32_e32 v87, v2
	v_mov_b32_e32 v88, v2
	v_mov_b32_e32 v89, v2
	v_mov_b32_e32 v98, v2
	v_mov_b32_e32 v99, v2
	v_mov_b32_e32 v100, v2
	v_mov_b32_e32 v101, v2
	v_mov_b32_e32 v102, v2
	v_mov_b32_e32 v103, v2
	v_mov_b32_e32 v104, v2
	v_mov_b32_e32 v105, v2
	v_mov_b32_e32 v114, v2
	v_mov_b32_e32 v115, v2
	v_mov_b32_e32 v116, v2
	v_mov_b32_e32 v117, v2
	v_mov_b32_e32 v118, v2
	v_mov_b32_e32 v119, v2
	v_mov_b32_e32 v120, v2
	v_mov_b32_e32 v121, v2
	v_mov_b32_e32 v74, v2
	v_mov_b32_e32 v75, v2
	v_mov_b32_e32 v76, v2
	v_mov_b32_e32 v77, v2
	v_mov_b32_e32 v78, v2
	v_mov_b32_e32 v79, v2
	v_mov_b32_e32 v80, v2
	v_mov_b32_e32 v81, v2
	v_mov_b32_e32 v90, v2
	v_mov_b32_e32 v91, v2
	v_mov_b32_e32 v92, v2
	v_mov_b32_e32 v93, v2
	v_mov_b32_e32 v94, v2
	v_mov_b32_e32 v95, v2
	v_mov_b32_e32 v96, v2
	v_mov_b32_e32 v97, v2
	v_mov_b32_e32 v106, v2
	v_mov_b32_e32 v107, v2
	v_mov_b32_e32 v108, v2
	v_mov_b32_e32 v109, v2
	v_mov_b32_e32 v110, v2
	v_mov_b32_e32 v111, v2
	v_mov_b32_e32 v112, v2
	v_mov_b32_e32 v113, v2
	v_mov_b32_e32 v122, v2
	v_mov_b32_e32 v123, v2
	v_mov_b32_e32 v124, v2
	v_mov_b32_e32 v125, v2
	v_mov_b32_e32 v126, v2
	v_mov_b32_e32 v127, v2
	v_mov_b32_e32 v128, v2
	v_mov_b32_e32 v129, v2
	.p2align 6
.LBB0_999:
	ds_read_b128 v[156:159], v152
	ds_read_b128 v[160:163], v152 offset:1024
	ds_read_b128 v[164:167], v152 offset:2048
	ds_read_b128 v[168:171], v152 offset:3072
	ds_read_b128 v[172:175], v153
	ds_read_b128 v[176:179], v153 offset:1024
	ds_read_b128 v[180:183], v153 offset:2048
	ds_read_b128 v[184:187], v153 offset:3072
	s_add_u32 s36, s28, s30
	s_addc_u32 s37, s29, s31
	s_add_u32 s36, s36, 0x100
	s_addc_u32 s37, s37, 0
	s_add_u32 s56, s15, s30
	s_addc_u32 s57, s54, s31
	s_cmpk_eq_i32 s30, 0xf00
	s_cselect_b32 s39, s17, s37
	s_cselect_b32 s38, s16, s36
	s_cselect_b32 s37, s21, s57
	s_cselect_b32 s36, s20, s56
	v_lshl_add_u64 v[220:221], v[146:147], 0, s[30:31]
	s_add_i32 m0, s42, 0xc000
	ds_read_b128 v[188:191], v154
	ds_read_b128 v[192:195], v154 offset:1024
	ds_read_b128 v[196:199], v154 offset:2048
	ds_read_b128 v[200:203], v154 offset:3072
	ds_read_b128 v[204:207], v154 offset:4096
	ds_read_b128 v[208:211], v154 offset:5120
	ds_read_b128 v[212:215], v154 offset:6144
	ds_read_b128 v[216:219], v154 offset:7168
	global_load_lds_dwordx4 v[220:221], off
	v_lshl_add_u64 v[220:221], v[148:149], 0, s[30:31]
	s_add_i32 m0, s42, 0xe000
	s_nop 0
	global_load_lds_dwordx4 v[220:221], off
	s_waitcnt vmcnt(8)
	s_waitcnt lgkmcnt(0)
	s_barrier
	s_setprio 1
	s_waitcnt lgkmcnt(0)
	v_mfma_f32_16x16x32_bf16 v[126:129], v[156:159], v[188:191], v[126:129]
	v_mfma_f32_16x16x32_bf16 v[122:125], v[164:167], v[188:191], v[122:125]
	v_mfma_f32_16x16x32_bf16 v[110:113], v[156:159], v[196:199], v[110:113]
	v_mfma_f32_16x16x32_bf16 v[106:109], v[164:167], v[196:199], v[106:109]
	v_mfma_f32_16x16x32_bf16 v[94:97], v[156:159], v[204:207], v[94:97]
	v_mfma_f32_16x16x32_bf16 v[90:93], v[164:167], v[204:207], v[90:93]
	v_mfma_f32_16x16x32_bf16 v[78:81], v[156:159], v[212:215], v[78:81]
	v_mfma_f32_16x16x32_bf16 v[74:77], v[164:167], v[212:215], v[74:77]
	v_mfma_f32_16x16x32_bf16 v[126:129], v[160:163], v[192:195], v[126:129]
	v_mfma_f32_16x16x32_bf16 v[122:125], v[168:171], v[192:195], v[122:125]
	v_mfma_f32_16x16x32_bf16 v[110:113], v[160:163], v[200:203], v[110:113]
	v_mfma_f32_16x16x32_bf16 v[106:109], v[168:171], v[200:203], v[106:109]
	v_mfma_f32_16x16x32_bf16 v[94:97], v[160:163], v[208:211], v[94:97]
	v_mfma_f32_16x16x32_bf16 v[90:93], v[168:171], v[208:211], v[90:93]
	v_mfma_f32_16x16x32_bf16 v[78:81], v[160:163], v[216:219], v[78:81]
	v_mfma_f32_16x16x32_bf16 v[74:77], v[168:171], v[216:219], v[74:77]
	v_mfma_f32_16x16x32_bf16 v[118:121], v[172:175], v[188:191], v[118:121]
	v_mfma_f32_16x16x32_bf16 v[114:117], v[180:183], v[188:191], v[114:117]
	v_mfma_f32_16x16x32_bf16 v[102:105], v[172:175], v[196:199], v[102:105]
	v_mfma_f32_16x16x32_bf16 v[98:101], v[180:183], v[196:199], v[98:101]
	v_mfma_f32_16x16x32_bf16 v[86:89], v[172:175], v[204:207], v[86:89]
	v_mfma_f32_16x16x32_bf16 v[82:85], v[180:183], v[204:207], v[82:85]
	v_mfma_f32_16x16x32_bf16 v[70:73], v[172:175], v[212:215], v[70:73]
	v_mfma_f32_16x16x32_bf16 v[66:69], v[180:183], v[212:215], v[66:69]
	v_mfma_f32_16x16x32_bf16 v[118:121], v[176:179], v[192:195], v[118:121]
	v_mfma_f32_16x16x32_bf16 v[114:117], v[184:187], v[192:195], v[114:117]
	v_mfma_f32_16x16x32_bf16 v[102:105], v[176:179], v[200:203], v[102:105]
	v_mfma_f32_16x16x32_bf16 v[98:101], v[184:187], v[200:203], v[98:101]
	v_mfma_f32_16x16x32_bf16 v[86:89], v[176:179], v[208:211], v[86:89]
	v_mfma_f32_16x16x32_bf16 v[82:85], v[184:187], v[208:211], v[82:85]
	v_mfma_f32_16x16x32_bf16 v[70:73], v[176:179], v[216:219], v[70:73]
	v_mfma_f32_16x16x32_bf16 v[66:69], v[184:187], v[216:219], v[66:69]
	s_setprio 0
	s_barrier
; #define PG8_STAGE(bufoff, gbase, RR, ld) do { _Pragma("unroll") for (int _i = 0; _i < 2; ++_i) \
;         __builtin_amdgcn_global_load_lds((const unsigned*)((const char*)(gbase) + (RR)[_i] * (ld) + C2[_i]), (LAS unsigned*)(lds + (bufoff) + ldsw + _i * 8192), 16, 0, 0); } while (0)
; #define PG8_LDA(dst, b, h) do { _Pragma("unroll") for (int m = 0; m < 4; ++m) _Pragma("unroll") for (int k = 0; k < 2; ++k) dst[m][k] = *(const LAS bf16x8*)(lds + PG8_SA(b, h) + aoff + m * 2048 + k * 1024); } while (0)
; #define PG8_LDB(dst, b, h) do { _Pragma("unroll") for (int n = 0; n < 2; ++n) _Pragma("unroll") for (int k = 0; k < 2; ++k) dst[n][k] = *(const LAS bf16x8*)(lds + PG8_SB(b, h) + boff + n * 2048 + k * 1024); } while (0)
; #define PG8_MMA(ai, bj, At, Bt) do { __builtin_amdgcn_s_setprio(1); _Pragma("unroll") for (int m = 0; m < 4; ++m) _Pragma("unroll") for (int n = 0; n < 2; ++n) _Pragma("unroll") for (int k = 0; k < 2; ++k) \
;         acc[ai][bj][m][n] = __builtin_amdgcn_mfma_f32_16x16x32_bf16(Bt[n][k], At[m][k], acc[ai][bj][m][n], 0, 0, 0); __builtin_amdgcn_s_setprio(0); } while (0)
; #define PG8_WAIT_V(n) asm volatile("s_waitcnt vmcnt(" #n ")" ::: "memory")
; #define PG8_WAIT_L(n) asm volatile("s_waitcnt lgkmcnt(" #n ")" ::: "memory")
; #define PG8_BAR __builtin_amdgcn_s_barrier()
; #define PG8_SCHED __builtin_amdgcn_sched_barrier(0)
; template <class Sched, class Epi>
; __device__ __forceinline__ void gemm_run(LAS unsigned char* lds, const Sched& S, const Epi& E) {
;     ...
;             PG8_LDA(At, 0, 1); PG8_STAGE(PG8_SB(0, 0), b2, RB, lb2); PG8_STAGE(PG8_SB(0, 1), b2 + (size_t)HALF * lb2, RB, lb2); PG8_STAGE(PG8_SA(0, 0), a2, RA, la2);
;             PG8_WAIT_V(8); PG8_WAIT_L(0); PG8_BAR; PG8_MMA(1, 0, At, B0); PG8_MMA(1, 1, At, B1); PG8_BAR; PG8_SCHED;
;             PG8_LDB(B0, 1, 0); PG8_LDB(B1, 1, 1); PG8_SCHED; PG8_LDA(At, 1, 0); PG8_STAGE(PG8_SA(0, 1), a2 + (size_t)HALF * la2, RA, la2);
;             PG8_WAIT_V(8); PG8_WAIT_L(0); PG8_BAR; PG8_MMA(0, 0, At, B0); PG8_MMA(0, 1, At, B1); PG8_BAR; PG8_SCHED;
	v_lshl_add_u64 v[220:221], s[36:37], 0, v[132:133]
	s_add_i32 s56, s49, s3
	v_lshl_add_u64 v[220:221], v[220:221], 0, v[130:131]
	s_mov_b32 m0, s56
	ds_read_b128 v[188:191], v154 offset:16384
	ds_read_b128 v[192:195], v154 offset:17408
	ds_read_b128 v[196:199], v154 offset:18432
	ds_read_b128 v[200:203], v154 offset:19456
	ds_read_b128 v[204:207], v154 offset:20480
	ds_read_b128 v[208:211], v154 offset:21504
	ds_read_b128 v[212:215], v154 offset:22528
	ds_read_b128 v[216:219], v154 offset:23552
	global_load_lds_dwordx4 v[220:221], off
	s_add_i32 m0, s56, 0x2000
	s_add_u32 s56, s36, 0x80000
	v_lshl_add_u64 v[222:223], s[36:37], 0, v[136:137]
	s_addc_u32 s57, s37, 0
	v_lshl_add_u64 v[222:223], v[222:223], 0, v[130:131]
	v_lshl_add_u64 v[224:225], s[56:57], 0, v[132:133]
	s_add_i32 s58, s50, s3
	global_load_lds_dwordx4 v[222:223], off
	v_lshl_add_u64 v[224:225], v[224:225], 0, v[130:131]
	s_mov_b32 m0, s58
	v_lshl_add_u64 v[226:227], s[38:39], 0, v[140:141]
	global_load_lds_dwordx4 v[224:225], off
	v_lshl_add_u64 v[224:225], s[56:57], 0, v[136:137]
	v_lshl_add_u64 v[224:225], v[224:225], 0, v[130:131]
	s_add_i32 m0, s58, 0x2000
	v_lshl_add_u64 v[226:227], v[226:227], 0, v[130:131]
	global_load_lds_dwordx4 v[224:225], off
	v_lshl_add_u64 v[224:225], s[38:39], 0, v[138:139]
	v_lshl_add_u64 v[224:225], v[224:225], 0, v[130:131]
	s_mov_b32 m0, s42
	s_nop 0
	global_load_lds_dwordx4 v[224:225], off
	s_mov_b32 m0, s43
	s_nop 0
	global_load_lds_dwordx4 v[226:227], off
	s_waitcnt vmcnt(8)
	s_waitcnt lgkmcnt(0)
	s_barrier
	s_setprio 1
	s_waitcnt lgkmcnt(0)
	v_mfma_f32_16x16x32_bf16 v[62:65], v[156:159], v[188:191], v[62:65]
	v_mfma_f32_16x16x32_bf16 v[58:61], v[164:167], v[188:191], v[58:61]
	v_mfma_f32_16x16x32_bf16 v[46:49], v[156:159], v[196:199], v[46:49]
	v_mfma_f32_16x16x32_bf16 v[42:45], v[164:167], v[196:199], v[42:45]
	v_mfma_f32_16x16x32_bf16 v[30:33], v[156:159], v[204:207], v[30:33]
	v_mfma_f32_16x16x32_bf16 v[26:29], v[164:167], v[204:207], v[26:29]
	v_mfma_f32_16x16x32_bf16 v[14:17], v[156:159], v[212:215], v[14:17]
	v_mfma_f32_16x16x32_bf16 v[10:13], v[164:167], v[212:215], v[10:13]
	v_mfma_f32_16x16x32_bf16 v[62:65], v[160:163], v[192:195], v[62:65]
	v_mfma_f32_16x16x32_bf16 v[58:61], v[168:171], v[192:195], v[58:61]
	v_mfma_f32_16x16x32_bf16 v[46:49], v[160:163], v[200:203], v[46:49]
	v_mfma_f32_16x16x32_bf16 v[42:45], v[168:171], v[200:203], v[42:45]
	v_mfma_f32_16x16x32_bf16 v[30:33], v[160:163], v[208:211], v[30:33]
	v_mfma_f32_16x16x32_bf16 v[26:29], v[168:171], v[208:211], v[26:29]
	v_mfma_f32_16x16x32_bf16 v[14:17], v[160:163], v[216:219], v[14:17]
	v_mfma_f32_16x16x32_bf16 v[10:13], v[168:171], v[216:219], v[10:13]
	v_mfma_f32_16x16x32_bf16 v[54:57], v[172:175], v[188:191], v[54:57]
	v_mfma_f32_16x16x32_bf16 v[50:53], v[180:183], v[188:191], v[50:53]
	v_mfma_f32_16x16x32_bf16 v[38:41], v[172:175], v[196:199], v[38:41]
	v_mfma_f32_16x16x32_bf16 v[34:37], v[180:183], v[196:199], v[34:37]
	v_mfma_f32_16x16x32_bf16 v[22:25], v[172:175], v[204:207], v[22:25]
	v_mfma_f32_16x16x32_bf16 v[18:21], v[180:183], v[204:207], v[18:21]
	v_mfma_f32_16x16x32_bf16 v[6:9], v[172:175], v[212:215], v[6:9]
	v_mfma_f32_16x16x32_bf16 v[2:5], v[180:183], v[212:215], v[2:5]
	v_mfma_f32_16x16x32_bf16 v[54:57], v[176:179], v[192:195], v[54:57]
	v_mfma_f32_16x16x32_bf16 v[50:53], v[184:187], v[192:195], v[50:53]
	v_mfma_f32_16x16x32_bf16 v[38:41], v[176:179], v[200:203], v[38:41]
	v_mfma_f32_16x16x32_bf16 v[34:37], v[184:187], v[200:203], v[34:37]
	v_mfma_f32_16x16x32_bf16 v[22:25], v[176:179], v[208:211], v[22:25]
	v_mfma_f32_16x16x32_bf16 v[18:21], v[184:187], v[208:211], v[18:21]
	v_mfma_f32_16x16x32_bf16 v[6:9], v[176:179], v[216:219], v[6:9]
	v_mfma_f32_16x16x32_bf16 v[2:5], v[184:187], v[216:219], v[2:5]
	s_setprio 0
	s_barrier
	s_add_i32 s56, 0, 0x18000
	s_add_i32 s57, 0, 0x1c000
	v_add_u32_e32 v168, s56, v151
	v_add_u32_e32 v184, s57, v151
	ds_read_b128 v[156:159], v168
	ds_read_b128 v[160:163], v168 offset:1024
	ds_read_b128 v[164:167], v168 offset:2048
	ds_read_b128 v[168:171], v168 offset:3072
	ds_read_b128 v[172:175], v184
	ds_read_b128 v[176:179], v184 offset:1024
	ds_read_b128 v[180:183], v184 offset:2048
	ds_read_b128 v[184:187], v184 offset:3072
	s_add_u32 s38, s38, 0x80000
	s_addc_u32 s39, s39, 0
	v_lshl_add_u64 v[228:229], s[38:39], 0, v[138:139]
	s_mov_b32 m0, s44
	v_lshl_add_u64 v[228:229], v[228:229], 0, v[130:131]
	ds_read_b128 v[188:191], v154 offset:32768
	ds_read_b128 v[192:195], v154 offset:33792
	ds_read_b128 v[196:199], v154 offset:34816
	ds_read_b128 v[200:203], v154 offset:35840
	ds_read_b128 v[204:207], v154 offset:36864
	ds_read_b128 v[208:211], v154 offset:37888
	ds_read_b128 v[212:215], v154 offset:38912
	ds_read_b128 v[216:219], v154 offset:39936
	global_load_lds_dwordx4 v[228:229], off
	v_lshl_add_u64 v[228:229], s[38:39], 0, v[140:141]
	v_lshl_add_u64 v[228:229], v[228:229], 0, v[130:131]
	s_mov_b32 m0, s45
	s_nop 0
	global_load_lds_dwordx4 v[228:229], off
	s_waitcnt vmcnt(8)
	s_waitcnt lgkmcnt(0)
	s_barrier
; #define PG8_STAGE(bufoff, gbase, RR, ld) do { _Pragma("unroll") for (int _i = 0; _i < 2; ++_i) \
;         __builtin_amdgcn_global_load_lds((const unsigned*)((const char*)(gbase) + (RR)[_i] * (ld) + C2[_i]), (LAS unsigned*)(lds + (bufoff) + ldsw + _i * 8192), 16, 0, 0); } while (0)
; #define PG8_LDA(dst, b, h) do { _Pragma("unroll") for (int m = 0; m < 4; ++m) _Pragma("unroll") for (int k = 0; k < 2; ++k) dst[m][k] = *(const LAS bf16x8*)(lds + PG8_SA(b, h) + aoff + m * 2048 + k * 1024); } while (0)
; #define PG8_MMA(ai, bj, At, Bt) do { __builtin_amdgcn_s_setprio(1); _Pragma("unroll") for (int m = 0; m < 4; ++m) _Pragma("unroll") for (int n = 0; n < 2; ++n) _Pragma("unroll") for (int k = 0; k < 2; ++k) \
;         acc[ai][bj][m][n] = __builtin_amdgcn_mfma_f32_16x16x32_bf16(Bt[n][k], At[m][k], acc[ai][bj][m][n], 0, 0, 0); __builtin_amdgcn_s_setprio(0); } while (0)
; #define PG8_WAIT_V(n) asm volatile("s_waitcnt vmcnt(" #n ")" ::: "memory")
; #define PG8_WAIT_L(n) asm volatile("s_waitcnt lgkmcnt(" #n ")" ::: "memory")
; #define PG8_BAR __builtin_amdgcn_s_barrier()
; #define PG8_SCHED __builtin_amdgcn_sched_barrier(0)
; template <class Sched, class Epi>
; __device__ __forceinline__ void gemm_run(LAS unsigned char* lds, const Sched& S, const Epi& E) {
;     ...
;             PG8_WAIT_V(8); PG8_WAIT_L(0); PG8_BAR; PG8_MMA(0, 0, At, B0); PG8_MMA(0, 1, At, B1); PG8_BAR; PG8_SCHED;
;             PG8_LDA(At, 1, 1); PG8_STAGE(PG8_SB(1, 0), b3, RB, lb2); PG8_STAGE(PG8_SB(1, 1), b3 + (size_t)HALF * lb2, RB, lb2); PG8_STAGE(PG8_SA(1, 0), a3, RA, la2);
;             PG8_WAIT_V(8); PG8_WAIT_L(0); PG8_BAR; PG8_MMA(1, 0, At, B0); PG8_MMA(1, 1, At, B1); PG8_BAR; PG8_SCHED;
;         }
;         if (wr == 0) PG8_BAR;
	s_setprio 1
	s_waitcnt lgkmcnt(0)
	v_mfma_f32_16x16x32_bf16 v[126:129], v[156:159], v[188:191], v[126:129]
	v_mfma_f32_16x16x32_bf16 v[122:125], v[164:167], v[188:191], v[122:125]
	v_mfma_f32_16x16x32_bf16 v[110:113], v[156:159], v[196:199], v[110:113]
	v_mfma_f32_16x16x32_bf16 v[106:109], v[164:167], v[196:199], v[106:109]
	v_mfma_f32_16x16x32_bf16 v[94:97], v[156:159], v[204:207], v[94:97]
	v_mfma_f32_16x16x32_bf16 v[90:93], v[164:167], v[204:207], v[90:93]
	v_mfma_f32_16x16x32_bf16 v[78:81], v[156:159], v[212:215], v[78:81]
	v_mfma_f32_16x16x32_bf16 v[74:77], v[164:167], v[212:215], v[74:77]
	v_mfma_f32_16x16x32_bf16 v[126:129], v[160:163], v[192:195], v[126:129]
	v_mfma_f32_16x16x32_bf16 v[122:125], v[168:171], v[192:195], v[122:125]
	v_mfma_f32_16x16x32_bf16 v[110:113], v[160:163], v[200:203], v[110:113]
	v_mfma_f32_16x16x32_bf16 v[106:109], v[168:171], v[200:203], v[106:109]
	v_mfma_f32_16x16x32_bf16 v[94:97], v[160:163], v[208:211], v[94:97]
	v_mfma_f32_16x16x32_bf16 v[90:93], v[168:171], v[208:211], v[90:93]
	v_mfma_f32_16x16x32_bf16 v[78:81], v[160:163], v[216:219], v[78:81]
	v_mfma_f32_16x16x32_bf16 v[74:77], v[168:171], v[216:219], v[74:77]
	v_mfma_f32_16x16x32_bf16 v[118:121], v[172:175], v[188:191], v[118:121]
	v_mfma_f32_16x16x32_bf16 v[114:117], v[180:183], v[188:191], v[114:117]
	v_mfma_f32_16x16x32_bf16 v[102:105], v[172:175], v[196:199], v[102:105]
	v_mfma_f32_16x16x32_bf16 v[98:101], v[180:183], v[196:199], v[98:101]
	v_mfma_f32_16x16x32_bf16 v[86:89], v[172:175], v[204:207], v[86:89]
	v_mfma_f32_16x16x32_bf16 v[82:85], v[180:183], v[204:207], v[82:85]
	v_mfma_f32_16x16x32_bf16 v[70:73], v[172:175], v[212:215], v[70:73]
	v_mfma_f32_16x16x32_bf16 v[66:69], v[180:183], v[212:215], v[66:69]
	v_mfma_f32_16x16x32_bf16 v[118:121], v[176:179], v[192:195], v[118:121]
	v_mfma_f32_16x16x32_bf16 v[114:117], v[184:187], v[192:195], v[114:117]
	v_mfma_f32_16x16x32_bf16 v[102:105], v[176:179], v[200:203], v[102:105]
	v_mfma_f32_16x16x32_bf16 v[98:101], v[184:187], v[200:203], v[98:101]
	v_mfma_f32_16x16x32_bf16 v[86:89], v[176:179], v[208:211], v[86:89]
	v_mfma_f32_16x16x32_bf16 v[82:85], v[184:187], v[208:211], v[82:85]
	v_mfma_f32_16x16x32_bf16 v[70:73], v[176:179], v[216:219], v[70:73]
	v_mfma_f32_16x16x32_bf16 v[66:69], v[184:187], v[216:219], v[66:69]
	s_setprio 0
	s_barrier
	s_add_i32 s38, s56, s3
	v_lshl_add_u64 v[220:221], v[220:221], 0, s[6:7]
	s_mov_b32 m0, s38
	ds_read_b128 v[188:191], v154 offset:49152
	ds_read_b128 v[192:195], v154 offset:50176
	ds_read_b128 v[196:199], v154 offset:51200
	ds_read_b128 v[200:203], v154 offset:52224
	ds_read_b128 v[204:207], v154 offset:53248
	ds_read_b128 v[208:211], v154 offset:54272
	ds_read_b128 v[212:215], v154 offset:55296
	ds_read_b128 v[216:219], v154 offset:56320
	global_load_lds_dwordx4 v[220:221], off
	s_add_i32 m0, s38, 0x2000
	s_add_u32 s36, s36, 0x80080
	v_lshl_add_u64 v[220:221], v[222:223], 0, s[6:7]
	s_addc_u32 s37, s37, 0
	global_load_lds_dwordx4 v[220:221], off
	v_lshl_add_u64 v[220:221], s[36:37], 0, v[132:133]
	s_add_i32 s38, s57, s3
	v_lshl_add_u64 v[220:221], v[220:221], 0, v[130:131]
	s_mov_b32 m0, s38
	s_nop 0
	global_load_lds_dwordx4 v[220:221], off
	v_lshl_add_u64 v[220:221], s[36:37], 0, v[136:137]
	v_lshl_add_u64 v[220:221], v[220:221], 0, v[130:131]
	s_add_i32 m0, s38, 0x2000
	s_nop 0
	global_load_lds_dwordx4 v[220:221], off
	v_lshl_add_u64 v[220:221], v[224:225], 0, s[6:7]
	s_mov_b32 m0, s47
	s_nop 0
	global_load_lds_dwordx4 v[220:221], off
	v_lshl_add_u64 v[220:221], v[226:227], 0, s[6:7]
	s_mov_b32 m0, s48
	s_nop 0
	global_load_lds_dwordx4 v[220:221], off
	s_waitcnt vmcnt(8)
	s_waitcnt lgkmcnt(0)
	s_barrier
	s_setprio 1
	s_waitcnt lgkmcnt(0)
	v_mfma_f32_16x16x32_bf16 v[62:65], v[156:159], v[188:191], v[62:65]
	v_mfma_f32_16x16x32_bf16 v[58:61], v[164:167], v[188:191], v[58:61]
	v_mfma_f32_16x16x32_bf16 v[46:49], v[156:159], v[196:199], v[46:49]
	v_mfma_f32_16x16x32_bf16 v[42:45], v[164:167], v[196:199], v[42:45]
	v_mfma_f32_16x16x32_bf16 v[30:33], v[156:159], v[204:207], v[30:33]
	v_mfma_f32_16x16x32_bf16 v[26:29], v[164:167], v[204:207], v[26:29]
	v_mfma_f32_16x16x32_bf16 v[14:17], v[156:159], v[212:215], v[14:17]
	v_mfma_f32_16x16x32_bf16 v[10:13], v[164:167], v[212:215], v[10:13]
	v_mfma_f32_16x16x32_bf16 v[62:65], v[160:163], v[192:195], v[62:65]
	v_mfma_f32_16x16x32_bf16 v[58:61], v[168:171], v[192:195], v[58:61]
	v_mfma_f32_16x16x32_bf16 v[46:49], v[160:163], v[200:203], v[46:49]
	v_mfma_f32_16x16x32_bf16 v[42:45], v[168:171], v[200:203], v[42:45]
	v_mfma_f32_16x16x32_bf16 v[30:33], v[160:163], v[208:211], v[30:33]
	v_mfma_f32_16x16x32_bf16 v[26:29], v[168:171], v[208:211], v[26:29]
	v_mfma_f32_16x16x32_bf16 v[14:17], v[160:163], v[216:219], v[14:17]
	v_mfma_f32_16x16x32_bf16 v[10:13], v[168:171], v[216:219], v[10:13]
	v_mfma_f32_16x16x32_bf16 v[54:57], v[172:175], v[188:191], v[54:57]
	v_mfma_f32_16x16x32_bf16 v[50:53], v[180:183], v[188:191], v[50:53]
	v_mfma_f32_16x16x32_bf16 v[38:41], v[172:175], v[196:199], v[38:41]
	v_mfma_f32_16x16x32_bf16 v[34:37], v[180:183], v[196:199], v[34:37]
	v_mfma_f32_16x16x32_bf16 v[22:25], v[172:175], v[204:207], v[22:25]
	v_mfma_f32_16x16x32_bf16 v[18:21], v[180:183], v[204:207], v[18:21]
	v_mfma_f32_16x16x32_bf16 v[6:9], v[172:175], v[212:215], v[6:9]
	v_mfma_f32_16x16x32_bf16 v[2:5], v[180:183], v[212:215], v[2:5]
	v_mfma_f32_16x16x32_bf16 v[54:57], v[176:179], v[192:195], v[54:57]
	v_mfma_f32_16x16x32_bf16 v[50:53], v[184:187], v[192:195], v[50:53]
	v_mfma_f32_16x16x32_bf16 v[38:41], v[176:179], v[200:203], v[38:41]
	v_mfma_f32_16x16x32_bf16 v[34:37], v[184:187], v[200:203], v[34:37]
	v_mfma_f32_16x16x32_bf16 v[22:25], v[176:179], v[208:211], v[22:25]
	v_mfma_f32_16x16x32_bf16 v[18:21], v[184:187], v[208:211], v[18:21]
	v_mfma_f32_16x16x32_bf16 v[6:9], v[176:179], v[216:219], v[6:9]
	v_mfma_f32_16x16x32_bf16 v[2:5], v[184:187], v[216:219], v[2:5]
	s_setprio 0
	s_barrier
	s_add_i32 s55, s55, 2
	s_add_u32 s30, s30, 0x100
	s_addc_u32 s31, s31, 0
	s_cmp_gt_u32 s55, 29
	s_cbranch_scc0 .LBB0_999
	s_and_b64 vcc, exec, s[8:9]
	s_cbranch_vccz .LBB0_1002
	s_barrier

; #define PG8_STAGE(bufoff, gbase, RR, ld) do { _Pragma("unroll") for (int _i = 0; _i < 2; ++_i) \
;         __builtin_amdgcn_global_load_lds((const unsigned*)((const char*)(gbase) + (RR)[_i] * (ld) + C2[_i]), (LAS unsigned*)(lds + (bufoff) + ldsw + _i * 8192), 16, 0, 0); } while (0)
; #define PG8_LDA(dst, b, h) do { _Pragma("unroll") for (int m = 0; m < 4; ++m) _Pragma("unroll") for (int k = 0; k < 2; ++k) dst[m][k] = *(const LAS bf16x8*)(lds + PG8_SA(b, h) + aoff + m * 2048 + k * 1024); } while (0)
; #define PG8_LDB(dst, b, h) do { _Pragma("unroll") for (int n = 0; n < 2; ++n) _Pragma("unroll") for (int k = 0; k < 2; ++k) dst[n][k] = *(const LAS bf16x8*)(lds + PG8_SB(b, h) + boff + n * 2048 + k * 1024); } while (0)
; template <class Sched, class Epi>
; __device__ __forceinline__ void gemm_run(LAS unsigned char* lds, const Sched& S, const Epi& E) {
;     ...
;         const bool has_next = S.next(ui + 1, nxt);
;         const char* nA = has_next ? nxt.A : cA; const char* nB = has_next ? nxt.B : cB; const unsigned nlda = has_next ? nxt.lda : lda, nldb = has_next ? nxt.ldb : ldb;
;         const int nt = cur.nt;
;         for (int t = 0; t < nt; t += 2) {
;             const bool last = (t == nt - 2);
;             const char* a1 = cA + (size_t)(t + 1) * kstep;
;             const char* a2 = last ? nA : cA + (size_t)(t + 2) * kstep; const char* b2 = last ? nB : cB + (size_t)(t + 2) * kstep;
;             const unsigned la2 = last ? nlda : lda, lb2 = last ? nldb : ldb;
;             const char* a3 = a2 + kstep; const char* b3 = b2 + kstep;
;             PG8_LDB(B0, 0, 0); PG8_LDB(B1, 0, 1); PG8_SCHED; PG8_LDA(At, 0, 0); PG8_STAGE(PG8_SA(1, 1), a1 + (size_t)HALF * lda, RA, lda);
;             PG8_WAIT_V(8); PG8_WAIT_L(0); PG8_BAR; PG8_MMA(0, 0, At, B0); PG8_MMA(0, 1, At, B1); PG8_BAR; PG8_SCHED;
;             PG8_LDA(At, 0, 1); PG8_STAGE(PG8_SB(0, 0), b2, RB, lb2); PG8_STAGE(PG8_SB(0, 1), b2 + (size_t)HALF * lb2, RB, lb2); PG8_STAGE(PG8_SA(0, 0), a2, RA, la2);
;             PG8_WAIT_V(8); PG8_WAIT_L(0); PG8_BAR; PG8_MMA(1, 0, At, B0); PG8_MMA(1, 1, At, B1); PG8_BAR; PG8_SCHED;
;             PG8_LDB(B0, 1, 0); PG8_LDB(B1, 1, 1); PG8_SCHED; PG8_LDA(At, 1, 0); PG8_STAGE(PG8_SA(0, 1), a2 + (size_t)HALF * la2, RA, la2);
;             PG8_WAIT_V(8); PG8_WAIT_L(0); PG8_BAR; PG8_MMA(0, 0, At, B0); PG8_MMA(0, 1, At, B1); PG8_BAR; PG8_SCHED;
.LBB0_1067:
	s_add_u32 s65, s28, 0x100
	s_addc_u32 s66, s29, 0
	v_lshl_add_u64 v[144:145], s[20:21], 0, v[140:141]
	v_lshl_add_u64 v[146:147], s[20:21], 0, v[142:143]
	s_mov_b32 s67, -2
	s_mov_b64 s[28:29], 0
	.p2align 6
.LBB0_1068:
	v_add_u32_e32 v151, s50, v149
	ds_read_b128 v[152:155], v151
	ds_read_b128 v[156:159], v151 offset:1024
	ds_read_b128 v[160:163], v151 offset:2048
	ds_read_b128 v[164:167], v151 offset:3072
	v_add_u32_e32 v151, s51, v149
	s_add_u32 s30, s20, s28
	ds_read_b128 v[168:171], v151
	ds_read_b128 v[172:175], v151 offset:1024
	ds_read_b128 v[176:179], v151 offset:2048
	ds_read_b128 v[180:183], v151 offset:3072
	s_addc_u32 s31, s21, s29
	s_add_u32 s30, s30, 0x100
	s_addc_u32 s31, s31, 0
	s_add_u32 s68, s65, s28
	s_addc_u32 s69, s66, s29
	s_cmpk_eq_i32 s28, 0x2b00
	s_cselect_b32 s37, s17, s31
	s_cselect_b32 s36, s16, s30
	s_cselect_b32 s31, s19, s69
	s_cselect_b32 s30, s18, s68
	s_mov_b32 m0, s52
	v_lshl_add_u64 v[184:185], v[144:145], 0, s[28:29]
	ds_read_b128 v[190:193], v150
	ds_read_b128 v[194:197], v150 offset:1024
	ds_read_b128 v[198:201], v150 offset:2048
	ds_read_b128 v[202:205], v150 offset:3072
	ds_read_b128 v[206:209], v150 offset:4096
	ds_read_b128 v[210:213], v150 offset:5120
	ds_read_b128 v[214:217], v150 offset:6144
	ds_read_b128 v[218:221], v150 offset:7168
	global_load_lds_dwordx4 v[184:185], off
	v_lshl_add_u64 v[184:185], v[146:147], 0, s[28:29]
	s_mov_b32 m0, s53
	s_nop 0
	global_load_lds_dwordx4 v[184:185], off
	s_waitcnt vmcnt(8)
	s_waitcnt lgkmcnt(0)
	s_barrier
	s_setprio 1
	s_waitcnt lgkmcnt(0)
	v_mfma_f32_16x16x32_bf16 v[126:129], v[152:155], v[190:193], v[126:129]
	v_mfma_f32_16x16x32_bf16 v[122:125], v[160:163], v[190:193], v[122:125]
	v_mfma_f32_16x16x32_bf16 v[110:113], v[152:155], v[198:201], v[110:113]
	v_mfma_f32_16x16x32_bf16 v[106:109], v[160:163], v[198:201], v[106:109]
	v_mfma_f32_16x16x32_bf16 v[94:97], v[152:155], v[206:209], v[94:97]
	v_mfma_f32_16x16x32_bf16 v[90:93], v[160:163], v[206:209], v[90:93]
	v_mfma_f32_16x16x32_bf16 v[78:81], v[152:155], v[214:217], v[78:81]
	v_mfma_f32_16x16x32_bf16 v[74:77], v[160:163], v[214:217], v[74:77]
	v_mfma_f32_16x16x32_bf16 v[126:129], v[156:159], v[194:197], v[126:129]
	v_mfma_f32_16x16x32_bf16 v[122:125], v[164:167], v[194:197], v[122:125]
	v_mfma_f32_16x16x32_bf16 v[110:113], v[156:159], v[202:205], v[110:113]
	v_mfma_f32_16x16x32_bf16 v[106:109], v[164:167], v[202:205], v[106:109]
	v_mfma_f32_16x16x32_bf16 v[94:97], v[156:159], v[210:213], v[94:97]
	v_mfma_f32_16x16x32_bf16 v[90:93], v[164:167], v[210:213], v[90:93]
	v_mfma_f32_16x16x32_bf16 v[78:81], v[156:159], v[218:221], v[78:81]
	v_mfma_f32_16x16x32_bf16 v[74:77], v[164:167], v[218:221], v[74:77]
	v_mfma_f32_16x16x32_bf16 v[118:121], v[168:171], v[190:193], v[118:121]
	v_mfma_f32_16x16x32_bf16 v[114:117], v[176:179], v[190:193], v[114:117]
	v_mfma_f32_16x16x32_bf16 v[102:105], v[168:171], v[198:201], v[102:105]
	v_mfma_f32_16x16x32_bf16 v[98:101], v[176:179], v[198:201], v[98:101]
	v_mfma_f32_16x16x32_bf16 v[86:89], v[168:171], v[206:209], v[86:89]
	v_mfma_f32_16x16x32_bf16 v[82:85], v[176:179], v[206:209], v[82:85]
	v_mfma_f32_16x16x32_bf16 v[70:73], v[168:171], v[214:217], v[70:73]
	v_mfma_f32_16x16x32_bf16 v[66:69], v[176:179], v[214:217], v[66:69]
	v_mfma_f32_16x16x32_bf16 v[118:121], v[172:175], v[194:197], v[118:121]
	v_mfma_f32_16x16x32_bf16 v[114:117], v[180:183], v[194:197], v[114:117]
	v_mfma_f32_16x16x32_bf16 v[102:105], v[172:175], v[202:205], v[102:105]
	v_mfma_f32_16x16x32_bf16 v[98:101], v[180:183], v[202:205], v[98:101]
	v_mfma_f32_16x16x32_bf16 v[86:89], v[172:175], v[210:213], v[86:89]
	v_mfma_f32_16x16x32_bf16 v[82:85], v[180:183], v[210:213], v[82:85]
	v_mfma_f32_16x16x32_bf16 v[70:73], v[172:175], v[218:221], v[70:73]
	v_mfma_f32_16x16x32_bf16 v[66:69], v[180:183], v[218:221], v[66:69]
	s_setprio 0
	s_barrier
	v_lshl_add_u64 v[184:185], s[30:31], 0, v[132:133]
	s_add_u32 s68, s30, 0x160000
	s_mov_b32 m0, s54
	v_lshl_add_u64 v[184:185], v[184:185], 0, v[130:131]
	v_lshl_add_u64 v[222:223], s[30:31], 0, v[134:135]
	s_addc_u32 s69, s31, 0
	ds_read_b128 v[190:193], v150 offset:16384
	ds_read_b128 v[194:197], v150 offset:17408
	ds_read_b128 v[198:201], v150 offset:18432
	ds_read_b128 v[202:205], v150 offset:19456
	ds_read_b128 v[206:209], v150 offset:20480
	ds_read_b128 v[210:213], v150 offset:21504
	ds_read_b128 v[214:217], v150 offset:22528
	ds_read_b128 v[218:221], v150 offset:23552
	global_load_lds_dwordx4 v[184:185], off
	v_lshl_add_u64 v[222:223], v[222:223], 0, v[130:131]
	s_mov_b32 m0, s55
	v_lshl_add_u64 v[224:225], s[68:69], 0, v[132:133]
	global_load_lds_dwordx4 v[222:223], off
	v_lshl_add_u64 v[224:225], v[224:225], 0, v[130:131]
	s_mov_b32 m0, s56
	v_lshl_add_u64 v[226:227], s[36:37], 0, v[138:139]
	global_load_lds_dwordx4 v[224:225], off
	v_lshl_add_u64 v[224:225], s[68:69], 0, v[134:135]
	v_lshl_add_u64 v[224:225], v[224:225], 0, v[130:131]
	s_mov_b32 m0, s57
	v_lshl_add_u64 v[226:227], v[226:227], 0, v[130:131]
	global_load_lds_dwordx4 v[224:225], off
	v_lshl_add_u64 v[224:225], s[36:37], 0, v[136:137]
	v_lshl_add_u64 v[224:225], v[224:225], 0, v[130:131]
	s_mov_b32 m0, s42
	s_nop 0
	global_load_lds_dwordx4 v[224:225], off
	s_mov_b32 m0, s43
	s_nop 0
	global_load_lds_dwordx4 v[226:227], off
	s_waitcnt vmcnt(8)
	s_waitcnt lgkmcnt(0)
	s_barrier
; #define PG8_STAGE(bufoff, gbase, RR, ld) do { _Pragma("unroll") for (int _i = 0; _i < 2; ++_i) \
;         __builtin_amdgcn_global_load_lds((const unsigned*)((const char*)(gbase) + (RR)[_i] * (ld) + C2[_i]), (LAS unsigned*)(lds + (bufoff) + ldsw + _i * 8192), 16, 0, 0); } while (0)
; #define PG8_LDA(dst, b, h) do { _Pragma("unroll") for (int m = 0; m < 4; ++m) _Pragma("unroll") for (int k = 0; k < 2; ++k) dst[m][k] = *(const LAS bf16x8*)(lds + PG8_SA(b, h) + aoff + m * 2048 + k * 1024); } while (0)
; #define PG8_LDB(dst, b, h) do { _Pragma("unroll") for (int n = 0; n < 2; ++n) _Pragma("unroll") for (int k = 0; k < 2; ++k) dst[n][k] = *(const LAS bf16x8*)(lds + PG8_SB(b, h) + boff + n * 2048 + k * 1024); } while (0)
; #define PG8_MMA(ai, bj, At, Bt) do { __builtin_amdgcn_s_setprio(1); _Pragma("unroll") for (int m = 0; m < 4; ++m) _Pragma("unroll") for (int n = 0; n < 2; ++n) _Pragma("unroll") for (int k = 0; k < 2; ++k) \
;         acc[ai][bj][m][n] = __builtin_amdgcn_mfma_f32_16x16x32_bf16(Bt[n][k], At[m][k], acc[ai][bj][m][n], 0, 0, 0); __builtin_amdgcn_s_setprio(0); } while (0)
; #define PG8_WAIT_V(n) asm volatile("s_waitcnt vmcnt(" #n ")" ::: "memory")
; #define PG8_WAIT_L(n) asm volatile("s_waitcnt lgkmcnt(" #n ")" ::: "memory")
; #define PG8_BAR __builtin_amdgcn_s_barrier()
; #define PG8_SCHED __builtin_amdgcn_sched_barrier(0)
; template <class Sched, class Epi>
; __device__ __forceinline__ void gemm_run(LAS unsigned char* lds, const Sched& S, const Epi& E) {
;     ...
;             PG8_WAIT_V(8); PG8_WAIT_L(0); PG8_BAR; PG8_MMA(1, 0, At, B0); PG8_MMA(1, 1, At, B1); PG8_BAR; PG8_SCHED;
;             PG8_LDB(B0, 1, 0); PG8_LDB(B1, 1, 1); PG8_SCHED; PG8_LDA(At, 1, 0); PG8_STAGE(PG8_SA(0, 1), a2 + (size_t)HALF * la2, RA, la2);
;             PG8_WAIT_V(8); PG8_WAIT_L(0); PG8_BAR; PG8_MMA(0, 0, At, B0); PG8_MMA(0, 1, At, B1); PG8_BAR; PG8_SCHED;
	s_setprio 1
	s_waitcnt lgkmcnt(0)
	v_mfma_f32_16x16x32_bf16 v[62:65], v[152:155], v[190:193], v[62:65]
	v_mfma_f32_16x16x32_bf16 v[58:61], v[160:163], v[190:193], v[58:61]
	v_mfma_f32_16x16x32_bf16 v[46:49], v[152:155], v[198:201], v[46:49]
	v_mfma_f32_16x16x32_bf16 v[42:45], v[160:163], v[198:201], v[42:45]
	v_mfma_f32_16x16x32_bf16 v[30:33], v[152:155], v[206:209], v[30:33]
	v_mfma_f32_16x16x32_bf16 v[26:29], v[160:163], v[206:209], v[26:29]
	v_mfma_f32_16x16x32_bf16 v[14:17], v[152:155], v[214:217], v[14:17]
	v_mfma_f32_16x16x32_bf16 v[10:13], v[160:163], v[214:217], v[10:13]
	v_mfma_f32_16x16x32_bf16 v[62:65], v[156:159], v[194:197], v[62:65]
	v_mfma_f32_16x16x32_bf16 v[58:61], v[164:167], v[194:197], v[58:61]
	v_mfma_f32_16x16x32_bf16 v[46:49], v[156:159], v[202:205], v[46:49]
	v_mfma_f32_16x16x32_bf16 v[42:45], v[164:167], v[202:205], v[42:45]
	v_mfma_f32_16x16x32_bf16 v[30:33], v[156:159], v[210:213], v[30:33]
	v_mfma_f32_16x16x32_bf16 v[26:29], v[164:167], v[210:213], v[26:29]
	v_mfma_f32_16x16x32_bf16 v[14:17], v[156:159], v[218:221], v[14:17]
	v_mfma_f32_16x16x32_bf16 v[10:13], v[164:167], v[218:221], v[10:13]
	v_mfma_f32_16x16x32_bf16 v[54:57], v[168:171], v[190:193], v[54:57]
	v_mfma_f32_16x16x32_bf16 v[50:53], v[176:179], v[190:193], v[50:53]
	v_mfma_f32_16x16x32_bf16 v[38:41], v[168:171], v[198:201], v[38:41]
	v_mfma_f32_16x16x32_bf16 v[34:37], v[176:179], v[198:201], v[34:37]
	v_mfma_f32_16x16x32_bf16 v[22:25], v[168:171], v[206:209], v[22:25]
	v_mfma_f32_16x16x32_bf16 v[18:21], v[176:179], v[206:209], v[18:21]
	v_mfma_f32_16x16x32_bf16 v[6:9], v[168:171], v[214:217], v[6:9]
	v_mfma_f32_16x16x32_bf16 v[2:5], v[176:179], v[214:217], v[2:5]
	v_mfma_f32_16x16x32_bf16 v[54:57], v[172:175], v[194:197], v[54:57]
	v_mfma_f32_16x16x32_bf16 v[50:53], v[180:183], v[194:197], v[50:53]
	v_mfma_f32_16x16x32_bf16 v[38:41], v[172:175], v[202:205], v[38:41]
	v_mfma_f32_16x16x32_bf16 v[34:37], v[180:183], v[202:205], v[34:37]
	v_mfma_f32_16x16x32_bf16 v[22:25], v[172:175], v[210:213], v[22:25]
	v_mfma_f32_16x16x32_bf16 v[18:21], v[180:183], v[210:213], v[18:21]
	v_mfma_f32_16x16x32_bf16 v[6:9], v[172:175], v[218:221], v[6:9]
	v_mfma_f32_16x16x32_bf16 v[2:5], v[180:183], v[218:221], v[2:5]
	s_setprio 0
	s_barrier
	v_add_u32_e32 v151, s58, v149
	ds_read_b128 v[152:155], v151
	ds_read_b128 v[156:159], v151 offset:1024
	ds_read_b128 v[160:163], v151 offset:2048
	ds_read_b128 v[164:167], v151 offset:3072
	v_add_u32_e32 v151, s59, v149
	ds_read_b128 v[168:171], v151
	ds_read_b128 v[172:175], v151 offset:1024
	ds_read_b128 v[176:179], v151 offset:2048
	ds_read_b128 v[180:183], v151 offset:3072
	s_add_u32 s36, s36, 0x160000
	s_addc_u32 s37, s37, 0
	v_lshl_add_u64 v[228:229], s[36:37], 0, v[136:137]
	s_mov_b32 m0, s44
	v_lshl_add_u64 v[228:229], v[228:229], 0, v[130:131]
	ds_read_b128 v[190:193], v150 offset:32768
	ds_read_b128 v[194:197], v150 offset:33792
	ds_read_b128 v[198:201], v150 offset:34816
	ds_read_b128 v[202:205], v150 offset:35840
	ds_read_b128 v[206:209], v150 offset:36864
	ds_read_b128 v[210:213], v150 offset:37888
	ds_read_b128 v[214:217], v150 offset:38912
	ds_read_b128 v[218:221], v150 offset:39936
	global_load_lds_dwordx4 v[228:229], off
	v_lshl_add_u64 v[228:229], s[36:37], 0, v[138:139]
	v_lshl_add_u64 v[228:229], v[228:229], 0, v[130:131]
	s_mov_b32 m0, s45
	s_nop 0
	global_load_lds_dwordx4 v[228:229], off
	s_waitcnt vmcnt(8)
	s_waitcnt lgkmcnt(0)
	s_barrier
	s_setprio 1
	s_waitcnt lgkmcnt(0)
	v_mfma_f32_16x16x32_bf16 v[126:129], v[152:155], v[190:193], v[126:129]
	v_mfma_f32_16x16x32_bf16 v[122:125], v[160:163], v[190:193], v[122:125]
	v_mfma_f32_16x16x32_bf16 v[110:113], v[152:155], v[198:201], v[110:113]
	v_mfma_f32_16x16x32_bf16 v[106:109], v[160:163], v[198:201], v[106:109]
	v_mfma_f32_16x16x32_bf16 v[94:97], v[152:155], v[206:209], v[94:97]
	v_mfma_f32_16x16x32_bf16 v[90:93], v[160:163], v[206:209], v[90:93]
	v_mfma_f32_16x16x32_bf16 v[78:81], v[152:155], v[214:217], v[78:81]
	v_mfma_f32_16x16x32_bf16 v[74:77], v[160:163], v[214:217], v[74:77]
	v_mfma_f32_16x16x32_bf16 v[126:129], v[156:159], v[194:197], v[126:129]
	v_mfma_f32_16x16x32_bf16 v[122:125], v[164:167], v[194:197], v[122:125]
	v_mfma_f32_16x16x32_bf16 v[110:113], v[156:159], v[202:205], v[110:113]
	v_mfma_f32_16x16x32_bf16 v[106:109], v[164:167], v[202:205], v[106:109]
	v_mfma_f32_16x16x32_bf16 v[94:97], v[156:159], v[210:213], v[94:97]
	v_mfma_f32_16x16x32_bf16 v[90:93], v[164:167], v[210:213], v[90:93]
	v_mfma_f32_16x16x32_bf16 v[78:81], v[156:159], v[218:221], v[78:81]
	v_mfma_f32_16x16x32_bf16 v[74:77], v[164:167], v[218:221], v[74:77]
	v_mfma_f32_16x16x32_bf16 v[118:121], v[168:171], v[190:193], v[118:121]
	v_mfma_f32_16x16x32_bf16 v[114:117], v[176:179], v[190:193], v[114:117]
	v_mfma_f32_16x16x32_bf16 v[102:105], v[168:171], v[198:201], v[102:105]
	v_mfma_f32_16x16x32_bf16 v[98:101], v[176:179], v[198:201], v[98:101]
	v_mfma_f32_16x16x32_bf16 v[86:89], v[168:171], v[206:209], v[86:89]
	v_mfma_f32_16x16x32_bf16 v[82:85], v[176:179], v[206:209], v[82:85]
	v_mfma_f32_16x16x32_bf16 v[70:73], v[168:171], v[214:217], v[70:73]
	v_mfma_f32_16x16x32_bf16 v[66:69], v[176:179], v[214:217], v[66:69]
	v_mfma_f32_16x16x32_bf16 v[118:121], v[172:175], v[194:197], v[118:121]
	v_mfma_f32_16x16x32_bf16 v[114:117], v[180:183], v[194:197], v[114:117]
	v_mfma_f32_16x16x32_bf16 v[102:105], v[172:175], v[202:205], v[102:105]
	v_mfma_f32_16x16x32_bf16 v[98:101], v[180:183], v[202:205], v[98:101]
	v_mfma_f32_16x16x32_bf16 v[86:89], v[172:175], v[210:213], v[86:89]
	v_mfma_f32_16x16x32_bf16 v[82:85], v[180:183], v[210:213], v[82:85]
	v_mfma_f32_16x16x32_bf16 v[70:73], v[172:175], v[218:221], v[70:73]
	v_mfma_f32_16x16x32_bf16 v[66:69], v[180:183], v[218:221], v[66:69]
	s_setprio 0
	s_barrier
; #define PG8_STAGE(bufoff, gbase, RR, ld) do { _Pragma("unroll") for (int _i = 0; _i < 2; ++_i) \
;         __builtin_amdgcn_global_load_lds((const unsigned*)((const char*)(gbase) + (RR)[_i] * (ld) + C2[_i]), (LAS unsigned*)(lds + (bufoff) + ldsw + _i * 8192), 16, 0, 0); } while (0)
; #define PG8_LDA(dst, b, h) do { _Pragma("unroll") for (int m = 0; m < 4; ++m) _Pragma("unroll") for (int k = 0; k < 2; ++k) dst[m][k] = *(const LAS bf16x8*)(lds + PG8_SA(b, h) + aoff + m * 2048 + k * 1024); } while (0)
; #define PG8_MMA(ai, bj, At, Bt) do { __builtin_amdgcn_s_setprio(1); _Pragma("unroll") for (int m = 0; m < 4; ++m) _Pragma("unroll") for (int n = 0; n < 2; ++n) _Pragma("unroll") for (int k = 0; k < 2; ++k) \
;         acc[ai][bj][m][n] = __builtin_amdgcn_mfma_f32_16x16x32_bf16(Bt[n][k], At[m][k], acc[ai][bj][m][n], 0, 0, 0); __builtin_amdgcn_s_setprio(0); } while (0)
; #define PG8_WAIT_V(n) asm volatile("s_waitcnt vmcnt(" #n ")" ::: "memory")
; #define PG8_WAIT_L(n) asm volatile("s_waitcnt lgkmcnt(" #n ")" ::: "memory")
; #define PG8_BAR __builtin_amdgcn_s_barrier()
; #define PG8_SCHED __builtin_amdgcn_sched_barrier(0)
; template <class Sched, class Epi>
; __device__ __forceinline__ void gemm_run(LAS unsigned char* lds, const Sched& S, const Epi& E) {
;     ...
;             PG8_LDA(At, 1, 1); PG8_STAGE(PG8_SB(1, 0), b3, RB, lb2); PG8_STAGE(PG8_SB(1, 1), b3 + (size_t)HALF * lb2, RB, lb2); PG8_STAGE(PG8_SA(1, 0), a3, RA, la2);
;             PG8_WAIT_V(8); PG8_WAIT_L(0); PG8_BAR; PG8_MMA(1, 0, At, B0); PG8_MMA(1, 1, At, B1); PG8_BAR; PG8_SCHED;
;         }
;         if (wr == 0) PG8_BAR;
	s_mov_b32 m0, s60
	v_lshl_add_u64 v[184:185], v[184:185], 0, s[10:11]
	ds_read_b128 v[190:193], v150 offset:49152
	ds_read_b128 v[194:197], v150 offset:50176
	ds_read_b128 v[198:201], v150 offset:51200
	ds_read_b128 v[202:205], v150 offset:52224
	ds_read_b128 v[206:209], v150 offset:53248
	ds_read_b128 v[210:213], v150 offset:54272
	ds_read_b128 v[214:217], v150 offset:55296
	ds_read_b128 v[218:221], v150 offset:56320
	global_load_lds_dwordx4 v[184:185], off
	s_add_i32 m0, s60, 0x2000
	s_add_u32 s30, s30, 0x160080
	v_lshl_add_u64 v[184:185], v[222:223], 0, s[10:11]
	s_addc_u32 s31, s31, 0
	global_load_lds_dwordx4 v[184:185], off
	v_lshl_add_u64 v[184:185], s[30:31], 0, v[132:133]
	s_add_i32 s36, s59, s35
	v_lshl_add_u64 v[184:185], v[184:185], 0, v[130:131]
	s_mov_b32 m0, s36
	s_nop 0
	global_load_lds_dwordx4 v[184:185], off
	v_lshl_add_u64 v[184:185], s[30:31], 0, v[134:135]
	v_lshl_add_u64 v[184:185], v[184:185], 0, v[130:131]
	s_add_i32 m0, s36, 0x2000
	s_nop 0
	global_load_lds_dwordx4 v[184:185], off
	v_lshl_add_u64 v[184:185], v[224:225], 0, s[10:11]
	s_mov_b32 m0, s47
	s_nop 0
	global_load_lds_dwordx4 v[184:185], off
	v_lshl_add_u64 v[184:185], v[226:227], 0, s[10:11]
	s_mov_b32 m0, s48
	s_nop 0
	global_load_lds_dwordx4 v[184:185], off
	s_waitcnt vmcnt(8)
	s_waitcnt lgkmcnt(0)
	s_barrier
	s_setprio 1
	s_waitcnt lgkmcnt(0)
	v_mfma_f32_16x16x32_bf16 v[62:65], v[152:155], v[190:193], v[62:65]
	v_mfma_f32_16x16x32_bf16 v[58:61], v[160:163], v[190:193], v[58:61]
	v_mfma_f32_16x16x32_bf16 v[46:49], v[152:155], v[198:201], v[46:49]
	v_mfma_f32_16x16x32_bf16 v[42:45], v[160:163], v[198:201], v[42:45]
	v_mfma_f32_16x16x32_bf16 v[30:33], v[152:155], v[206:209], v[30:33]
	v_mfma_f32_16x16x32_bf16 v[26:29], v[160:163], v[206:209], v[26:29]
	v_mfma_f32_16x16x32_bf16 v[14:17], v[152:155], v[214:217], v[14:17]
	v_mfma_f32_16x16x32_bf16 v[10:13], v[160:163], v[214:217], v[10:13]
	v_mfma_f32_16x16x32_bf16 v[62:65], v[156:159], v[194:197], v[62:65]
	v_mfma_f32_16x16x32_bf16 v[58:61], v[164:167], v[194:197], v[58:61]
	v_mfma_f32_16x16x32_bf16 v[46:49], v[156:159], v[202:205], v[46:49]
	v_mfma_f32_16x16x32_bf16 v[42:45], v[164:167], v[202:205], v[42:45]
	v_mfma_f32_16x16x32_bf16 v[30:33], v[156:159], v[210:213], v[30:33]
	v_mfma_f32_16x16x32_bf16 v[26:29], v[164:167], v[210:213], v[26:29]
	v_mfma_f32_16x16x32_bf16 v[14:17], v[156:159], v[218:221], v[14:17]
	v_mfma_f32_16x16x32_bf16 v[10:13], v[164:167], v[218:221], v[10:13]
	v_mfma_f32_16x16x32_bf16 v[54:57], v[168:171], v[190:193], v[54:57]
	v_mfma_f32_16x16x32_bf16 v[50:53], v[176:179], v[190:193], v[50:53]
	v_mfma_f32_16x16x32_bf16 v[38:41], v[168:171], v[198:201], v[38:41]
	v_mfma_f32_16x16x32_bf16 v[34:37], v[176:179], v[198:201], v[34:37]
	v_mfma_f32_16x16x32_bf16 v[22:25], v[168:171], v[206:209], v[22:25]
	v_mfma_f32_16x16x32_bf16 v[18:21], v[176:179], v[206:209], v[18:21]
	v_mfma_f32_16x16x32_bf16 v[6:9], v[168:171], v[214:217], v[6:9]
	v_mfma_f32_16x16x32_bf16 v[2:5], v[176:179], v[214:217], v[2:5]
	v_mfma_f32_16x16x32_bf16 v[54:57], v[172:175], v[194:197], v[54:57]
	v_mfma_f32_16x16x32_bf16 v[50:53], v[180:183], v[194:197], v[50:53]
	v_mfma_f32_16x16x32_bf16 v[38:41], v[172:175], v[202:205], v[38:41]
	v_mfma_f32_16x16x32_bf16 v[34:37], v[180:183], v[202:205], v[34:37]
	v_mfma_f32_16x16x32_bf16 v[22:25], v[172:175], v[210:213], v[22:25]
	v_mfma_f32_16x16x32_bf16 v[18:21], v[180:183], v[210:213], v[18:21]
	v_mfma_f32_16x16x32_bf16 v[6:9], v[172:175], v[218:221], v[6:9]
	v_mfma_f32_16x16x32_bf16 v[2:5], v[180:183], v[218:221], v[2:5]
	s_setprio 0
	s_barrier
	s_add_i32 s67, s67, 2
	s_add_u32 s28, s28, 0x100
	s_addc_u32 s29, s29, 0
	s_cmpk_gt_u32 s67, 0x55
	s_cbranch_scc0 .LBB0_1068
	s_and_b64 vcc, exec, s[12:13]
	s_cbranch_vccz .LBB0_1071
	s_barrier

; #define PG8_STAGE(bufoff, gbase, RR, ld) do { _Pragma("unroll") for (int _i = 0; _i < 2; ++_i) \
;         __builtin_amdgcn_global_load_lds((const unsigned*)((const char*)(gbase) + (RR)[_i] * (ld) + C2[_i]), (LAS unsigned*)(lds + (bufoff) + ldsw + _i * 8192), 16, 0, 0); } while (0)
; #define PG8_LDA(dst, b, h) do { _Pragma("unroll") for (int m = 0; m < 4; ++m) _Pragma("unroll") for (int k = 0; k < 2; ++k) dst[m][k] = *(const LAS bf16x8*)(lds + PG8_SA(b, h) + aoff + m * 2048 + k * 1024); } while (0)
; #define PG8_LDB(dst, b, h) do { _Pragma("unroll") for (int n = 0; n < 2; ++n) _Pragma("unroll") for (int k = 0; k < 2; ++k) dst[n][k] = *(const LAS bf16x8*)(lds + PG8_SB(b, h) + boff + n * 2048 + k * 1024); } while (0)
; #define PG8_MMA(ai, bj, At, Bt) do { __builtin_amdgcn_s_setprio(1); _Pragma("unroll") for (int m = 0; m < 4; ++m) _Pragma("unroll") for (int n = 0; n < 2; ++n) _Pragma("unroll") for (int k = 0; k < 2; ++k) \
;         acc[ai][bj][m][n] = __builtin_amdgcn_mfma_f32_16x16x32_bf16(Bt[n][k], At[m][k], acc[ai][bj][m][n], 0, 0, 0); __builtin_amdgcn_s_setprio(0); } while (0)
; #define PG8_WAIT_V(n) asm volatile("s_waitcnt vmcnt(" #n ")" ::: "memory")
; #define PG8_WAIT_L(n) asm volatile("s_waitcnt lgkmcnt(" #n ")" ::: "memory")
; template <class Sched, class Epi>
; __device__ __forceinline__ void gemm_run(LAS unsigned char* lds, const Sched& S, const Epi& E) {
;     ...
;         for (int t = 0; t < nt; t += 2) {
;             const bool last = (t == nt - 2);
;             const char* a1 = cA + (size_t)(t + 1) * kstep;
;             const char* a2 = last ? nA : cA + (size_t)(t + 2) * kstep; const char* b2 = last ? nB : cB + (size_t)(t + 2) * kstep;
;             const unsigned la2 = last ? nlda : lda, lb2 = last ? nldb : ldb;
;             const char* a3 = a2 + kstep; const char* b3 = b2 + kstep;
;             PG8_LDB(B0, 0, 0); PG8_LDB(B1, 0, 1); PG8_SCHED; PG8_LDA(At, 0, 0); PG8_STAGE(PG8_SA(1, 1), a1 + (size_t)HALF * lda, RA, lda);
;             PG8_WAIT_V(8); PG8_WAIT_L(0); PG8_BAR; PG8_MMA(0, 0, At, B0); PG8_MMA(0, 1, At, B1); PG8_BAR; PG8_SCHED;
;     ...
;         for (int a = 0; a < 2; ++a)
; #pragma unroll
;             for (int b = 0; b < 2; ++b)
; #pragma unroll
;                 for (int m = 0; m < 4; ++m)
; #pragma unroll
;                     for (int n = 0; n < 2; ++n) acc[a][b][m][n] = (f32x4){0.f, 0.f, 0.f, 0.f};
.LBB0_1123:
	s_add_u32 s55, s30, 0x100
	v_mov_b32_e32 v2, 0
	s_addc_u32 s56, s31, 0
	v_lshl_add_u64 v[146:147], s[28:29], 0, v[142:143]
	v_lshl_add_u64 v[148:149], s[28:29], 0, v[144:145]
	s_mov_b32 s57, -2
	s_mov_b64 s[30:31], 0
	s_waitcnt lgkmcnt(0)
	v_mov_b32_e32 v3, v2
	v_mov_b32_e32 v4, v2
	v_mov_b32_e32 v5, v2
	v_mov_b32_e32 v6, v2
	v_mov_b32_e32 v7, v2
	v_mov_b32_e32 v8, v2
	v_mov_b32_e32 v9, v2
	v_mov_b32_e32 v18, v2
	v_mov_b32_e32 v19, v2
	v_mov_b32_e32 v20, v2
	v_mov_b32_e32 v21, v2
	v_mov_b32_e32 v22, v2
	v_mov_b32_e32 v23, v2
	v_mov_b32_e32 v24, v2
	v_mov_b32_e32 v25, v2
	v_mov_b32_e32 v34, v2
	v_mov_b32_e32 v35, v2
	v_mov_b32_e32 v36, v2
	v_mov_b32_e32 v37, v2
	v_mov_b32_e32 v38, v2
	v_mov_b32_e32 v39, v2
	v_mov_b32_e32 v40, v2
	v_mov_b32_e32 v41, v2
	v_mov_b32_e32 v50, v2
	v_mov_b32_e32 v51, v2
	v_mov_b32_e32 v52, v2
	v_mov_b32_e32 v53, v2
	v_mov_b32_e32 v54, v2
	v_mov_b32_e32 v55, v2
	v_mov_b32_e32 v56, v2
	v_mov_b32_e32 v57, v2
	v_mov_b32_e32 v10, v2
	v_mov_b32_e32 v11, v2
	v_mov_b32_e32 v12, v2
	v_mov_b32_e32 v13, v2
	v_mov_b32_e32 v14, v2
	v_mov_b32_e32 v15, v2
	v_mov_b32_e32 v16, v2
	v_mov_b32_e32 v17, v2
	v_mov_b32_e32 v26, v2
	v_mov_b32_e32 v27, v2
	v_mov_b32_e32 v28, v2
	v_mov_b32_e32 v29, v2
	v_mov_b32_e32 v30, v2
	v_mov_b32_e32 v31, v2
	v_mov_b32_e32 v32, v2
	v_mov_b32_e32 v33, v2
	v_mov_b32_e32 v42, v2
	v_mov_b32_e32 v43, v2
	v_mov_b32_e32 v44, v2
	v_mov_b32_e32 v45, v2
	v_mov_b32_e32 v46, v2
	v_mov_b32_e32 v47, v2
	v_mov_b32_e32 v48, v2
	v_mov_b32_e32 v49, v2
	v_mov_b32_e32 v58, v2
	v_mov_b32_e32 v59, v2
	v_mov_b32_e32 v60, v2
	v_mov_b32_e32 v61, v2
	v_mov_b32_e32 v62, v2
	v_mov_b32_e32 v63, v2
	v_mov_b32_e32 v64, v2
	v_mov_b32_e32 v65, v2
	v_mov_b32_e32 v66, v2
	v_mov_b32_e32 v67, v2
	v_mov_b32_e32 v68, v2
	v_mov_b32_e32 v69, v2
	v_mov_b32_e32 v70, v2
	v_mov_b32_e32 v71, v2
	v_mov_b32_e32 v72, v2
	v_mov_b32_e32 v73, v2
	v_mov_b32_e32 v82, v2
	v_mov_b32_e32 v83, v2
	v_mov_b32_e32 v84, v2
	v_mov_b32_e32 v85, v2
	v_mov_b32_e32 v86, v2
	v_mov_b32_e32 v87, v2
	v_mov_b32_e32 v88, v2
	v_mov_b32_e32 v89, v2
	v_mov_b32_e32 v98, v2
	v_mov_b32_e32 v99, v2
	v_mov_b32_e32 v100, v2
	v_mov_b32_e32 v101, v2
	v_mov_b32_e32 v102, v2
	v_mov_b32_e32 v103, v2
	v_mov_b32_e32 v104, v2
	v_mov_b32_e32 v105, v2
	v_mov_b32_e32 v114, v2
	v_mov_b32_e32 v115, v2
	v_mov_b32_e32 v116, v2
	v_mov_b32_e32 v117, v2
	v_mov_b32_e32 v118, v2
	v_mov_b32_e32 v119, v2
	v_mov_b32_e32 v120, v2
	v_mov_b32_e32 v121, v2
	v_mov_b32_e32 v74, v2
	v_mov_b32_e32 v75, v2
	v_mov_b32_e32 v76, v2
	v_mov_b32_e32 v77, v2
	v_mov_b32_e32 v78, v2
	v_mov_b32_e32 v79, v2
	v_mov_b32_e32 v80, v2
	v_mov_b32_e32 v81, v2
	v_mov_b32_e32 v90, v2
	v_mov_b32_e32 v91, v2
	v_mov_b32_e32 v92, v2
	v_mov_b32_e32 v93, v2
	v_mov_b32_e32 v94, v2
	v_mov_b32_e32 v95, v2
	v_mov_b32_e32 v96, v2
	v_mov_b32_e32 v97, v2
	v_mov_b32_e32 v106, v2
	v_mov_b32_e32 v107, v2
	v_mov_b32_e32 v108, v2
	v_mov_b32_e32 v109, v2
	v_mov_b32_e32 v110, v2
	v_mov_b32_e32 v111, v2
	v_mov_b32_e32 v112, v2
	v_mov_b32_e32 v113, v2
	v_mov_b32_e32 v122, v2
	v_mov_b32_e32 v123, v2
	v_mov_b32_e32 v124, v2
	v_mov_b32_e32 v125, v2
	v_mov_b32_e32 v126, v2
	v_mov_b32_e32 v127, v2
	v_mov_b32_e32 v128, v2
	v_mov_b32_e32 v129, v2
	.p2align 6
.LBB0_1124:
	ds_read_b128 v[154:157], v150
	ds_read_b128 v[158:161], v150 offset:1024
	ds_read_b128 v[162:165], v150 offset:2048
	ds_read_b128 v[166:169], v150 offset:3072
	ds_read_b128 v[170:173], v151
	ds_read_b128 v[174:177], v151 offset:1024
	ds_read_b128 v[178:181], v151 offset:2048
	ds_read_b128 v[182:185], v151 offset:3072
	s_add_u32 s36, s28, s30
	s_addc_u32 s37, s29, s31
	s_add_u32 s36, s36, 0x100
	s_addc_u32 s37, s37, 0
	s_add_u32 s58, s55, s30
	s_addc_u32 s59, s56, s31
	s_cmpk_eq_i32 s30, 0x2b00
	s_cselect_b32 s39, s19, s37
	s_cselect_b32 s38, s18, s36
	s_cselect_b32 s37, s23, s59
	s_cselect_b32 s36, s22, s58
	v_lshl_add_u64 v[218:219], v[146:147], 0, s[30:31]
	s_add_i32 m0, s33, 0xc000
	ds_read_b128 v[186:189], v152
	ds_read_b128 v[190:193], v152 offset:1024
	ds_read_b128 v[194:197], v152 offset:2048
	ds_read_b128 v[198:201], v152 offset:3072
	ds_read_b128 v[202:205], v152 offset:4096
	ds_read_b128 v[206:209], v152 offset:5120
	ds_read_b128 v[210:213], v152 offset:6144
	ds_read_b128 v[214:217], v152 offset:7168
	global_load_lds_dwordx4 v[218:219], off
	v_lshl_add_u64 v[218:219], v[148:149], 0, s[30:31]
	s_add_i32 m0, s33, 0xe000
	s_nop 0
	global_load_lds_dwordx4 v[218:219], off
	s_waitcnt vmcnt(8)
	s_waitcnt lgkmcnt(0)
	s_barrier
	s_setprio 1
	s_waitcnt lgkmcnt(0)
	v_mfma_f32_16x16x32_bf16 v[126:129], v[154:157], v[186:189], v[126:129]
	v_mfma_f32_16x16x32_bf16 v[122:125], v[162:165], v[186:189], v[122:125]
	v_mfma_f32_16x16x32_bf16 v[110:113], v[154:157], v[194:197], v[110:113]
	v_mfma_f32_16x16x32_bf16 v[106:109], v[162:165], v[194:197], v[106:109]
	v_mfma_f32_16x16x32_bf16 v[94:97], v[154:157], v[202:205], v[94:97]
	v_mfma_f32_16x16x32_bf16 v[90:93], v[162:165], v[202:205], v[90:93]
	v_mfma_f32_16x16x32_bf16 v[78:81], v[154:157], v[210:213], v[78:81]
	v_mfma_f32_16x16x32_bf16 v[74:77], v[162:165], v[210:213], v[74:77]
	v_mfma_f32_16x16x32_bf16 v[126:129], v[158:161], v[190:193], v[126:129]
	v_mfma_f32_16x16x32_bf16 v[122:125], v[166:169], v[190:193], v[122:125]
	v_mfma_f32_16x16x32_bf16 v[110:113], v[158:161], v[198:201], v[110:113]
	v_mfma_f32_16x16x32_bf16 v[106:109], v[166:169], v[198:201], v[106:109]
	v_mfma_f32_16x16x32_bf16 v[94:97], v[158:161], v[206:209], v[94:97]
	v_mfma_f32_16x16x32_bf16 v[90:93], v[166:169], v[206:209], v[90:93]
	v_mfma_f32_16x16x32_bf16 v[78:81], v[158:161], v[214:217], v[78:81]
	v_mfma_f32_16x16x32_bf16 v[74:77], v[166:169], v[214:217], v[74:77]
	v_mfma_f32_16x16x32_bf16 v[118:121], v[170:173], v[186:189], v[118:121]
	v_mfma_f32_16x16x32_bf16 v[114:117], v[178:181], v[186:189], v[114:117]
	v_mfma_f32_16x16x32_bf16 v[102:105], v[170:173], v[194:197], v[102:105]
	v_mfma_f32_16x16x32_bf16 v[98:101], v[178:181], v[194:197], v[98:101]
	v_mfma_f32_16x16x32_bf16 v[86:89], v[170:173], v[202:205], v[86:89]
	v_mfma_f32_16x16x32_bf16 v[82:85], v[178:181], v[202:205], v[82:85]
	v_mfma_f32_16x16x32_bf16 v[70:73], v[170:173], v[210:213], v[70:73]
	v_mfma_f32_16x16x32_bf16 v[66:69], v[178:181], v[210:213], v[66:69]
	v_mfma_f32_16x16x32_bf16 v[118:121], v[174:177], v[190:193], v[118:121]
	v_mfma_f32_16x16x32_bf16 v[114:117], v[182:185], v[190:193], v[114:117]
	v_mfma_f32_16x16x32_bf16 v[102:105], v[174:177], v[198:201], v[102:105]
	v_mfma_f32_16x16x32_bf16 v[98:101], v[182:185], v[198:201], v[98:101]
	v_mfma_f32_16x16x32_bf16 v[86:89], v[174:177], v[206:209], v[86:89]
	v_mfma_f32_16x16x32_bf16 v[82:85], v[182:185], v[206:209], v[82:85]
	v_mfma_f32_16x16x32_bf16 v[70:73], v[174:177], v[214:217], v[70:73]
	v_mfma_f32_16x16x32_bf16 v[66:69], v[182:185], v[214:217], v[66:69]
	s_setprio 0
	s_barrier
; #define PG8_STAGE(bufoff, gbase, RR, ld) do { _Pragma("unroll") for (int _i = 0; _i < 2; ++_i) \
;         __builtin_amdgcn_global_load_lds((const unsigned*)((const char*)(gbase) + (RR)[_i] * (ld) + C2[_i]), (LAS unsigned*)(lds + (bufoff) + ldsw + _i * 8192), 16, 0, 0); } while (0)
; #define PG8_LDA(dst, b, h) do { _Pragma("unroll") for (int m = 0; m < 4; ++m) _Pragma("unroll") for (int k = 0; k < 2; ++k) dst[m][k] = *(const LAS bf16x8*)(lds + PG8_SA(b, h) + aoff + m * 2048 + k * 1024); } while (0)
; #define PG8_LDB(dst, b, h) do { _Pragma("unroll") for (int n = 0; n < 2; ++n) _Pragma("unroll") for (int k = 0; k < 2; ++k) dst[n][k] = *(const LAS bf16x8*)(lds + PG8_SB(b, h) + boff + n * 2048 + k * 1024); } while (0)
; #define PG8_MMA(ai, bj, At, Bt) do { __builtin_amdgcn_s_setprio(1); _Pragma("unroll") for (int m = 0; m < 4; ++m) _Pragma("unroll") for (int n = 0; n < 2; ++n) _Pragma("unroll") for (int k = 0; k < 2; ++k) \
;         acc[ai][bj][m][n] = __builtin_amdgcn_mfma_f32_16x16x32_bf16(Bt[n][k], At[m][k], acc[ai][bj][m][n], 0, 0, 0); __builtin_amdgcn_s_setprio(0); } while (0)
; #define PG8_WAIT_V(n) asm volatile("s_waitcnt vmcnt(" #n ")" ::: "memory")
; #define PG8_WAIT_L(n) asm volatile("s_waitcnt lgkmcnt(" #n ")" ::: "memory")
; #define PG8_BAR __builtin_amdgcn_s_barrier()
; #define PG8_SCHED __builtin_amdgcn_sched_barrier(0)
; template <class Sched, class Epi>
; __device__ __forceinline__ void gemm_run(LAS unsigned char* lds, const Sched& S, const Epi& E) {
;     ...
;             PG8_LDA(At, 0, 1); PG8_STAGE(PG8_SB(0, 0), b2, RB, lb2); PG8_STAGE(PG8_SB(0, 1), b2 + (size_t)HALF * lb2, RB, lb2); PG8_STAGE(PG8_SA(0, 0), a2, RA, la2);
;             PG8_WAIT_V(8); PG8_WAIT_L(0); PG8_BAR; PG8_MMA(1, 0, At, B0); PG8_MMA(1, 1, At, B1); PG8_BAR; PG8_SCHED;
;             PG8_LDB(B0, 1, 0); PG8_LDB(B1, 1, 1); PG8_SCHED; PG8_LDA(At, 1, 0); PG8_STAGE(PG8_SA(0, 1), a2 + (size_t)HALF * la2, RA, la2);
;             PG8_WAIT_V(8); PG8_WAIT_L(0); PG8_BAR; PG8_MMA(0, 0, At, B0); PG8_MMA(0, 1, At, B1); PG8_BAR; PG8_SCHED;
	v_lshl_add_u64 v[218:219], s[36:37], 0, v[132:133]
	s_add_i32 s58, s49, s3
	v_lshl_add_u64 v[218:219], v[218:219], 0, v[130:131]
	s_mov_b32 m0, s58
	ds_read_b128 v[186:189], v152 offset:16384
	ds_read_b128 v[190:193], v152 offset:17408
	ds_read_b128 v[194:197], v152 offset:18432
	ds_read_b128 v[198:201], v152 offset:19456
	ds_read_b128 v[202:205], v152 offset:20480
	ds_read_b128 v[206:209], v152 offset:21504
	ds_read_b128 v[210:213], v152 offset:22528
	ds_read_b128 v[214:217], v152 offset:23552
	global_load_lds_dwordx4 v[218:219], off
	s_add_i32 m0, s58, 0x2000
	s_add_u32 s58, s36, 0x160000
	v_lshl_add_u64 v[220:221], s[36:37], 0, v[134:135]
	s_addc_u32 s59, s37, 0
	v_lshl_add_u64 v[220:221], v[220:221], 0, v[130:131]
	v_lshl_add_u64 v[222:223], s[58:59], 0, v[132:133]
	s_add_i32 s60, s50, s3
	global_load_lds_dwordx4 v[220:221], off
	v_lshl_add_u64 v[222:223], v[222:223], 0, v[130:131]
	s_mov_b32 m0, s60
	v_lshl_add_u64 v[224:225], s[38:39], 0, v[138:139]
	global_load_lds_dwordx4 v[222:223], off
	v_lshl_add_u64 v[222:223], s[58:59], 0, v[134:135]
	v_lshl_add_u64 v[222:223], v[222:223], 0, v[130:131]
	s_add_i32 m0, s60, 0x2000
	v_lshl_add_u64 v[224:225], v[224:225], 0, v[130:131]
	global_load_lds_dwordx4 v[222:223], off
	v_lshl_add_u64 v[222:223], s[38:39], 0, v[136:137]
	v_lshl_add_u64 v[222:223], v[222:223], 0, v[130:131]
	s_mov_b32 m0, s33
	s_nop 0
	global_load_lds_dwordx4 v[222:223], off
	s_mov_b32 m0, s35
	s_nop 0
	global_load_lds_dwordx4 v[224:225], off
	s_waitcnt vmcnt(8)
	s_waitcnt lgkmcnt(0)
	s_barrier
	s_setprio 1
	s_waitcnt lgkmcnt(0)
	v_mfma_f32_16x16x32_bf16 v[62:65], v[154:157], v[186:189], v[62:65]
	v_mfma_f32_16x16x32_bf16 v[58:61], v[162:165], v[186:189], v[58:61]
	v_mfma_f32_16x16x32_bf16 v[46:49], v[154:157], v[194:197], v[46:49]
	v_mfma_f32_16x16x32_bf16 v[42:45], v[162:165], v[194:197], v[42:45]
	v_mfma_f32_16x16x32_bf16 v[30:33], v[154:157], v[202:205], v[30:33]
	v_mfma_f32_16x16x32_bf16 v[26:29], v[162:165], v[202:205], v[26:29]
	v_mfma_f32_16x16x32_bf16 v[14:17], v[154:157], v[210:213], v[14:17]
	v_mfma_f32_16x16x32_bf16 v[10:13], v[162:165], v[210:213], v[10:13]
	v_mfma_f32_16x16x32_bf16 v[62:65], v[158:161], v[190:193], v[62:65]
	v_mfma_f32_16x16x32_bf16 v[58:61], v[166:169], v[190:193], v[58:61]
	v_mfma_f32_16x16x32_bf16 v[46:49], v[158:161], v[198:201], v[46:49]
	v_mfma_f32_16x16x32_bf16 v[42:45], v[166:169], v[198:201], v[42:45]
	v_mfma_f32_16x16x32_bf16 v[30:33], v[158:161], v[206:209], v[30:33]
	v_mfma_f32_16x16x32_bf16 v[26:29], v[166:169], v[206:209], v[26:29]
	v_mfma_f32_16x16x32_bf16 v[14:17], v[158:161], v[214:217], v[14:17]
	v_mfma_f32_16x16x32_bf16 v[10:13], v[166:169], v[214:217], v[10:13]
	v_mfma_f32_16x16x32_bf16 v[54:57], v[170:173], v[186:189], v[54:57]
	v_mfma_f32_16x16x32_bf16 v[50:53], v[178:181], v[186:189], v[50:53]
	v_mfma_f32_16x16x32_bf16 v[38:41], v[170:173], v[194:197], v[38:41]
	v_mfma_f32_16x16x32_bf16 v[34:37], v[178:181], v[194:197], v[34:37]
	v_mfma_f32_16x16x32_bf16 v[22:25], v[170:173], v[202:205], v[22:25]
	v_mfma_f32_16x16x32_bf16 v[18:21], v[178:181], v[202:205], v[18:21]
	v_mfma_f32_16x16x32_bf16 v[6:9], v[170:173], v[210:213], v[6:9]
	v_mfma_f32_16x16x32_bf16 v[2:5], v[178:181], v[210:213], v[2:5]
	v_mfma_f32_16x16x32_bf16 v[54:57], v[174:177], v[190:193], v[54:57]
	v_mfma_f32_16x16x32_bf16 v[50:53], v[182:185], v[190:193], v[50:53]
	v_mfma_f32_16x16x32_bf16 v[38:41], v[174:177], v[198:201], v[38:41]
	v_mfma_f32_16x16x32_bf16 v[34:37], v[182:185], v[198:201], v[34:37]
	v_mfma_f32_16x16x32_bf16 v[22:25], v[174:177], v[206:209], v[22:25]
	v_mfma_f32_16x16x32_bf16 v[18:21], v[182:185], v[206:209], v[18:21]
	v_mfma_f32_16x16x32_bf16 v[6:9], v[174:177], v[214:217], v[6:9]
	v_mfma_f32_16x16x32_bf16 v[2:5], v[182:185], v[214:217], v[2:5]
	s_setprio 0
	s_barrier
	s_add_i32 s58, 0, 0x18000
	s_add_i32 s59, 0, 0x1c000
	v_add_u32_e32 v166, s58, v141
	v_add_u32_e32 v182, s59, v141
	ds_read_b128 v[154:157], v166
	ds_read_b128 v[158:161], v166 offset:1024
	ds_read_b128 v[162:165], v166 offset:2048
	ds_read_b128 v[166:169], v166 offset:3072
	ds_read_b128 v[170:173], v182
	ds_read_b128 v[174:177], v182 offset:1024
	ds_read_b128 v[178:181], v182 offset:2048
	ds_read_b128 v[182:185], v182 offset:3072
	s_add_u32 s38, s38, 0x160000
	s_addc_u32 s39, s39, 0
	v_lshl_add_u64 v[226:227], s[38:39], 0, v[136:137]
	s_mov_b32 m0, s40
	v_lshl_add_u64 v[226:227], v[226:227], 0, v[130:131]
	ds_read_b128 v[186:189], v152 offset:32768
	ds_read_b128 v[190:193], v152 offset:33792
	ds_read_b128 v[194:197], v152 offset:34816
	ds_read_b128 v[198:201], v152 offset:35840
	ds_read_b128 v[202:205], v152 offset:36864
	ds_read_b128 v[206:209], v152 offset:37888
	ds_read_b128 v[210:213], v152 offset:38912
	ds_read_b128 v[214:217], v152 offset:39936
	global_load_lds_dwordx4 v[226:227], off
	v_lshl_add_u64 v[226:227], s[38:39], 0, v[138:139]
	v_lshl_add_u64 v[226:227], v[226:227], 0, v[130:131]
	s_mov_b32 m0, s41
	s_nop 0
	global_load_lds_dwordx4 v[226:227], off
	s_waitcnt vmcnt(8)
	s_waitcnt lgkmcnt(0)
	s_barrier
; #define PG8_STAGE(bufoff, gbase, RR, ld) do { _Pragma("unroll") for (int _i = 0; _i < 2; ++_i) \
;         __builtin_amdgcn_global_load_lds((const unsigned*)((const char*)(gbase) + (RR)[_i] * (ld) + C2[_i]), (LAS unsigned*)(lds + (bufoff) + ldsw + _i * 8192), 16, 0, 0); } while (0)
; #define PG8_LDA(dst, b, h) do { _Pragma("unroll") for (int m = 0; m < 4; ++m) _Pragma("unroll") for (int k = 0; k < 2; ++k) dst[m][k] = *(const LAS bf16x8*)(lds + PG8_SA(b, h) + aoff + m * 2048 + k * 1024); } while (0)
; #define PG8_MMA(ai, bj, At, Bt) do { __builtin_amdgcn_s_setprio(1); _Pragma("unroll") for (int m = 0; m < 4; ++m) _Pragma("unroll") for (int n = 0; n < 2; ++n) _Pragma("unroll") for (int k = 0; k < 2; ++k) \
;         acc[ai][bj][m][n] = __builtin_amdgcn_mfma_f32_16x16x32_bf16(Bt[n][k], At[m][k], acc[ai][bj][m][n], 0, 0, 0); __builtin_amdgcn_s_setprio(0); } while (0)
; #define PG8_WAIT_V(n) asm volatile("s_waitcnt vmcnt(" #n ")" ::: "memory")
; #define PG8_WAIT_L(n) asm volatile("s_waitcnt lgkmcnt(" #n ")" ::: "memory")
; #define PG8_BAR __builtin_amdgcn_s_barrier()
; #define PG8_SCHED __builtin_amdgcn_sched_barrier(0)
; template <class Sched, class Epi>
; __device__ __forceinline__ void gemm_run(LAS unsigned char* lds, const Sched& S, const Epi& E) {
;     ...
;             PG8_WAIT_V(8); PG8_WAIT_L(0); PG8_BAR; PG8_MMA(0, 0, At, B0); PG8_MMA(0, 1, At, B1); PG8_BAR; PG8_SCHED;
;             PG8_LDA(At, 1, 1); PG8_STAGE(PG8_SB(1, 0), b3, RB, lb2); PG8_STAGE(PG8_SB(1, 1), b3 + (size_t)HALF * lb2, RB, lb2); PG8_STAGE(PG8_SA(1, 0), a3, RA, la2);
;             PG8_WAIT_V(8); PG8_WAIT_L(0); PG8_BAR; PG8_MMA(1, 0, At, B0); PG8_MMA(1, 1, At, B1); PG8_BAR; PG8_SCHED;
;         }
;         if (wr == 0) PG8_BAR;
	s_setprio 1
	s_waitcnt lgkmcnt(0)
	v_mfma_f32_16x16x32_bf16 v[126:129], v[154:157], v[186:189], v[126:129]
	v_mfma_f32_16x16x32_bf16 v[122:125], v[162:165], v[186:189], v[122:125]
	v_mfma_f32_16x16x32_bf16 v[110:113], v[154:157], v[194:197], v[110:113]
	v_mfma_f32_16x16x32_bf16 v[106:109], v[162:165], v[194:197], v[106:109]
	v_mfma_f32_16x16x32_bf16 v[94:97], v[154:157], v[202:205], v[94:97]
	v_mfma_f32_16x16x32_bf16 v[90:93], v[162:165], v[202:205], v[90:93]
	v_mfma_f32_16x16x32_bf16 v[78:81], v[154:157], v[210:213], v[78:81]
	v_mfma_f32_16x16x32_bf16 v[74:77], v[162:165], v[210:213], v[74:77]
	v_mfma_f32_16x16x32_bf16 v[126:129], v[158:161], v[190:193], v[126:129]
	v_mfma_f32_16x16x32_bf16 v[122:125], v[166:169], v[190:193], v[122:125]
	v_mfma_f32_16x16x32_bf16 v[110:113], v[158:161], v[198:201], v[110:113]
	v_mfma_f32_16x16x32_bf16 v[106:109], v[166:169], v[198:201], v[106:109]
	v_mfma_f32_16x16x32_bf16 v[94:97], v[158:161], v[206:209], v[94:97]
	v_mfma_f32_16x16x32_bf16 v[90:93], v[166:169], v[206:209], v[90:93]
	v_mfma_f32_16x16x32_bf16 v[78:81], v[158:161], v[214:217], v[78:81]
	v_mfma_f32_16x16x32_bf16 v[74:77], v[166:169], v[214:217], v[74:77]
	v_mfma_f32_16x16x32_bf16 v[118:121], v[170:173], v[186:189], v[118:121]
	v_mfma_f32_16x16x32_bf16 v[114:117], v[178:181], v[186:189], v[114:117]
	v_mfma_f32_16x16x32_bf16 v[102:105], v[170:173], v[194:197], v[102:105]
	v_mfma_f32_16x16x32_bf16 v[98:101], v[178:181], v[194:197], v[98:101]
	v_mfma_f32_16x16x32_bf16 v[86:89], v[170:173], v[202:205], v[86:89]
	v_mfma_f32_16x16x32_bf16 v[82:85], v[178:181], v[202:205], v[82:85]
	v_mfma_f32_16x16x32_bf16 v[70:73], v[170:173], v[210:213], v[70:73]
	v_mfma_f32_16x16x32_bf16 v[66:69], v[178:181], v[210:213], v[66:69]
	v_mfma_f32_16x16x32_bf16 v[118:121], v[174:177], v[190:193], v[118:121]
	v_mfma_f32_16x16x32_bf16 v[114:117], v[182:185], v[190:193], v[114:117]
	v_mfma_f32_16x16x32_bf16 v[102:105], v[174:177], v[198:201], v[102:105]
	v_mfma_f32_16x16x32_bf16 v[98:101], v[182:185], v[198:201], v[98:101]
	v_mfma_f32_16x16x32_bf16 v[86:89], v[174:177], v[206:209], v[86:89]
	v_mfma_f32_16x16x32_bf16 v[82:85], v[182:185], v[206:209], v[82:85]
	v_mfma_f32_16x16x32_bf16 v[70:73], v[174:177], v[214:217], v[70:73]
	v_mfma_f32_16x16x32_bf16 v[66:69], v[182:185], v[214:217], v[66:69]
	s_setprio 0
	s_barrier
	s_add_i32 s38, s58, s3
	v_lshl_add_u64 v[218:219], v[218:219], 0, s[10:11]
	s_mov_b32 m0, s38
	ds_read_b128 v[186:189], v152 offset:49152
	ds_read_b128 v[190:193], v152 offset:50176
	ds_read_b128 v[194:197], v152 offset:51200
	ds_read_b128 v[198:201], v152 offset:52224
	ds_read_b128 v[202:205], v152 offset:53248
	ds_read_b128 v[206:209], v152 offset:54272
	ds_read_b128 v[210:213], v152 offset:55296
	ds_read_b128 v[214:217], v152 offset:56320
	global_load_lds_dwordx4 v[218:219], off
	s_add_i32 m0, s38, 0x2000
	s_add_u32 s36, s36, 0x160080
	v_lshl_add_u64 v[218:219], v[220:221], 0, s[10:11]
	s_addc_u32 s37, s37, 0
	global_load_lds_dwordx4 v[218:219], off
	v_lshl_add_u64 v[218:219], s[36:37], 0, v[132:133]
	s_add_i32 s38, s59, s3
	v_lshl_add_u64 v[218:219], v[218:219], 0, v[130:131]
	s_mov_b32 m0, s38
	s_nop 0
	global_load_lds_dwordx4 v[218:219], off
	v_lshl_add_u64 v[218:219], s[36:37], 0, v[134:135]
	v_lshl_add_u64 v[218:219], v[218:219], 0, v[130:131]
	s_add_i32 m0, s38, 0x2000
	s_nop 0
	global_load_lds_dwordx4 v[218:219], off
	v_lshl_add_u64 v[218:219], v[222:223], 0, s[10:11]
	s_mov_b32 m0, s43
	s_nop 0
	global_load_lds_dwordx4 v[218:219], off
	v_lshl_add_u64 v[218:219], v[224:225], 0, s[10:11]
	s_mov_b32 m0, s44
	s_nop 0
	global_load_lds_dwordx4 v[218:219], off
	s_waitcnt vmcnt(8)
	s_waitcnt lgkmcnt(0)
	s_barrier
	s_setprio 1
	s_waitcnt lgkmcnt(0)
	v_mfma_f32_16x16x32_bf16 v[62:65], v[154:157], v[186:189], v[62:65]
	v_mfma_f32_16x16x32_bf16 v[58:61], v[162:165], v[186:189], v[58:61]
	v_mfma_f32_16x16x32_bf16 v[46:49], v[154:157], v[194:197], v[46:49]
	v_mfma_f32_16x16x32_bf16 v[42:45], v[162:165], v[194:197], v[42:45]
	v_mfma_f32_16x16x32_bf16 v[30:33], v[154:157], v[202:205], v[30:33]
	v_mfma_f32_16x16x32_bf16 v[26:29], v[162:165], v[202:205], v[26:29]
	v_mfma_f32_16x16x32_bf16 v[14:17], v[154:157], v[210:213], v[14:17]
	v_mfma_f32_16x16x32_bf16 v[10:13], v[162:165], v[210:213], v[10:13]
	v_mfma_f32_16x16x32_bf16 v[62:65], v[158:161], v[190:193], v[62:65]
	v_mfma_f32_16x16x32_bf16 v[58:61], v[166:169], v[190:193], v[58:61]
	v_mfma_f32_16x16x32_bf16 v[46:49], v[158:161], v[198:201], v[46:49]
	v_mfma_f32_16x16x32_bf16 v[42:45], v[166:169], v[198:201], v[42:45]
	v_mfma_f32_16x16x32_bf16 v[30:33], v[158:161], v[206:209], v[30:33]
	v_mfma_f32_16x16x32_bf16 v[26:29], v[166:169], v[206:209], v[26:29]
	v_mfma_f32_16x16x32_bf16 v[14:17], v[158:161], v[214:217], v[14:17]
	v_mfma_f32_16x16x32_bf16 v[10:13], v[166:169], v[214:217], v[10:13]
	v_mfma_f32_16x16x32_bf16 v[54:57], v[170:173], v[186:189], v[54:57]
	v_mfma_f32_16x16x32_bf16 v[50:53], v[178:181], v[186:189], v[50:53]
	v_mfma_f32_16x16x32_bf16 v[38:41], v[170:173], v[194:197], v[38:41]
	v_mfma_f32_16x16x32_bf16 v[34:37], v[178:181], v[194:197], v[34:37]
	v_mfma_f32_16x16x32_bf16 v[22:25], v[170:173], v[202:205], v[22:25]
	v_mfma_f32_16x16x32_bf16 v[18:21], v[178:181], v[202:205], v[18:21]
	v_mfma_f32_16x16x32_bf16 v[6:9], v[170:173], v[210:213], v[6:9]
	v_mfma_f32_16x16x32_bf16 v[2:5], v[178:181], v[210:213], v[2:5]
	v_mfma_f32_16x16x32_bf16 v[54:57], v[174:177], v[190:193], v[54:57]
	v_mfma_f32_16x16x32_bf16 v[50:53], v[182:185], v[190:193], v[50:53]
	v_mfma_f32_16x16x32_bf16 v[38:41], v[174:177], v[198:201], v[38:41]
	v_mfma_f32_16x16x32_bf16 v[34:37], v[182:185], v[198:201], v[34:37]
	v_mfma_f32_16x16x32_bf16 v[22:25], v[174:177], v[206:209], v[22:25]
	v_mfma_f32_16x16x32_bf16 v[18:21], v[182:185], v[206:209], v[18:21]
	v_mfma_f32_16x16x32_bf16 v[6:9], v[174:177], v[214:217], v[6:9]
	v_mfma_f32_16x16x32_bf16 v[2:5], v[182:185], v[214:217], v[2:5]
	s_setprio 0
	s_barrier
	s_add_i32 s57, s57, 2
	s_add_u32 s30, s30, 0x100
	s_addc_u32 s31, s31, 0
	s_cmpk_gt_u32 s57, 0x55
	s_cbranch_scc0 .LBB0_1124
	s_and_b64 vcc, exec, s[12:13]
	s_cbranch_vccz .LBB0_1127
	s_barrier
